# v75 + one static s_setprio 1 for waves 4-7 at kernel entry, every per-section s_setprio deleted (A/B on the edge-trimmed K-loop structure)
# baseline (speedup 1.0000x reference)
; #define LAS __attribute__((address_space(3)))
; __global__ void __launch_bounds__(512, 2) fwd_megakernel(Params p) {
;     extern __shared__ __attribute__((aligned(16))) uchar smem[];
;     cg::grid_group grid = cg::this_grid();
;     int ph = 0;
;     unsigned* barw = (unsigned*)(p.ws + WS_BAR);
;     volatile LAS unsigned* bst = (volatile LAS unsigned*)(LAS uchar*)(smem + LDS_MAIN);
;     if (threadIdx.x == 0) { bst[0] = 0u; bst[1] = 0u; }
;     if (p.ph_hi - p.ph_lo > 1 && blockIdx.x == 0) for (int i = threadIdx.x; i < XCD_BAR_WORDS; i += 512) barw[i] = 0u;
;     __syncthreads();
;     XcdBarrier xb; xb.bar = barw; xb.x = 0u; xb.st = bst;
_Z14fwd_megakernel6Params:
	s_load_dwordx8 s[4:11], s[0:1], 0x80
	s_load_dwordx4 s[92:95], s[0:1], 0xa0
	s_load_dword s16, s[0:1], 0xb0
	s_mov_b32 s68, s2
	v_readfirstlane_b32 s98, v0
	s_and_b32 s98, s98, 0x3ff
	s_lshr_b32 s98, s98, 6
	s_cmp_ge_u32 s98, 4
	s_cbranch_scc0 .Lprio_done
	s_setprio 1
.Lprio_done:
	s_add_u32 s2, s0, 0xa8
	s_addc_u32 s3, s1, 0
	s_waitcnt lgkmcnt(0)
	v_writelane_b32 v254, s4, 0
	v_and_b32_e32 v136, 0x3ff, v0
	s_nop 0
	v_writelane_b32 v254, s5, 1
	v_writelane_b32 v254, s6, 2
	v_writelane_b32 v254, s7, 3
	v_writelane_b32 v254, s8, 4
	v_writelane_b32 v254, s9, 5
	v_writelane_b32 v254, s10, 6
	v_writelane_b32 v254, s11, 7
	v_writelane_b32 v254, s2, 8
	v_cmp_eq_u32_e64 s[4:5], 0, v136
	s_nop 0
	v_writelane_b32 v254, s3, 9
	s_mov_b64 s[2:3], exec
	v_writelane_b32 v254, s4, 10
	s_nop 1
	v_writelane_b32 v254, s5, 11
	s_and_b64 s[4:5], s[2:3], s[4:5]
	s_mov_b64 exec, s[4:5]
	s_cbranch_execz .LBB0_2
	s_add_i32 s4, 0, 0x20000
	v_mov_b32_e32 v1, 0
	v_mov_b32_e32 v2, s4
	s_add_i32 s4, 0, 0x20004
	ds_write_b32 v2, v1
	v_mov_b32_e32 v2, s4
	ds_write_b32 v2, v1

; #define PG8_STAGE(bufoff, gbase, voff) do { _Pragma("unroll") for (int _i = 0; _i < 2; ++_i) \
;         __builtin_amdgcn_global_load_lds((const unsigned*)((const char*)(gbase) + (voff)[_i]), (LAS unsigned*)(lds + (bufoff) + ldsw + _i * 8192), 16, 0, 0); } while (0)
; #define PG8_LDA(dst, b, h) do { _Pragma("unroll") for (int m = 0; m < 4; ++m) _Pragma("unroll") for (int k = 0; k < 2; ++k) dst[m][k] = *(const LAS bf16x8*)(lds + PG8_SA(b, h) + aoff + m * 2048 + k * 1024); } while (0)
; #define PG8_MMA(ai, bj, At, Bt) do { __builtin_amdgcn_s_setprio(1); _Pragma("unroll") for (int m = 0; m < 4; ++m) _Pragma("unroll") for (int n = 0; n < 2; ++n) _Pragma("unroll") for (int k = 0; k < 2; ++k) \
;         acc[ai][bj][m][n] = __builtin_amdgcn_mfma_f32_16x16x32_bf16(Bt[n][k], At[m][k], acc[ai][bj][m][n], 0, 0, 0); __builtin_amdgcn_s_setprio(0); } while (0)
; #define PG8_WAIT_V(n) asm volatile("s_waitcnt vmcnt(" #n ")" ::: "memory")
; #define PG8_WAIT_L(n) asm volatile("s_waitcnt lgkmcnt(" #n ")" ::: "memory")
; #define PG8_BAR __builtin_amdgcn_s_barrier()
; #define PG8_SCHED __builtin_amdgcn_sched_barrier(0)
; template <class Epi, bool ALIGN_EPI = PG8_ALIGN, bool SP2 = PG8_SP2>
; __device__ __forceinline__ void gemm_phase(LAS uchar* lds, const Gemm g, const StaticOrder& S, const Epi& E) {
;     ...
;             PG8_WAIT_V(8); PG8_WAIT_L(0); PG8_BAR; PG8_MMA(0, 0, At, B0); PG8_MMA(0, 1, At, B1); PG8_BAR; PG8_SCHED;
;             PG8_LDA(At, 0, 1); PG8_STAGE(PG8_SB(0, 0), b2, voffB); PG8_STAGE(PG8_SB(0, 1), b2 + hstepB, voffB); PG8_STAGE(PG8_SA(0, 0), a2, voffA);
.Lrw_done_345_0_pl:
	s_waitcnt lgkmcnt(0)
	s_barrier
	v_mfma_f32_16x16x32_bf16 v[126:129], v[164:167], v[204:207], 0
	v_mfma_f32_16x16x32_bf16 v[122:125], v[176:179], v[204:207], 0
	v_mfma_f32_16x16x32_bf16 v[118:121], v[164:167], v[212:215], 0
	v_mfma_f32_16x16x32_bf16 v[110:113], v[176:179], v[212:215], 0
	v_mfma_f32_16x16x32_bf16 v[102:105], v[164:167], v[220:223], 0
	v_mfma_f32_16x16x32_bf16 v[94:97], v[176:179], v[220:223], 0
	v_mfma_f32_16x16x32_bf16 v[86:89], v[164:167], v[228:231], 0
	v_mfma_f32_16x16x32_bf16 v[78:81], v[176:179], v[228:231], 0
	v_mfma_f32_16x16x32_bf16 v[126:129], v[172:175], v[208:211], v[126:129]
	v_mfma_f32_16x16x32_bf16 v[122:125], v[184:187], v[208:211], v[122:125]
	v_mfma_f32_16x16x32_bf16 v[118:121], v[172:175], v[216:219], v[118:121]
	v_mfma_f32_16x16x32_bf16 v[110:113], v[184:187], v[216:219], v[110:113]
	v_mfma_f32_16x16x32_bf16 v[102:105], v[172:175], v[224:227], v[102:105]
	v_mfma_f32_16x16x32_bf16 v[94:97], v[184:187], v[224:227], v[94:97]
	v_mfma_f32_16x16x32_bf16 v[86:89], v[172:175], v[232:235], v[86:89]
	v_mfma_f32_16x16x32_bf16 v[78:81], v[184:187], v[232:235], v[78:81]
	v_mfma_f32_16x16x32_bf16 v[114:117], v[188:191], v[204:207], 0
	v_mfma_f32_16x16x32_bf16 v[106:109], v[196:199], v[204:207], 0
	v_mfma_f32_16x16x32_bf16 v[98:101], v[188:191], v[212:215], 0
	v_mfma_f32_16x16x32_bf16 v[90:93], v[196:199], v[212:215], 0
	v_mfma_f32_16x16x32_bf16 v[82:85], v[188:191], v[220:223], 0
	v_mfma_f32_16x16x32_bf16 v[74:77], v[196:199], v[220:223], 0
	v_mfma_f32_16x16x32_bf16 v[70:73], v[188:191], v[228:231], 0
	v_mfma_f32_16x16x32_bf16 v[66:69], v[196:199], v[228:231], 0
	v_mfma_f32_16x16x32_bf16 v[114:117], v[192:195], v[208:211], v[114:117]
	v_mfma_f32_16x16x32_bf16 v[106:109], v[200:203], v[208:211], v[106:109]
	v_mfma_f32_16x16x32_bf16 v[98:101], v[192:195], v[216:219], v[98:101]
	v_mfma_f32_16x16x32_bf16 v[90:93], v[200:203], v[216:219], v[90:93]
	v_mfma_f32_16x16x32_bf16 v[82:85], v[192:195], v[224:227], v[82:85]
	v_mfma_f32_16x16x32_bf16 v[74:77], v[200:203], v[224:227], v[74:77]
	v_mfma_f32_16x16x32_bf16 v[70:73], v[192:195], v[232:235], v[70:73]
	v_mfma_f32_16x16x32_bf16 v[66:69], v[200:203], v[232:235], v[66:69]
	s_barrier
	s_add_i32 s16, s41, s23
	v_lshl_add_u64 v[168:169], s[4:5], 0, v[134:135]
	s_mov_b32 m0, s16
	ds_read_b128 v[204:207], v171 offset:16384
	ds_read_b128 v[208:211], v171 offset:17408
	ds_read_b128 v[212:215], v171 offset:18432
	ds_read_b128 v[216:219], v171 offset:19456
	ds_read_b128 v[220:223], v171 offset:20480
	ds_read_b128 v[224:227], v171 offset:21504
	ds_read_b128 v[228:231], v171 offset:22528
	ds_read_b128 v[232:235], v171 offset:23552
	global_load_lds_dwordx4 v[168:169], off
	s_add_i32 m0, s16, 0x2000
	s_add_u32 s16, s4, 0x44000
	v_lshl_add_u64 v[180:181], s[4:5], 0, v[130:131]
	s_addc_u32 s17, s5, 0
	s_add_i32 s41, s42, s23
	global_load_lds_dwordx4 v[180:181], off
	v_lshl_add_u64 v[236:237], s[16:17], 0, v[134:135]
	s_mov_b32 m0, s41
	global_load_lds_dwordx4 v[236:237], off
	s_add_i32 m0, s41, 0x2000
	v_lshl_add_u64 v[236:237], s[16:17], 0, v[130:131]
	global_load_lds_dwordx4 v[236:237], off
	s_mov_b32 m0, s25
	v_lshl_add_u64 v[236:237], s[20:21], 0, v[156:157]
	global_load_lds_dwordx4 v[236:237], off
	s_mov_b32 m0, s26
	v_lshl_add_u64 v[238:239], s[20:21], 0, v[132:133]
	global_load_lds_dwordx4 v[238:239], off
	s_cmp_eq_u32 s97, 1
	s_cbranch_scc0 .Lrw_std_345_1_pl
	s_waitcnt vmcnt(24)
	s_branch .Lrw_done_345_1_pl

; #define PG8_STAGE(bufoff, gbase, voff) do { _Pragma("unroll") for (int _i = 0; _i < 2; ++_i) \
;         __builtin_amdgcn_global_load_lds((const unsigned*)((const char*)(gbase) + (voff)[_i]), (LAS unsigned*)(lds + (bufoff) + ldsw + _i * 8192), 16, 0, 0); } while (0)
; #define PG8_LDA(dst, b, h) do { _Pragma("unroll") for (int m = 0; m < 4; ++m) _Pragma("unroll") for (int k = 0; k < 2; ++k) dst[m][k] = *(const LAS bf16x8*)(lds + PG8_SA(b, h) + aoff + m * 2048 + k * 1024); } while (0)
; #define PG8_LDB(dst, b, h) do { _Pragma("unroll") for (int n = 0; n < 2; ++n) _Pragma("unroll") for (int k = 0; k < 2; ++k) dst[n][k] = *(const LAS bf16x8*)(lds + PG8_SB(b, h) + boff + n * 2048 + k * 1024); } while (0)
; #define PG8_MMA(ai, bj, At, Bt) do { __builtin_amdgcn_s_setprio(1); _Pragma("unroll") for (int m = 0; m < 4; ++m) _Pragma("unroll") for (int n = 0; n < 2; ++n) _Pragma("unroll") for (int k = 0; k < 2; ++k) \
;         acc[ai][bj][m][n] = __builtin_amdgcn_mfma_f32_16x16x32_bf16(Bt[n][k], At[m][k], acc[ai][bj][m][n], 0, 0, 0); __builtin_amdgcn_s_setprio(0); } while (0)
; #define PG8_WAIT_V(n) asm volatile("s_waitcnt vmcnt(" #n ")" ::: "memory")
; #define PG8_WAIT_L(n) asm volatile("s_waitcnt lgkmcnt(" #n ")" ::: "memory")
; #define PG8_BAR __builtin_amdgcn_s_barrier()
; #define PG8_SCHED __builtin_amdgcn_sched_barrier(0)
; template <class Epi, bool ALIGN_EPI = PG8_ALIGN, bool SP2 = PG8_SP2>
; __device__ __forceinline__ void gemm_phase(LAS uchar* lds, const Gemm g, const StaticOrder& S, const Epi& E) {
;     ...
;             PG8_WAIT_V(8); PG8_WAIT_L(0); PG8_BAR; PG8_MMA(1, 0, At, B0); PG8_MMA(1, 1, At, B1); PG8_BAR; PG8_SCHED;
;             PG8_LDB(B0, 1, 0); PG8_LDB(B1, 1, 1); PG8_SCHED; PG8_LDA(At, 1, 0); PG8_STAGE(PG8_SA(0, 1), a2 + hstepA, voffA);
;             PG8_WAIT_V(8); PG8_WAIT_L(0); PG8_BAR; PG8_MMA(0, 0, At, B0); PG8_MMA(0, 1, At, B1); PG8_BAR; PG8_SCHED;
.Lrw_done_345_1_pl:
	s_waitcnt lgkmcnt(0)
	s_barrier
	v_mfma_f32_16x16x32_bf16 v[62:65], v[164:167], v[204:207], 0
	v_mfma_f32_16x16x32_bf16 v[58:61], v[176:179], v[204:207], 0
	v_mfma_f32_16x16x32_bf16 v[54:57], v[164:167], v[212:215], 0
	v_mfma_f32_16x16x32_bf16 v[46:49], v[176:179], v[212:215], 0
	v_mfma_f32_16x16x32_bf16 v[38:41], v[164:167], v[220:223], 0
	v_mfma_f32_16x16x32_bf16 v[30:33], v[176:179], v[220:223], 0
	v_mfma_f32_16x16x32_bf16 v[22:25], v[164:167], v[228:231], 0
	v_mfma_f32_16x16x32_bf16 v[14:17], v[176:179], v[228:231], 0
	v_mfma_f32_16x16x32_bf16 v[62:65], v[172:175], v[208:211], v[62:65]
	v_mfma_f32_16x16x32_bf16 v[58:61], v[184:187], v[208:211], v[58:61]
	v_mfma_f32_16x16x32_bf16 v[54:57], v[172:175], v[216:219], v[54:57]
	v_mfma_f32_16x16x32_bf16 v[46:49], v[184:187], v[216:219], v[46:49]
	v_mfma_f32_16x16x32_bf16 v[38:41], v[172:175], v[224:227], v[38:41]
	v_mfma_f32_16x16x32_bf16 v[30:33], v[184:187], v[224:227], v[30:33]
	v_mfma_f32_16x16x32_bf16 v[22:25], v[172:175], v[232:235], v[22:25]
	v_mfma_f32_16x16x32_bf16 v[14:17], v[184:187], v[232:235], v[14:17]
	v_mfma_f32_16x16x32_bf16 v[50:53], v[188:191], v[204:207], 0
	v_mfma_f32_16x16x32_bf16 v[42:45], v[196:199], v[204:207], 0
	v_mfma_f32_16x16x32_bf16 v[34:37], v[188:191], v[212:215], 0
	v_mfma_f32_16x16x32_bf16 v[26:29], v[196:199], v[212:215], 0
	v_mfma_f32_16x16x32_bf16 v[18:21], v[188:191], v[220:223], 0
	v_mfma_f32_16x16x32_bf16 v[10:13], v[196:199], v[220:223], 0
	v_mfma_f32_16x16x32_bf16 v[6:9], v[188:191], v[228:231], 0
	v_mfma_f32_16x16x32_bf16 v[2:5], v[196:199], v[228:231], 0
	v_mfma_f32_16x16x32_bf16 v[50:53], v[192:195], v[208:211], v[50:53]
	v_mfma_f32_16x16x32_bf16 v[42:45], v[200:203], v[208:211], v[42:45]
	v_mfma_f32_16x16x32_bf16 v[34:37], v[192:195], v[216:219], v[34:37]
	v_mfma_f32_16x16x32_bf16 v[26:29], v[200:203], v[216:219], v[26:29]
	v_mfma_f32_16x16x32_bf16 v[18:21], v[192:195], v[224:227], v[18:21]
	v_mfma_f32_16x16x32_bf16 v[10:13], v[200:203], v[224:227], v[10:13]
	v_mfma_f32_16x16x32_bf16 v[6:9], v[192:195], v[232:235], v[6:9]
	v_mfma_f32_16x16x32_bf16 v[2:5], v[200:203], v[232:235], v[2:5]
	s_barrier
	s_add_i32 s41, 0, 0x18000
	s_add_i32 s42, 0, 0x1c000
	v_add_u32_e32 v184, s41, v139
	v_add_u32_e32 v200, s42, v139
	ds_read_b128 v[164:167], v184
	ds_read_b128 v[172:175], v184 offset:1024
	ds_read_b128 v[176:179], v184 offset:2048
	ds_read_b128 v[184:187], v184 offset:3072
	ds_read_b128 v[188:191], v200
	ds_read_b128 v[192:195], v200 offset:1024
	ds_read_b128 v[196:199], v200 offset:2048
	ds_read_b128 v[200:203], v200 offset:3072
	s_add_u32 s16, s20, 0x44000
	s_addc_u32 s17, s21, 0
	s_mov_b32 m0, s27
	v_lshl_add_u64 v[240:241], s[16:17], 0, v[156:157]
	ds_read_b128 v[204:207], v171 offset:32768
	ds_read_b128 v[208:211], v171 offset:33792
	ds_read_b128 v[212:215], v171 offset:34816
	ds_read_b128 v[216:219], v171 offset:35840
	ds_read_b128 v[220:223], v171 offset:36864
	ds_read_b128 v[224:227], v171 offset:37888
	ds_read_b128 v[228:231], v171 offset:38912
	ds_read_b128 v[232:235], v171 offset:39936
	global_load_lds_dwordx4 v[240:241], off
	s_mov_b32 m0, s28
	v_lshl_add_u64 v[240:241], s[16:17], 0, v[132:133]
	global_load_lds_dwordx4 v[240:241], off
	s_waitcnt vmcnt(8)
	s_waitcnt lgkmcnt(0)
	s_barrier
	v_mfma_f32_16x16x32_bf16 v[126:129], v[164:167], v[204:207], v[126:129]
	v_mfma_f32_16x16x32_bf16 v[122:125], v[176:179], v[204:207], v[122:125]
	v_mfma_f32_16x16x32_bf16 v[118:121], v[164:167], v[212:215], v[118:121]
	v_mfma_f32_16x16x32_bf16 v[110:113], v[176:179], v[212:215], v[110:113]
	v_mfma_f32_16x16x32_bf16 v[102:105], v[164:167], v[220:223], v[102:105]
	v_mfma_f32_16x16x32_bf16 v[94:97], v[176:179], v[220:223], v[94:97]
	v_mfma_f32_16x16x32_bf16 v[86:89], v[164:167], v[228:231], v[86:89]
	v_mfma_f32_16x16x32_bf16 v[78:81], v[176:179], v[228:231], v[78:81]
	v_mfma_f32_16x16x32_bf16 v[126:129], v[172:175], v[208:211], v[126:129]
	v_mfma_f32_16x16x32_bf16 v[122:125], v[184:187], v[208:211], v[122:125]
	v_mfma_f32_16x16x32_bf16 v[118:121], v[172:175], v[216:219], v[118:121]
	v_mfma_f32_16x16x32_bf16 v[110:113], v[184:187], v[216:219], v[110:113]
	v_mfma_f32_16x16x32_bf16 v[102:105], v[172:175], v[224:227], v[102:105]
	v_mfma_f32_16x16x32_bf16 v[94:97], v[184:187], v[224:227], v[94:97]
	v_mfma_f32_16x16x32_bf16 v[86:89], v[172:175], v[232:235], v[86:89]
	v_mfma_f32_16x16x32_bf16 v[78:81], v[184:187], v[232:235], v[78:81]
	v_mfma_f32_16x16x32_bf16 v[114:117], v[188:191], v[204:207], v[114:117]
	v_mfma_f32_16x16x32_bf16 v[106:109], v[196:199], v[204:207], v[106:109]
	v_mfma_f32_16x16x32_bf16 v[98:101], v[188:191], v[212:215], v[98:101]
	v_mfma_f32_16x16x32_bf16 v[90:93], v[196:199], v[212:215], v[90:93]
	v_mfma_f32_16x16x32_bf16 v[82:85], v[188:191], v[220:223], v[82:85]
	v_mfma_f32_16x16x32_bf16 v[74:77], v[196:199], v[220:223], v[74:77]
	v_mfma_f32_16x16x32_bf16 v[70:73], v[188:191], v[228:231], v[70:73]
	v_mfma_f32_16x16x32_bf16 v[66:69], v[196:199], v[228:231], v[66:69]
	v_mfma_f32_16x16x32_bf16 v[114:117], v[192:195], v[208:211], v[114:117]
	v_mfma_f32_16x16x32_bf16 v[106:109], v[200:203], v[208:211], v[106:109]
	v_mfma_f32_16x16x32_bf16 v[98:101], v[192:195], v[216:219], v[98:101]
	v_mfma_f32_16x16x32_bf16 v[90:93], v[200:203], v[216:219], v[90:93]
	v_mfma_f32_16x16x32_bf16 v[82:85], v[192:195], v[224:227], v[82:85]
	v_mfma_f32_16x16x32_bf16 v[74:77], v[200:203], v[224:227], v[74:77]
	v_mfma_f32_16x16x32_bf16 v[70:73], v[192:195], v[232:235], v[70:73]
	v_mfma_f32_16x16x32_bf16 v[66:69], v[200:203], v[232:235], v[66:69]
	s_barrier
; #define PG8_STAGE(bufoff, gbase, voff) do { _Pragma("unroll") for (int _i = 0; _i < 2; ++_i) \
;         __builtin_amdgcn_global_load_lds((const unsigned*)((const char*)(gbase) + (voff)[_i]), (LAS unsigned*)(lds + (bufoff) + ldsw + _i * 8192), 16, 0, 0); } while (0)
; #define PG8_LDA(dst, b, h) do { _Pragma("unroll") for (int m = 0; m < 4; ++m) _Pragma("unroll") for (int k = 0; k < 2; ++k) dst[m][k] = *(const LAS bf16x8*)(lds + PG8_SA(b, h) + aoff + m * 2048 + k * 1024); } while (0)
; #define PG8_LDB(dst, b, h) do { _Pragma("unroll") for (int n = 0; n < 2; ++n) _Pragma("unroll") for (int k = 0; k < 2; ++k) dst[n][k] = *(const LAS bf16x8*)(lds + PG8_SB(b, h) + boff + n * 2048 + k * 1024); } while (0)
; #define PG8_BAR __builtin_amdgcn_s_barrier()
; template <class Epi, bool ALIGN_EPI = PG8_ALIGN, bool SP2 = PG8_SP2>
; __device__ __forceinline__ void gemm_phase(LAS uchar* lds, const Gemm g, const StaticOrder& S, const Epi& E) {
;     ...
;         for (int t = tb; t < tb + tblk; t += 2) {
;             const bool last = (t == nt - 2);
;             const char* a1 = cA + (size_t)(t + 1) * kstep;
;             const char* a2 = last ? nA : cA + (size_t)(t + 2) * kstep; const char* b2 = last ? nB : cB + (size_t)(t + 2) * kstep;
;             const char* a3 = a2 + kstep; const char* b3 = b2 + kstep;
;             if constexpr (SP2) {
;             PG8_LDB(B0, 0, 0); PG8_LDB(B1, 0, 1); PG8_SCHED; PG8_LDA(At, 0, 0); PG8_STAGE(PG8_SA(1, 1), a1 + hstepA, voffA);
;             PG8_WAIT_V(8); PG8_WAIT_L(0); PG8_BAR; PG8_MMA(0, 0, At, B0); PG8_MMA(0, 1, At, B1); PG8_BAR; PG8_SCHED;
;             PG8_LDA(At, 0, 1); PG8_STAGE(PG8_SB(0, 0), b2, voffB); PG8_STAGE(PG8_SB(0, 1), b2 + hstepB, voffB); PG8_STAGE(PG8_SA(0, 0), a2, voffA);
;             PG8_WAIT_V(8); PG8_WAIT_L(0); PG8_BAR; PG8_MMA(1, 0, At, B0); PG8_MMA(1, 1, At, B1); PG8_BAR; PG8_SCHED;
;             PG8_LDB(B0, 1, 0); PG8_LDB(B1, 1, 1); PG8_SCHED; PG8_LDA(At, 1, 0); PG8_STAGE(PG8_SA(0, 1), a2 + hstepA, voffA);
;             PG8_WAIT_V(8); PG8_WAIT_L(0); PG8_BAR; PG8_MMA(0, 0, At, B0); PG8_MMA(0, 1, At, B1); PG8_BAR; PG8_SCHED;
;             PG8_LDA(At, 1, 1); PG8_STAGE(PG8_SB(1, 0), b3, voffB); PG8_STAGE(PG8_SB(1, 1), b3 + hstepB, voffB); PG8_STAGE(PG8_SA(1, 0), a3, voffA);
;             PG8_WAIT_V(8); PG8_WAIT_L(0); PG8_BAR; PG8_MMA(1, 0, At, B0); PG8_MMA(1, 1, At, B1); PG8_BAR; PG8_SCHED;
	s_add_i32 s16, s41, s23
	v_lshl_add_u64 v[168:169], v[168:169], 0, s[84:85]
	s_mov_b32 m0, s16
	ds_read_b128 v[204:207], v171 offset:49152
	ds_read_b128 v[208:211], v171 offset:50176
	ds_read_b128 v[212:215], v171 offset:51200
	ds_read_b128 v[216:219], v171 offset:52224
	ds_read_b128 v[220:223], v171 offset:53248
	ds_read_b128 v[224:227], v171 offset:54272
	ds_read_b128 v[228:231], v171 offset:55296
	ds_read_b128 v[232:235], v171 offset:56320
	global_load_lds_dwordx4 v[168:169], off
	s_add_i32 m0, s16, 0x2000
	s_add_u32 s4, s4, 0x44080
	v_lshl_add_u64 v[168:169], v[180:181], 0, s[84:85]
	s_addc_u32 s5, s5, 0
	s_add_i32 s16, s42, s23
	global_load_lds_dwordx4 v[168:169], off
	s_mov_b32 m0, s16
	v_lshl_add_u64 v[168:169], s[4:5], 0, v[134:135]
	global_load_lds_dwordx4 v[168:169], off
	s_add_i32 m0, s16, 0x2000
	v_lshl_add_u64 v[168:169], s[4:5], 0, v[130:131]
	global_load_lds_dwordx4 v[168:169], off
	s_mov_b32 m0, s29
	v_lshl_add_u64 v[168:169], v[236:237], 0, s[84:85]
	global_load_lds_dwordx4 v[168:169], off
	s_mov_b32 m0, s30
	v_lshl_add_u64 v[168:169], v[238:239], 0, s[84:85]
	global_load_lds_dwordx4 v[168:169], off
	s_waitcnt vmcnt(8)
	s_waitcnt lgkmcnt(0)
	s_barrier
	v_mfma_f32_16x16x32_bf16 v[62:65], v[164:167], v[204:207], v[62:65]
	v_mfma_f32_16x16x32_bf16 v[58:61], v[176:179], v[204:207], v[58:61]
	v_mfma_f32_16x16x32_bf16 v[54:57], v[164:167], v[212:215], v[54:57]
	v_mfma_f32_16x16x32_bf16 v[46:49], v[176:179], v[212:215], v[46:49]
	v_mfma_f32_16x16x32_bf16 v[38:41], v[164:167], v[220:223], v[38:41]
	v_mfma_f32_16x16x32_bf16 v[30:33], v[176:179], v[220:223], v[30:33]
	v_mfma_f32_16x16x32_bf16 v[22:25], v[164:167], v[228:231], v[22:25]
	v_mfma_f32_16x16x32_bf16 v[14:17], v[176:179], v[228:231], v[14:17]
	v_mfma_f32_16x16x32_bf16 v[62:65], v[172:175], v[208:211], v[62:65]
	v_mfma_f32_16x16x32_bf16 v[58:61], v[184:187], v[208:211], v[58:61]
	v_mfma_f32_16x16x32_bf16 v[54:57], v[172:175], v[216:219], v[54:57]
	v_mfma_f32_16x16x32_bf16 v[46:49], v[184:187], v[216:219], v[46:49]
	v_mfma_f32_16x16x32_bf16 v[38:41], v[172:175], v[224:227], v[38:41]
	v_mfma_f32_16x16x32_bf16 v[30:33], v[184:187], v[224:227], v[30:33]
	v_mfma_f32_16x16x32_bf16 v[22:25], v[172:175], v[232:235], v[22:25]
	v_mfma_f32_16x16x32_bf16 v[14:17], v[184:187], v[232:235], v[14:17]
	v_mfma_f32_16x16x32_bf16 v[50:53], v[188:191], v[204:207], v[50:53]
	v_mfma_f32_16x16x32_bf16 v[42:45], v[196:199], v[204:207], v[42:45]
	v_mfma_f32_16x16x32_bf16 v[34:37], v[188:191], v[212:215], v[34:37]
	v_mfma_f32_16x16x32_bf16 v[26:29], v[196:199], v[212:215], v[26:29]
	v_mfma_f32_16x16x32_bf16 v[18:21], v[188:191], v[220:223], v[18:21]
	v_mfma_f32_16x16x32_bf16 v[10:13], v[196:199], v[220:223], v[10:13]
	v_mfma_f32_16x16x32_bf16 v[6:9], v[188:191], v[228:231], v[6:9]
	v_mfma_f32_16x16x32_bf16 v[2:5], v[196:199], v[228:231], v[2:5]
	v_mfma_f32_16x16x32_bf16 v[50:53], v[192:195], v[208:211], v[50:53]
	v_mfma_f32_16x16x32_bf16 v[42:45], v[200:203], v[208:211], v[42:45]
	v_mfma_f32_16x16x32_bf16 v[34:37], v[192:195], v[216:219], v[34:37]
	v_mfma_f32_16x16x32_bf16 v[26:29], v[200:203], v[216:219], v[26:29]
	v_mfma_f32_16x16x32_bf16 v[18:21], v[192:195], v[224:227], v[18:21]
	v_mfma_f32_16x16x32_bf16 v[10:13], v[200:203], v[224:227], v[10:13]
	v_mfma_f32_16x16x32_bf16 v[6:9], v[192:195], v[232:235], v[6:9]
	v_mfma_f32_16x16x32_bf16 v[2:5], v[200:203], v[232:235], v[2:5]
	s_barrier
	s_add_i32 s40, s40, 2
	s_add_u32 s38, s38, 0x100
	s_addc_u32 s39, s39, 0
	s_cmp_gt_u32 s40, 13
	s_mov_b64 s[16:17], s[18:19]
.LBB0_345:
	s_add_u32 s18, s16, 0x100
	s_addc_u32 s19, s17, 0
	s_add_i32 s41, 0, 0x10000
	s_cmp_eq_u32 s40, 12
	s_cselect_b32 s21, s7, s19
	s_cselect_b32 s20, s6, s18
	v_add_u32_e32 v168, s41, v139
	s_cselect_b32 s5, s15, s39
	s_cselect_b32 s4, s14, s38
	s_add_i32 s42, 0, 0x14000
	ds_read_b128 v[164:167], v168
	ds_read_b128 v[172:175], v168 offset:1024
	ds_read_b128 v[176:179], v168 offset:2048
	ds_read_b128 v[184:187], v168 offset:3072
	v_add_u32_e32 v168, s42, v139
	ds_read_b128 v[188:191], v168
	ds_read_b128 v[192:195], v168 offset:1024
	ds_read_b128 v[196:199], v168 offset:2048
	ds_read_b128 v[200:203], v168 offset:3072
	v_lshl_add_u64 v[168:169], s[16:17], 0, v[160:161]
	s_add_i32 m0, s25, 0xc000
	ds_read_b128 v[204:207], v171
	ds_read_b128 v[208:211], v171 offset:1024
	ds_read_b128 v[212:215], v171 offset:2048
	ds_read_b128 v[216:219], v171 offset:3072
	ds_read_b128 v[220:223], v171 offset:4096
	ds_read_b128 v[224:227], v171 offset:5120
	ds_read_b128 v[228:231], v171 offset:6144
	ds_read_b128 v[232:235], v171 offset:7168
	global_load_lds_dwordx4 v[168:169], off
	s_add_i32 m0, s25, 0xe000
	v_lshl_add_u64 v[168:169], s[16:17], 0, v[162:163]
	global_load_lds_dwordx4 v[168:169], off
	s_waitcnt vmcnt(8)
	s_waitcnt lgkmcnt(0)
	s_barrier
; #define PG8_STAGE(bufoff, gbase, voff) do { _Pragma("unroll") for (int _i = 0; _i < 2; ++_i) \
;         __builtin_amdgcn_global_load_lds((const unsigned*)((const char*)(gbase) + (voff)[_i]), (LAS unsigned*)(lds + (bufoff) + ldsw + _i * 8192), 16, 0, 0); } while (0)
; #define PG8_LDA(dst, b, h) do { _Pragma("unroll") for (int m = 0; m < 4; ++m) _Pragma("unroll") for (int k = 0; k < 2; ++k) dst[m][k] = *(const LAS bf16x8*)(lds + PG8_SA(b, h) + aoff + m * 2048 + k * 1024); } while (0)
; #define PG8_MMA(ai, bj, At, Bt) do { __builtin_amdgcn_s_setprio(1); _Pragma("unroll") for (int m = 0; m < 4; ++m) _Pragma("unroll") for (int n = 0; n < 2; ++n) _Pragma("unroll") for (int k = 0; k < 2; ++k) \
;         acc[ai][bj][m][n] = __builtin_amdgcn_mfma_f32_16x16x32_bf16(Bt[n][k], At[m][k], acc[ai][bj][m][n], 0, 0, 0); __builtin_amdgcn_s_setprio(0); } while (0)
; #define PG8_WAIT_V(n) asm volatile("s_waitcnt vmcnt(" #n ")" ::: "memory")
; #define PG8_WAIT_L(n) asm volatile("s_waitcnt lgkmcnt(" #n ")" ::: "memory")
; #define PG8_BAR __builtin_amdgcn_s_barrier()
; #define PG8_SCHED __builtin_amdgcn_sched_barrier(0)
; template <class Epi, bool ALIGN_EPI = PG8_ALIGN, bool SP2 = PG8_SP2>
; __device__ __forceinline__ void gemm_phase(LAS uchar* lds, const Gemm g, const StaticOrder& S, const Epi& E) {
;     ...
;             PG8_WAIT_V(8); PG8_WAIT_L(0); PG8_BAR; PG8_MMA(0, 0, At, B0); PG8_MMA(0, 1, At, B1); PG8_BAR; PG8_SCHED;
;             PG8_LDA(At, 0, 1); PG8_STAGE(PG8_SB(0, 0), b2, voffB); PG8_STAGE(PG8_SB(0, 1), b2 + hstepB, voffB); PG8_STAGE(PG8_SA(0, 0), a2, voffA);
;             PG8_WAIT_V(8); PG8_WAIT_L(0); PG8_BAR; PG8_MMA(1, 0, At, B0); PG8_MMA(1, 1, At, B1); PG8_BAR; PG8_SCHED;
	v_mfma_f32_16x16x32_bf16 v[126:129], v[164:167], v[204:207], v[126:129]
	v_mfma_f32_16x16x32_bf16 v[122:125], v[176:179], v[204:207], v[122:125]
	v_mfma_f32_16x16x32_bf16 v[118:121], v[164:167], v[212:215], v[118:121]
	v_mfma_f32_16x16x32_bf16 v[110:113], v[176:179], v[212:215], v[110:113]
	v_mfma_f32_16x16x32_bf16 v[102:105], v[164:167], v[220:223], v[102:105]
	v_mfma_f32_16x16x32_bf16 v[94:97], v[176:179], v[220:223], v[94:97]
	v_mfma_f32_16x16x32_bf16 v[86:89], v[164:167], v[228:231], v[86:89]
	v_mfma_f32_16x16x32_bf16 v[78:81], v[176:179], v[228:231], v[78:81]
	v_mfma_f32_16x16x32_bf16 v[126:129], v[172:175], v[208:211], v[126:129]
	v_mfma_f32_16x16x32_bf16 v[122:125], v[184:187], v[208:211], v[122:125]
	v_mfma_f32_16x16x32_bf16 v[118:121], v[172:175], v[216:219], v[118:121]
	v_mfma_f32_16x16x32_bf16 v[110:113], v[184:187], v[216:219], v[110:113]
	v_mfma_f32_16x16x32_bf16 v[102:105], v[172:175], v[224:227], v[102:105]
	v_mfma_f32_16x16x32_bf16 v[94:97], v[184:187], v[224:227], v[94:97]
	v_mfma_f32_16x16x32_bf16 v[86:89], v[172:175], v[232:235], v[86:89]
	v_mfma_f32_16x16x32_bf16 v[78:81], v[184:187], v[232:235], v[78:81]
	v_mfma_f32_16x16x32_bf16 v[114:117], v[188:191], v[204:207], v[114:117]
	v_mfma_f32_16x16x32_bf16 v[106:109], v[196:199], v[204:207], v[106:109]
	v_mfma_f32_16x16x32_bf16 v[98:101], v[188:191], v[212:215], v[98:101]
	v_mfma_f32_16x16x32_bf16 v[90:93], v[196:199], v[212:215], v[90:93]
	v_mfma_f32_16x16x32_bf16 v[82:85], v[188:191], v[220:223], v[82:85]
	v_mfma_f32_16x16x32_bf16 v[74:77], v[196:199], v[220:223], v[74:77]
	v_mfma_f32_16x16x32_bf16 v[70:73], v[188:191], v[228:231], v[70:73]
	v_mfma_f32_16x16x32_bf16 v[66:69], v[196:199], v[228:231], v[66:69]
	v_mfma_f32_16x16x32_bf16 v[114:117], v[192:195], v[208:211], v[114:117]
	v_mfma_f32_16x16x32_bf16 v[106:109], v[200:203], v[208:211], v[106:109]
	v_mfma_f32_16x16x32_bf16 v[98:101], v[192:195], v[216:219], v[98:101]
	v_mfma_f32_16x16x32_bf16 v[90:93], v[200:203], v[216:219], v[90:93]
	v_mfma_f32_16x16x32_bf16 v[82:85], v[192:195], v[224:227], v[82:85]
	v_mfma_f32_16x16x32_bf16 v[74:77], v[200:203], v[224:227], v[74:77]
	v_mfma_f32_16x16x32_bf16 v[70:73], v[192:195], v[232:235], v[70:73]
	v_mfma_f32_16x16x32_bf16 v[66:69], v[200:203], v[232:235], v[66:69]
	s_barrier
	s_add_i32 s16, s41, s23
	v_lshl_add_u64 v[168:169], s[4:5], 0, v[134:135]
	s_mov_b32 m0, s16
	ds_read_b128 v[204:207], v171 offset:16384
	ds_read_b128 v[208:211], v171 offset:17408
	ds_read_b128 v[212:215], v171 offset:18432
	ds_read_b128 v[216:219], v171 offset:19456
	ds_read_b128 v[220:223], v171 offset:20480
	ds_read_b128 v[224:227], v171 offset:21504
	ds_read_b128 v[228:231], v171 offset:22528
	ds_read_b128 v[232:235], v171 offset:23552
	global_load_lds_dwordx4 v[168:169], off
	s_add_i32 m0, s16, 0x2000
	s_add_u32 s16, s4, 0x44000
	v_lshl_add_u64 v[180:181], s[4:5], 0, v[130:131]
	s_addc_u32 s17, s5, 0
	s_add_i32 s41, s42, s23
	global_load_lds_dwordx4 v[180:181], off
	v_lshl_add_u64 v[236:237], s[16:17], 0, v[134:135]
	s_mov_b32 m0, s41
	global_load_lds_dwordx4 v[236:237], off
	s_add_i32 m0, s41, 0x2000
	v_lshl_add_u64 v[236:237], s[16:17], 0, v[130:131]
	global_load_lds_dwordx4 v[236:237], off
	s_mov_b32 m0, s25
	v_lshl_add_u64 v[236:237], s[20:21], 0, v[156:157]
	global_load_lds_dwordx4 v[236:237], off
	s_mov_b32 m0, s26
	v_lshl_add_u64 v[238:239], s[20:21], 0, v[132:133]
	global_load_lds_dwordx4 v[238:239], off
	s_waitcnt vmcnt(8)
	s_waitcnt lgkmcnt(0)
	s_barrier
	v_mfma_f32_16x16x32_bf16 v[62:65], v[164:167], v[204:207], v[62:65]
	v_mfma_f32_16x16x32_bf16 v[58:61], v[176:179], v[204:207], v[58:61]
	v_mfma_f32_16x16x32_bf16 v[54:57], v[164:167], v[212:215], v[54:57]
	v_mfma_f32_16x16x32_bf16 v[46:49], v[176:179], v[212:215], v[46:49]
	v_mfma_f32_16x16x32_bf16 v[38:41], v[164:167], v[220:223], v[38:41]
	v_mfma_f32_16x16x32_bf16 v[30:33], v[176:179], v[220:223], v[30:33]
	v_mfma_f32_16x16x32_bf16 v[22:25], v[164:167], v[228:231], v[22:25]
	v_mfma_f32_16x16x32_bf16 v[14:17], v[176:179], v[228:231], v[14:17]
	v_mfma_f32_16x16x32_bf16 v[62:65], v[172:175], v[208:211], v[62:65]
	v_mfma_f32_16x16x32_bf16 v[58:61], v[184:187], v[208:211], v[58:61]
	v_mfma_f32_16x16x32_bf16 v[54:57], v[172:175], v[216:219], v[54:57]
	v_mfma_f32_16x16x32_bf16 v[46:49], v[184:187], v[216:219], v[46:49]
	v_mfma_f32_16x16x32_bf16 v[38:41], v[172:175], v[224:227], v[38:41]
	v_mfma_f32_16x16x32_bf16 v[30:33], v[184:187], v[224:227], v[30:33]
	v_mfma_f32_16x16x32_bf16 v[22:25], v[172:175], v[232:235], v[22:25]
	v_mfma_f32_16x16x32_bf16 v[14:17], v[184:187], v[232:235], v[14:17]
	v_mfma_f32_16x16x32_bf16 v[50:53], v[188:191], v[204:207], v[50:53]
	v_mfma_f32_16x16x32_bf16 v[42:45], v[196:199], v[204:207], v[42:45]
	v_mfma_f32_16x16x32_bf16 v[34:37], v[188:191], v[212:215], v[34:37]
	v_mfma_f32_16x16x32_bf16 v[26:29], v[196:199], v[212:215], v[26:29]
	v_mfma_f32_16x16x32_bf16 v[18:21], v[188:191], v[220:223], v[18:21]
	v_mfma_f32_16x16x32_bf16 v[10:13], v[196:199], v[220:223], v[10:13]
	v_mfma_f32_16x16x32_bf16 v[6:9], v[188:191], v[228:231], v[6:9]
	v_mfma_f32_16x16x32_bf16 v[2:5], v[196:199], v[228:231], v[2:5]
	v_mfma_f32_16x16x32_bf16 v[50:53], v[192:195], v[208:211], v[50:53]
	v_mfma_f32_16x16x32_bf16 v[42:45], v[200:203], v[208:211], v[42:45]
	v_mfma_f32_16x16x32_bf16 v[34:37], v[192:195], v[216:219], v[34:37]
	v_mfma_f32_16x16x32_bf16 v[26:29], v[200:203], v[216:219], v[26:29]
	v_mfma_f32_16x16x32_bf16 v[18:21], v[192:195], v[224:227], v[18:21]
	v_mfma_f32_16x16x32_bf16 v[10:13], v[200:203], v[224:227], v[10:13]
	v_mfma_f32_16x16x32_bf16 v[6:9], v[192:195], v[232:235], v[6:9]
	v_mfma_f32_16x16x32_bf16 v[2:5], v[200:203], v[232:235], v[2:5]
	s_barrier
; #define PG8_STAGE(bufoff, gbase, voff) do { _Pragma("unroll") for (int _i = 0; _i < 2; ++_i) \
;         __builtin_amdgcn_global_load_lds((const unsigned*)((const char*)(gbase) + (voff)[_i]), (LAS unsigned*)(lds + (bufoff) + ldsw + _i * 8192), 16, 0, 0); } while (0)
; #define PG8_LDA(dst, b, h) do { _Pragma("unroll") for (int m = 0; m < 4; ++m) _Pragma("unroll") for (int k = 0; k < 2; ++k) dst[m][k] = *(const LAS bf16x8*)(lds + PG8_SA(b, h) + aoff + m * 2048 + k * 1024); } while (0)
; #define PG8_LDB(dst, b, h) do { _Pragma("unroll") for (int n = 0; n < 2; ++n) _Pragma("unroll") for (int k = 0; k < 2; ++k) dst[n][k] = *(const LAS bf16x8*)(lds + PG8_SB(b, h) + boff + n * 2048 + k * 1024); } while (0)
; #define PG8_MMA(ai, bj, At, Bt) do { __builtin_amdgcn_s_setprio(1); _Pragma("unroll") for (int m = 0; m < 4; ++m) _Pragma("unroll") for (int n = 0; n < 2; ++n) _Pragma("unroll") for (int k = 0; k < 2; ++k) \
;         acc[ai][bj][m][n] = __builtin_amdgcn_mfma_f32_16x16x32_bf16(Bt[n][k], At[m][k], acc[ai][bj][m][n], 0, 0, 0); __builtin_amdgcn_s_setprio(0); } while (0)
; #define PG8_WAIT_V(n) asm volatile("s_waitcnt vmcnt(" #n ")" ::: "memory")
; #define PG8_WAIT_L(n) asm volatile("s_waitcnt lgkmcnt(" #n ")" ::: "memory")
; #define PG8_BAR __builtin_amdgcn_s_barrier()
; #define PG8_SCHED __builtin_amdgcn_sched_barrier(0)
; template <class Epi, bool ALIGN_EPI = PG8_ALIGN, bool SP2 = PG8_SP2>
; __device__ __forceinline__ void gemm_phase(LAS uchar* lds, const Gemm g, const StaticOrder& S, const Epi& E) {
;     ...
;             PG8_LDB(B0, 1, 0); PG8_LDB(B1, 1, 1); PG8_SCHED; PG8_LDA(At, 1, 0); PG8_STAGE(PG8_SA(0, 1), a2 + hstepA, voffA);
;             PG8_WAIT_V(8); PG8_WAIT_L(0); PG8_BAR; PG8_MMA(0, 0, At, B0); PG8_MMA(0, 1, At, B1); PG8_BAR; PG8_SCHED;
	s_add_i32 s41, 0, 0x18000
	s_add_i32 s42, 0, 0x1c000
	v_add_u32_e32 v184, s41, v139
	v_add_u32_e32 v200, s42, v139
	ds_read_b128 v[164:167], v184
	ds_read_b128 v[172:175], v184 offset:1024
	ds_read_b128 v[176:179], v184 offset:2048
	ds_read_b128 v[184:187], v184 offset:3072
	ds_read_b128 v[188:191], v200
	ds_read_b128 v[192:195], v200 offset:1024
	ds_read_b128 v[196:199], v200 offset:2048
	ds_read_b128 v[200:203], v200 offset:3072
	s_add_u32 s16, s20, 0x44000
	s_addc_u32 s17, s21, 0
	s_mov_b32 m0, s27
	v_lshl_add_u64 v[240:241], s[16:17], 0, v[156:157]
	ds_read_b128 v[204:207], v171 offset:32768
	ds_read_b128 v[208:211], v171 offset:33792
	ds_read_b128 v[212:215], v171 offset:34816
	ds_read_b128 v[216:219], v171 offset:35840
	ds_read_b128 v[220:223], v171 offset:36864
	ds_read_b128 v[224:227], v171 offset:37888
	ds_read_b128 v[228:231], v171 offset:38912
	ds_read_b128 v[232:235], v171 offset:39936
	global_load_lds_dwordx4 v[240:241], off
	s_mov_b32 m0, s28
	v_lshl_add_u64 v[240:241], s[16:17], 0, v[132:133]
	global_load_lds_dwordx4 v[240:241], off
	s_waitcnt vmcnt(8)
	s_waitcnt lgkmcnt(0)
	s_barrier
	v_mfma_f32_16x16x32_bf16 v[126:129], v[164:167], v[204:207], v[126:129]
	v_mfma_f32_16x16x32_bf16 v[122:125], v[176:179], v[204:207], v[122:125]
	v_mfma_f32_16x16x32_bf16 v[118:121], v[164:167], v[212:215], v[118:121]
	v_mfma_f32_16x16x32_bf16 v[110:113], v[176:179], v[212:215], v[110:113]
	v_mfma_f32_16x16x32_bf16 v[102:105], v[164:167], v[220:223], v[102:105]
	v_mfma_f32_16x16x32_bf16 v[94:97], v[176:179], v[220:223], v[94:97]
	v_mfma_f32_16x16x32_bf16 v[86:89], v[164:167], v[228:231], v[86:89]
	v_mfma_f32_16x16x32_bf16 v[78:81], v[176:179], v[228:231], v[78:81]
	v_mfma_f32_16x16x32_bf16 v[126:129], v[172:175], v[208:211], v[126:129]
	v_mfma_f32_16x16x32_bf16 v[122:125], v[184:187], v[208:211], v[122:125]
	v_mfma_f32_16x16x32_bf16 v[118:121], v[172:175], v[216:219], v[118:121]
	v_mfma_f32_16x16x32_bf16 v[110:113], v[184:187], v[216:219], v[110:113]
	v_mfma_f32_16x16x32_bf16 v[102:105], v[172:175], v[224:227], v[102:105]
	v_mfma_f32_16x16x32_bf16 v[94:97], v[184:187], v[224:227], v[94:97]
	v_mfma_f32_16x16x32_bf16 v[86:89], v[172:175], v[232:235], v[86:89]
	v_mfma_f32_16x16x32_bf16 v[78:81], v[184:187], v[232:235], v[78:81]
	v_mfma_f32_16x16x32_bf16 v[114:117], v[188:191], v[204:207], v[114:117]
	v_mfma_f32_16x16x32_bf16 v[106:109], v[196:199], v[204:207], v[106:109]
	v_mfma_f32_16x16x32_bf16 v[98:101], v[188:191], v[212:215], v[98:101]
	v_mfma_f32_16x16x32_bf16 v[90:93], v[196:199], v[212:215], v[90:93]
	v_mfma_f32_16x16x32_bf16 v[82:85], v[188:191], v[220:223], v[82:85]
	v_mfma_f32_16x16x32_bf16 v[74:77], v[196:199], v[220:223], v[74:77]
	v_mfma_f32_16x16x32_bf16 v[70:73], v[188:191], v[228:231], v[70:73]
	v_mfma_f32_16x16x32_bf16 v[66:69], v[196:199], v[228:231], v[66:69]
	v_mfma_f32_16x16x32_bf16 v[114:117], v[192:195], v[208:211], v[114:117]
	v_mfma_f32_16x16x32_bf16 v[106:109], v[200:203], v[208:211], v[106:109]
	v_mfma_f32_16x16x32_bf16 v[98:101], v[192:195], v[216:219], v[98:101]
	v_mfma_f32_16x16x32_bf16 v[90:93], v[200:203], v[216:219], v[90:93]
	v_mfma_f32_16x16x32_bf16 v[82:85], v[192:195], v[224:227], v[82:85]
	v_mfma_f32_16x16x32_bf16 v[74:77], v[200:203], v[224:227], v[74:77]
	v_mfma_f32_16x16x32_bf16 v[70:73], v[192:195], v[232:235], v[70:73]
	v_mfma_f32_16x16x32_bf16 v[66:69], v[200:203], v[232:235], v[66:69]
	s_barrier
; #define PG8_STAGE(bufoff, gbase, voff) do { _Pragma("unroll") for (int _i = 0; _i < 2; ++_i) \
;         __builtin_amdgcn_global_load_lds((const unsigned*)((const char*)(gbase) + (voff)[_i]), (LAS unsigned*)(lds + (bufoff) + ldsw + _i * 8192), 16, 0, 0); } while (0)
; #define PG8_LDA(dst, b, h) do { _Pragma("unroll") for (int m = 0; m < 4; ++m) _Pragma("unroll") for (int k = 0; k < 2; ++k) dst[m][k] = *(const LAS bf16x8*)(lds + PG8_SA(b, h) + aoff + m * 2048 + k * 1024); } while (0)
; #define PG8_MMA(ai, bj, At, Bt) do { __builtin_amdgcn_s_setprio(1); _Pragma("unroll") for (int m = 0; m < 4; ++m) _Pragma("unroll") for (int n = 0; n < 2; ++n) _Pragma("unroll") for (int k = 0; k < 2; ++k) \
;         acc[ai][bj][m][n] = __builtin_amdgcn_mfma_f32_16x16x32_bf16(Bt[n][k], At[m][k], acc[ai][bj][m][n], 0, 0, 0); __builtin_amdgcn_s_setprio(0); } while (0)
; #define PG8_WAIT_V(n) asm volatile("s_waitcnt vmcnt(" #n ")" ::: "memory")
; #define PG8_WAIT_L(n) asm volatile("s_waitcnt lgkmcnt(" #n ")" ::: "memory")
; #define PG8_BAR __builtin_amdgcn_s_barrier()
; #define PG8_SCHED __builtin_amdgcn_sched_barrier(0)
; template <class Epi, bool ALIGN_EPI = PG8_ALIGN, bool SP2 = PG8_SP2>
; __device__ __forceinline__ void gemm_phase(LAS uchar* lds, const Gemm g, const StaticOrder& S, const Epi& E) {
;     ...
;             PG8_LDA(At, 1, 1); PG8_STAGE(PG8_SB(1, 0), b3, voffB); PG8_STAGE(PG8_SB(1, 1), b3 + hstepB, voffB); PG8_STAGE(PG8_SA(1, 0), a3, voffA);
;             PG8_WAIT_V(8); PG8_WAIT_L(0); PG8_BAR; PG8_MMA(1, 0, At, B0); PG8_MMA(1, 1, At, B1); PG8_BAR; PG8_SCHED;
;     __device__ __forceinline__ void operator()(const f32x4 (&acc)[2][2][4][2], const pg8::Unit& u, int wr, int wc, int fr, int fq, int) const {
;         const int row0 = u.pm * 256 + wr * 64 + fr;
;         if (u.pn < 24) {
	s_add_i32 s16, s41, s23
	v_lshl_add_u64 v[168:169], v[168:169], 0, s[84:85]
	s_mov_b32 m0, s16
	ds_read_b128 v[204:207], v171 offset:49152
	ds_read_b128 v[208:211], v171 offset:50176
	ds_read_b128 v[212:215], v171 offset:51200
	ds_read_b128 v[216:219], v171 offset:52224
	ds_read_b128 v[220:223], v171 offset:53248
	ds_read_b128 v[224:227], v171 offset:54272
	ds_read_b128 v[228:231], v171 offset:55296
	ds_read_b128 v[232:235], v171 offset:56320
	global_load_lds_dwordx4 v[168:169], off
	s_add_i32 m0, s16, 0x2000
	s_add_u32 s4, s4, 0x44080
	v_lshl_add_u64 v[168:169], v[180:181], 0, s[84:85]
	s_addc_u32 s5, s5, 0
	s_add_i32 s16, s42, s23
	global_load_lds_dwordx4 v[168:169], off
	s_mov_b32 m0, s16
	v_lshl_add_u64 v[168:169], s[4:5], 0, v[134:135]
	global_load_lds_dwordx4 v[168:169], off
	s_add_i32 m0, s16, 0x2000
	v_lshl_add_u64 v[168:169], s[4:5], 0, v[130:131]
	global_load_lds_dwordx4 v[168:169], off
	s_mov_b32 m0, s29
	v_lshl_add_u64 v[168:169], v[236:237], 0, s[84:85]
	global_load_lds_dwordx4 v[168:169], off
	s_mov_b32 m0, s30
	v_lshl_add_u64 v[168:169], v[238:239], 0, s[84:85]
	global_load_lds_dwordx4 v[168:169], off
	s_waitcnt vmcnt(8)
	s_waitcnt lgkmcnt(0)
	s_barrier
	v_mfma_f32_16x16x32_bf16 v[62:65], v[164:167], v[204:207], v[62:65]
	v_mfma_f32_16x16x32_bf16 v[58:61], v[176:179], v[204:207], v[58:61]
	v_mfma_f32_16x16x32_bf16 v[54:57], v[164:167], v[212:215], v[54:57]
	v_mfma_f32_16x16x32_bf16 v[46:49], v[176:179], v[212:215], v[46:49]
	v_mfma_f32_16x16x32_bf16 v[38:41], v[164:167], v[220:223], v[38:41]
	v_mfma_f32_16x16x32_bf16 v[30:33], v[176:179], v[220:223], v[30:33]
	v_mfma_f32_16x16x32_bf16 v[22:25], v[164:167], v[228:231], v[22:25]
	v_mfma_f32_16x16x32_bf16 v[14:17], v[176:179], v[228:231], v[14:17]
	v_mfma_f32_16x16x32_bf16 v[62:65], v[172:175], v[208:211], v[62:65]
	v_mfma_f32_16x16x32_bf16 v[58:61], v[184:187], v[208:211], v[58:61]
	v_mfma_f32_16x16x32_bf16 v[54:57], v[172:175], v[216:219], v[54:57]
	v_mfma_f32_16x16x32_bf16 v[46:49], v[184:187], v[216:219], v[46:49]
	v_mfma_f32_16x16x32_bf16 v[38:41], v[172:175], v[224:227], v[38:41]
	v_mfma_f32_16x16x32_bf16 v[30:33], v[184:187], v[224:227], v[30:33]
	v_mfma_f32_16x16x32_bf16 v[22:25], v[172:175], v[232:235], v[22:25]
	v_mfma_f32_16x16x32_bf16 v[14:17], v[184:187], v[232:235], v[14:17]
	v_mfma_f32_16x16x32_bf16 v[50:53], v[188:191], v[204:207], v[50:53]
	v_mfma_f32_16x16x32_bf16 v[42:45], v[196:199], v[204:207], v[42:45]
	v_mfma_f32_16x16x32_bf16 v[34:37], v[188:191], v[212:215], v[34:37]
	v_mfma_f32_16x16x32_bf16 v[26:29], v[196:199], v[212:215], v[26:29]
	v_mfma_f32_16x16x32_bf16 v[18:21], v[188:191], v[220:223], v[18:21]
	v_mfma_f32_16x16x32_bf16 v[10:13], v[196:199], v[220:223], v[10:13]
	v_mfma_f32_16x16x32_bf16 v[6:9], v[188:191], v[228:231], v[6:9]
	v_mfma_f32_16x16x32_bf16 v[2:5], v[196:199], v[228:231], v[2:5]
	v_mfma_f32_16x16x32_bf16 v[50:53], v[192:195], v[208:211], v[50:53]
	v_mfma_f32_16x16x32_bf16 v[42:45], v[200:203], v[208:211], v[42:45]
	v_mfma_f32_16x16x32_bf16 v[34:37], v[192:195], v[216:219], v[34:37]
	v_mfma_f32_16x16x32_bf16 v[26:29], v[200:203], v[216:219], v[26:29]
	v_mfma_f32_16x16x32_bf16 v[18:21], v[192:195], v[224:227], v[18:21]
	v_mfma_f32_16x16x32_bf16 v[10:13], v[200:203], v[224:227], v[10:13]
	v_mfma_f32_16x16x32_bf16 v[6:9], v[192:195], v[232:235], v[6:9]
	v_mfma_f32_16x16x32_bf16 v[2:5], v[200:203], v[232:235], v[2:5]
	s_barrier
	s_add_i32 s40, s40, 2
	s_add_u32 s38, s38, 0x100
	s_addc_u32 s39, s39, 0
	s_cmp_gt_u32 s40, 13
	s_mov_b64 s[16:17], s[18:19]
	s_cbranch_scc0 .LBB0_345
	s_mov_b32 s97, 0
	s_and_b64 vcc, exec, s[10:11]
	s_cbranch_vccnz .LBB0_350
	v_lshl_add_u32 v164, s37, 8, v1
	s_cmp_gt_i32 s36, 23
	s_mov_b64 s[4:5], -1
	s_cbranch_scc1 .LBB0_351

; #define PG8_STAGE(bufoff, gbase, voff) do { _Pragma("unroll") for (int _i = 0; _i < 2; ++_i) \
;         __builtin_amdgcn_global_load_lds((const unsigned*)((const char*)(gbase) + (voff)[_i]), (LAS unsigned*)(lds + (bufoff) + ldsw + _i * 8192), 16, 0, 0); } while (0)
; #define PG8_LDA(dst, b, h) do { _Pragma("unroll") for (int m = 0; m < 4; ++m) _Pragma("unroll") for (int k = 0; k < 2; ++k) dst[m][k] = *(const LAS bf16x8*)(lds + PG8_SA(b, h) + aoff + m * 2048 + k * 1024); } while (0)
; #define PG8_LDB(dst, b, h) do { _Pragma("unroll") for (int n = 0; n < 2; ++n) _Pragma("unroll") for (int k = 0; k < 2; ++k) dst[n][k] = *(const LAS bf16x8*)(lds + PG8_SB(b, h) + boff + n * 2048 + k * 1024); } while (0)
; #define PG8_MMA(ai, bj, At, Bt) do { __builtin_amdgcn_s_setprio(1); _Pragma("unroll") for (int m = 0; m < 4; ++m) _Pragma("unroll") for (int n = 0; n < 2; ++n) _Pragma("unroll") for (int k = 0; k < 2; ++k) \
;         acc[ai][bj][m][n] = __builtin_amdgcn_mfma_f32_16x16x32_bf16(Bt[n][k], At[m][k], acc[ai][bj][m][n], 0, 0, 0); __builtin_amdgcn_s_setprio(0); } while (0)
; #define PG8_WAIT_V(n) asm volatile("s_waitcnt vmcnt(" #n ")" ::: "memory")
; #define PG8_WAIT_L(n) asm volatile("s_waitcnt lgkmcnt(" #n ")" ::: "memory")
; #define PG8_BAR __builtin_amdgcn_s_barrier()
; #define PG8_SCHED __builtin_amdgcn_sched_barrier(0)
; template <class Epi, bool ALIGN_EPI = PG8_ALIGN, bool SP2 = PG8_SP2>
; __device__ __forceinline__ void gemm_phase(LAS uchar* lds, const Gemm g, const StaticOrder& S, const Epi& E) {
;     ...
;         for (int t = tb; t < tb + tblk; t += 2) {
;             const bool last = (t == nt - 2);
;             const char* a1 = cA + (size_t)(t + 1) * kstep;
;             const char* a2 = last ? nA : cA + (size_t)(t + 2) * kstep; const char* b2 = last ? nB : cB + (size_t)(t + 2) * kstep;
;             const char* a3 = a2 + kstep; const char* b3 = b2 + kstep;
;             if constexpr (SP2) {
;             PG8_LDB(B0, 0, 0); PG8_LDB(B1, 0, 1); PG8_SCHED; PG8_LDA(At, 0, 0); PG8_STAGE(PG8_SA(1, 1), a1 + hstepA, voffA);
;             PG8_WAIT_V(8); PG8_WAIT_L(0); PG8_BAR; PG8_MMA(0, 0, At, B0); PG8_MMA(0, 1, At, B1); PG8_BAR; PG8_SCHED;
;             PG8_LDA(At, 0, 1); PG8_STAGE(PG8_SB(0, 0), b2, voffB); PG8_STAGE(PG8_SB(0, 1), b2 + hstepB, voffB); PG8_STAGE(PG8_SA(0, 0), a2, voffA);
.LBB0_580:
	s_add_i32 s42, s42, 2
	s_add_u32 s4, s14, s18
	s_addc_u32 s5, s15, s19
	s_add_u32 s4, s4, 0x100
	s_addc_u32 s5, s5, 0
	s_add_u32 s43, s38, s18
	s_addc_u32 s44, s39, s19
	s_add_i32 s45, 0, 0x10000
	s_cmpk_eq_i32 s18, 0xf00
	s_cselect_b32 s21, s1, s5
	s_cselect_b32 s20, s0, s4
	v_add_u32_e32 v1, s45, v168
	s_cselect_b32 s5, s13, s44
	s_cselect_b32 s4, s12, s43
	s_add_i32 s43, 0, 0x14000
	ds_read_b128 v[174:177], v1
	ds_read_b128 v[178:181], v1 offset:1024
	ds_read_b128 v[184:187], v1 offset:2048
	ds_read_b128 v[188:191], v1 offset:3072
	v_add_u32_e32 v1, s43, v168
	ds_read_b128 v[192:195], v1
	ds_read_b128 v[196:199], v1 offset:1024
	ds_read_b128 v[200:203], v1 offset:2048
	ds_read_b128 v[204:207], v1 offset:3072
	v_lshl_add_u64 v[2:3], v[164:165], 0, s[18:19]
	s_add_i32 m0, s25, 0xc000
	ds_read_b128 v[208:211], v170
	ds_read_b128 v[212:215], v170 offset:1024
	ds_read_b128 v[216:219], v170 offset:2048
	ds_read_b128 v[220:223], v170 offset:3072
	ds_read_b128 v[224:227], v170 offset:4096
	ds_read_b128 v[228:231], v170 offset:5120
	ds_read_b128 v[232:235], v170 offset:6144
	ds_read_b128 v[236:239], v170 offset:7168
	global_load_lds_dwordx4 v[2:3], off
	s_add_i32 m0, s25, 0xe000
	v_lshl_add_u64 v[2:3], v[166:167], 0, s[18:19]
	global_load_lds_dwordx4 v[2:3], off
	s_waitcnt vmcnt(8)
	s_waitcnt lgkmcnt(0)
	s_barrier
	v_mfma_f32_16x16x32_bf16 v[128:131], v[174:177], v[208:211], v[128:131]
	v_mfma_f32_16x16x32_bf16 v[124:127], v[184:187], v[208:211], v[124:127]
	v_mfma_f32_16x16x32_bf16 v[112:115], v[174:177], v[216:219], v[112:115]
	v_mfma_f32_16x16x32_bf16 v[108:111], v[184:187], v[216:219], v[108:111]
	v_mfma_f32_16x16x32_bf16 v[96:99], v[174:177], v[224:227], v[96:99]
	v_mfma_f32_16x16x32_bf16 v[92:95], v[184:187], v[224:227], v[92:95]
	v_mfma_f32_16x16x32_bf16 v[80:83], v[174:177], v[232:235], v[80:83]
	v_mfma_f32_16x16x32_bf16 v[76:79], v[184:187], v[232:235], v[76:79]
	v_mfma_f32_16x16x32_bf16 v[128:131], v[178:181], v[212:215], v[128:131]
	v_mfma_f32_16x16x32_bf16 v[124:127], v[188:191], v[212:215], v[124:127]
	v_mfma_f32_16x16x32_bf16 v[112:115], v[178:181], v[220:223], v[112:115]
	v_mfma_f32_16x16x32_bf16 v[108:111], v[188:191], v[220:223], v[108:111]
	v_mfma_f32_16x16x32_bf16 v[96:99], v[178:181], v[228:231], v[96:99]
	v_mfma_f32_16x16x32_bf16 v[92:95], v[188:191], v[228:231], v[92:95]
	v_mfma_f32_16x16x32_bf16 v[80:83], v[178:181], v[236:239], v[80:83]
	v_mfma_f32_16x16x32_bf16 v[76:79], v[188:191], v[236:239], v[76:79]
	v_mfma_f32_16x16x32_bf16 v[120:123], v[192:195], v[208:211], v[120:123]
	v_mfma_f32_16x16x32_bf16 v[116:119], v[200:203], v[208:211], v[116:119]
	v_mfma_f32_16x16x32_bf16 v[104:107], v[192:195], v[216:219], v[104:107]
	v_mfma_f32_16x16x32_bf16 v[100:103], v[200:203], v[216:219], v[100:103]
	v_mfma_f32_16x16x32_bf16 v[88:91], v[192:195], v[224:227], v[88:91]
	v_mfma_f32_16x16x32_bf16 v[84:87], v[200:203], v[224:227], v[84:87]
	v_mfma_f32_16x16x32_bf16 v[72:75], v[192:195], v[232:235], v[72:75]
	v_mfma_f32_16x16x32_bf16 v[68:71], v[200:203], v[232:235], v[68:71]
	v_mfma_f32_16x16x32_bf16 v[120:123], v[196:199], v[212:215], v[120:123]
	v_mfma_f32_16x16x32_bf16 v[116:119], v[204:207], v[212:215], v[116:119]
	v_mfma_f32_16x16x32_bf16 v[104:107], v[196:199], v[220:223], v[104:107]
	v_mfma_f32_16x16x32_bf16 v[100:103], v[204:207], v[220:223], v[100:103]
	v_mfma_f32_16x16x32_bf16 v[88:91], v[196:199], v[228:231], v[88:91]
	v_mfma_f32_16x16x32_bf16 v[84:87], v[204:207], v[228:231], v[84:87]
	v_mfma_f32_16x16x32_bf16 v[72:75], v[196:199], v[236:239], v[72:75]
	v_mfma_f32_16x16x32_bf16 v[68:71], v[204:207], v[236:239], v[68:71]
	s_barrier
	s_add_i32 s44, s45, s24
	v_lshl_add_u64 v[240:241], s[4:5], 0, v[134:135]
	s_mov_b32 m0, s44
	ds_read_b128 v[208:211], v170 offset:16384
	ds_read_b128 v[212:215], v170 offset:17408
	ds_read_b128 v[216:219], v170 offset:18432
	ds_read_b128 v[220:223], v170 offset:19456
	ds_read_b128 v[224:227], v170 offset:20480
	ds_read_b128 v[228:231], v170 offset:21504
	ds_read_b128 v[232:235], v170 offset:22528
	ds_read_b128 v[236:239], v170 offset:23552
	global_load_lds_dwordx4 v[240:241], off
	s_add_i32 m0, s44, 0x2000
	s_add_u32 s44, s4, 0x84000
	v_lshl_add_u64 v[242:243], s[4:5], 0, v[158:159]
	s_addc_u32 s45, s5, 0
	s_add_i32 s43, s43, s24
	global_load_lds_dwordx4 v[242:243], off
	v_lshl_add_u64 v[2:3], s[44:45], 0, v[134:135]
	s_mov_b32 m0, s43
	global_load_lds_dwordx4 v[2:3], off
	v_lshl_add_u64 v[2:3], s[44:45], 0, v[158:159]
	s_add_i32 m0, s43, 0x2000
	global_load_lds_dwordx4 v[2:3], off
	s_mov_b32 m0, s25
	v_lshl_add_u64 v[244:245], s[20:21], 0, v[132:133]
	global_load_lds_dwordx4 v[244:245], off
	s_mov_b32 m0, s26
	v_lshl_add_u64 v[246:247], s[20:21], 0, v[156:157]
	global_load_lds_dwordx4 v[246:247], off
	s_waitcnt vmcnt(8)
	s_waitcnt lgkmcnt(0)
	s_barrier
; #define PG8_STAGE(bufoff, gbase, voff) do { _Pragma("unroll") for (int _i = 0; _i < 2; ++_i) \
;         __builtin_amdgcn_global_load_lds((const unsigned*)((const char*)(gbase) + (voff)[_i]), (LAS unsigned*)(lds + (bufoff) + ldsw + _i * 8192), 16, 0, 0); } while (0)
; #define PG8_LDA(dst, b, h) do { _Pragma("unroll") for (int m = 0; m < 4; ++m) _Pragma("unroll") for (int k = 0; k < 2; ++k) dst[m][k] = *(const LAS bf16x8*)(lds + PG8_SA(b, h) + aoff + m * 2048 + k * 1024); } while (0)
; #define PG8_LDB(dst, b, h) do { _Pragma("unroll") for (int n = 0; n < 2; ++n) _Pragma("unroll") for (int k = 0; k < 2; ++k) dst[n][k] = *(const LAS bf16x8*)(lds + PG8_SB(b, h) + boff + n * 2048 + k * 1024); } while (0)
; #define PG8_MMA(ai, bj, At, Bt) do { __builtin_amdgcn_s_setprio(1); _Pragma("unroll") for (int m = 0; m < 4; ++m) _Pragma("unroll") for (int n = 0; n < 2; ++n) _Pragma("unroll") for (int k = 0; k < 2; ++k) \
;         acc[ai][bj][m][n] = __builtin_amdgcn_mfma_f32_16x16x32_bf16(Bt[n][k], At[m][k], acc[ai][bj][m][n], 0, 0, 0); __builtin_amdgcn_s_setprio(0); } while (0)
; #define PG8_WAIT_V(n) asm volatile("s_waitcnt vmcnt(" #n ")" ::: "memory")
; #define PG8_WAIT_L(n) asm volatile("s_waitcnt lgkmcnt(" #n ")" ::: "memory")
; #define PG8_BAR __builtin_amdgcn_s_barrier()
; #define PG8_SCHED __builtin_amdgcn_sched_barrier(0)
; template <class Epi, bool ALIGN_EPI = PG8_ALIGN, bool SP2 = PG8_SP2>
; __device__ __forceinline__ void gemm_phase(LAS uchar* lds, const Gemm g, const StaticOrder& S, const Epi& E) {
;     ...
;             PG8_WAIT_V(8); PG8_WAIT_L(0); PG8_BAR; PG8_MMA(1, 0, At, B0); PG8_MMA(1, 1, At, B1); PG8_BAR; PG8_SCHED;
;             PG8_LDB(B0, 1, 0); PG8_LDB(B1, 1, 1); PG8_SCHED; PG8_LDA(At, 1, 0); PG8_STAGE(PG8_SA(0, 1), a2 + hstepA, voffA);
;             PG8_WAIT_V(8); PG8_WAIT_L(0); PG8_BAR; PG8_MMA(0, 0, At, B0); PG8_MMA(0, 1, At, B1); PG8_BAR; PG8_SCHED;
	v_mfma_f32_16x16x32_bf16 v[64:67], v[174:177], v[208:211], v[64:67]
	v_mfma_f32_16x16x32_bf16 v[60:63], v[184:187], v[208:211], v[60:63]
	v_mfma_f32_16x16x32_bf16 v[48:51], v[174:177], v[216:219], v[48:51]
	v_mfma_f32_16x16x32_bf16 v[44:47], v[184:187], v[216:219], v[44:47]
	v_mfma_f32_16x16x32_bf16 v[32:35], v[174:177], v[224:227], v[32:35]
	v_mfma_f32_16x16x32_bf16 v[28:31], v[184:187], v[224:227], v[28:31]
	v_mfma_f32_16x16x32_bf16 v[16:19], v[174:177], v[232:235], v[16:19]
	v_mfma_f32_16x16x32_bf16 v[12:15], v[184:187], v[232:235], v[12:15]
	v_mfma_f32_16x16x32_bf16 v[64:67], v[178:181], v[212:215], v[64:67]
	v_mfma_f32_16x16x32_bf16 v[60:63], v[188:191], v[212:215], v[60:63]
	v_mfma_f32_16x16x32_bf16 v[48:51], v[178:181], v[220:223], v[48:51]
	v_mfma_f32_16x16x32_bf16 v[44:47], v[188:191], v[220:223], v[44:47]
	v_mfma_f32_16x16x32_bf16 v[32:35], v[178:181], v[228:231], v[32:35]
	v_mfma_f32_16x16x32_bf16 v[28:31], v[188:191], v[228:231], v[28:31]
	v_mfma_f32_16x16x32_bf16 v[16:19], v[178:181], v[236:239], v[16:19]
	v_mfma_f32_16x16x32_bf16 v[12:15], v[188:191], v[236:239], v[12:15]
	v_mfma_f32_16x16x32_bf16 v[56:59], v[192:195], v[208:211], v[56:59]
	v_mfma_f32_16x16x32_bf16 v[52:55], v[200:203], v[208:211], v[52:55]
	v_mfma_f32_16x16x32_bf16 v[40:43], v[192:195], v[216:219], v[40:43]
	v_mfma_f32_16x16x32_bf16 v[36:39], v[200:203], v[216:219], v[36:39]
	v_mfma_f32_16x16x32_bf16 v[24:27], v[192:195], v[224:227], v[24:27]
	v_mfma_f32_16x16x32_bf16 v[20:23], v[200:203], v[224:227], v[20:23]
	v_mfma_f32_16x16x32_bf16 v[8:11], v[192:195], v[232:235], v[8:11]
	v_mfma_f32_16x16x32_bf16 v[2:5], v[200:203], v[232:235], v[4:7]
	v_mfma_f32_16x16x32_bf16 v[56:59], v[196:199], v[212:215], v[56:59]
	v_mfma_f32_16x16x32_bf16 v[52:55], v[204:207], v[212:215], v[52:55]
	v_mfma_f32_16x16x32_bf16 v[40:43], v[196:199], v[220:223], v[40:43]
	v_mfma_f32_16x16x32_bf16 v[36:39], v[204:207], v[220:223], v[36:39]
	v_mfma_f32_16x16x32_bf16 v[24:27], v[196:199], v[228:231], v[24:27]
	v_mfma_f32_16x16x32_bf16 v[20:23], v[204:207], v[228:231], v[20:23]
	v_mfma_f32_16x16x32_bf16 v[8:11], v[196:199], v[236:239], v[8:11]
	v_mfma_f32_16x16x32_bf16 v[2:5], v[204:207], v[236:239], v[2:5]
	s_barrier
	s_add_i32 s43, 0, 0x18000
	v_add_u32_e32 v1, s43, v168
	s_add_i32 s44, 0, 0x1c000
	ds_read_b128 v[174:177], v1
	ds_read_b128 v[178:181], v1 offset:1024
	ds_read_b128 v[184:187], v1 offset:2048
	ds_read_b128 v[188:191], v1 offset:3072
	v_add_u32_e32 v1, s44, v168
	ds_read_b128 v[192:195], v1
	ds_read_b128 v[196:199], v1 offset:1024
	ds_read_b128 v[200:203], v1 offset:2048
	ds_read_b128 v[204:207], v1 offset:3072
	s_add_u32 s20, s20, 0x184000
	s_addc_u32 s21, s21, 0
	s_mov_b32 m0, s27
	v_lshl_add_u64 v[6:7], s[20:21], 0, v[132:133]
	ds_read_b128 v[208:211], v170 offset:32768
	ds_read_b128 v[212:215], v170 offset:33792
	ds_read_b128 v[216:219], v170 offset:34816
	ds_read_b128 v[220:223], v170 offset:35840
	ds_read_b128 v[224:227], v170 offset:36864
	ds_read_b128 v[228:231], v170 offset:37888
	ds_read_b128 v[232:235], v170 offset:38912
	ds_read_b128 v[236:239], v170 offset:39936
	global_load_lds_dwordx4 v[6:7], off
	s_mov_b32 m0, s28
	v_lshl_add_u64 v[6:7], s[20:21], 0, v[156:157]
	global_load_lds_dwordx4 v[6:7], off
	s_waitcnt vmcnt(8)
	s_waitcnt lgkmcnt(0)
	s_barrier
	v_mfma_f32_16x16x32_bf16 v[128:131], v[174:177], v[208:211], v[128:131]
	v_mfma_f32_16x16x32_bf16 v[124:127], v[184:187], v[208:211], v[124:127]
	v_mfma_f32_16x16x32_bf16 v[112:115], v[174:177], v[216:219], v[112:115]
	v_mfma_f32_16x16x32_bf16 v[108:111], v[184:187], v[216:219], v[108:111]
	v_mfma_f32_16x16x32_bf16 v[96:99], v[174:177], v[224:227], v[96:99]
	v_mfma_f32_16x16x32_bf16 v[92:95], v[184:187], v[224:227], v[92:95]
	v_mfma_f32_16x16x32_bf16 v[80:83], v[174:177], v[232:235], v[80:83]
	v_mfma_f32_16x16x32_bf16 v[76:79], v[184:187], v[232:235], v[76:79]
	v_mfma_f32_16x16x32_bf16 v[128:131], v[178:181], v[212:215], v[128:131]
	v_mfma_f32_16x16x32_bf16 v[124:127], v[188:191], v[212:215], v[124:127]
	v_mfma_f32_16x16x32_bf16 v[112:115], v[178:181], v[220:223], v[112:115]
	v_mfma_f32_16x16x32_bf16 v[108:111], v[188:191], v[220:223], v[108:111]
	v_mfma_f32_16x16x32_bf16 v[96:99], v[178:181], v[228:231], v[96:99]
	v_mfma_f32_16x16x32_bf16 v[92:95], v[188:191], v[228:231], v[92:95]
	v_mfma_f32_16x16x32_bf16 v[80:83], v[178:181], v[236:239], v[80:83]
	v_mfma_f32_16x16x32_bf16 v[76:79], v[188:191], v[236:239], v[76:79]
	v_mfma_f32_16x16x32_bf16 v[120:123], v[192:195], v[208:211], v[120:123]
	v_mfma_f32_16x16x32_bf16 v[116:119], v[200:203], v[208:211], v[116:119]
	v_mfma_f32_16x16x32_bf16 v[104:107], v[192:195], v[216:219], v[104:107]
	v_mfma_f32_16x16x32_bf16 v[100:103], v[200:203], v[216:219], v[100:103]
	v_mfma_f32_16x16x32_bf16 v[88:91], v[192:195], v[224:227], v[88:91]
	v_mfma_f32_16x16x32_bf16 v[84:87], v[200:203], v[224:227], v[84:87]
	v_mfma_f32_16x16x32_bf16 v[72:75], v[192:195], v[232:235], v[72:75]
	v_mfma_f32_16x16x32_bf16 v[68:71], v[200:203], v[232:235], v[68:71]
	v_mfma_f32_16x16x32_bf16 v[120:123], v[196:199], v[212:215], v[120:123]
	v_mfma_f32_16x16x32_bf16 v[116:119], v[204:207], v[212:215], v[116:119]
	v_mfma_f32_16x16x32_bf16 v[104:107], v[196:199], v[220:223], v[104:107]
	v_mfma_f32_16x16x32_bf16 v[100:103], v[204:207], v[220:223], v[100:103]
	v_mfma_f32_16x16x32_bf16 v[88:91], v[196:199], v[228:231], v[88:91]
	v_mfma_f32_16x16x32_bf16 v[84:87], v[204:207], v[228:231], v[84:87]
	v_mfma_f32_16x16x32_bf16 v[72:75], v[196:199], v[236:239], v[72:75]
	v_mfma_f32_16x16x32_bf16 v[68:71], v[204:207], v[236:239], v[68:71]
	s_barrier
; #define LAS __attribute__((address_space(3)))
; #define PG8_STAGE(bufoff, gbase, voff) do { _Pragma("unroll") for (int _i = 0; _i < 2; ++_i) \
;         __builtin_amdgcn_global_load_lds((const unsigned*)((const char*)(gbase) + (voff)[_i]), (LAS unsigned*)(lds + (bufoff) + ldsw + _i * 8192), 16, 0, 0); } while (0)
; #define PG8_LDA(dst, b, h) do { _Pragma("unroll") for (int m = 0; m < 4; ++m) _Pragma("unroll") for (int k = 0; k < 2; ++k) dst[m][k] = *(const LAS bf16x8*)(lds + PG8_SA(b, h) + aoff + m * 2048 + k * 1024); } while (0)
; #define PG8_MMA(ai, bj, At, Bt) do { __builtin_amdgcn_s_setprio(1); _Pragma("unroll") for (int m = 0; m < 4; ++m) _Pragma("unroll") for (int n = 0; n < 2; ++n) _Pragma("unroll") for (int k = 0; k < 2; ++k) \
;         acc[ai][bj][m][n] = __builtin_amdgcn_mfma_f32_16x16x32_bf16(Bt[n][k], At[m][k], acc[ai][bj][m][n], 0, 0, 0); __builtin_amdgcn_s_setprio(0); } while (0)
; #define PG8_WAIT_V(n) asm volatile("s_waitcnt vmcnt(" #n ")" ::: "memory")
; #define PG8_WAIT_L(n) asm volatile("s_waitcnt lgkmcnt(" #n ")" ::: "memory")
; #define PG8_BAR __builtin_amdgcn_s_barrier()
; #define PG8_SCHED __builtin_amdgcn_sched_barrier(0)
; template <class Epi, bool ALIGN_EPI = PG8_ALIGN, bool SP2 = PG8_SP2>
; __device__ __forceinline__ void gemm_phase(LAS uchar* lds, const Gemm g, const StaticOrder& S, const Epi& E) {
;     ...
;         for (int tb = 0; tb < nt; tb += tblk) {
;         if constexpr (Epi::GROUPS) { if (tb > 0) {
;             const LAS float* rt = (const LAS float*)(lds + LDS_RT) + ((ui & 1) * 256 + wr * 64 + fr) * 8 + ((tb >> 2) - 1);
;     ...
;             PG8_LDA(At, 1, 1); PG8_STAGE(PG8_SB(1, 0), b3, voffB); PG8_STAGE(PG8_SB(1, 1), b3 + hstepB, voffB); PG8_STAGE(PG8_SA(1, 0), a3, voffA);
;             PG8_WAIT_V(8); PG8_WAIT_L(0); PG8_BAR; PG8_MMA(1, 0, At, B0); PG8_MMA(1, 1, At, B1); PG8_BAR; PG8_SCHED;
	s_add_i32 s20, s43, s24
	v_lshl_add_u64 v[6:7], v[240:241], 0, s[84:85]
	s_mov_b32 m0, s20
	ds_read_b128 v[208:211], v170 offset:49152
	ds_read_b128 v[212:215], v170 offset:50176
	ds_read_b128 v[216:219], v170 offset:51200
	ds_read_b128 v[220:223], v170 offset:52224
	ds_read_b128 v[224:227], v170 offset:53248
	ds_read_b128 v[228:231], v170 offset:54272
	ds_read_b128 v[232:235], v170 offset:55296
	ds_read_b128 v[236:239], v170 offset:56320
	global_load_lds_dwordx4 v[6:7], off
	s_add_i32 m0, s20, 0x2000
	s_add_u32 s4, s4, 0x84080
	v_lshl_add_u64 v[6:7], v[242:243], 0, s[84:85]
	s_addc_u32 s5, s5, 0
	s_add_i32 s20, s44, s24
	global_load_lds_dwordx4 v[6:7], off
	s_mov_b32 m0, s20
	v_lshl_add_u64 v[6:7], s[4:5], 0, v[134:135]
	global_load_lds_dwordx4 v[6:7], off
	s_add_i32 m0, s20, 0x2000
	v_lshl_add_u64 v[6:7], s[4:5], 0, v[158:159]
	global_load_lds_dwordx4 v[6:7], off
	s_mov_b32 m0, s29
	v_lshl_add_u64 v[6:7], v[244:245], 0, s[84:85]
	global_load_lds_dwordx4 v[6:7], off
	s_mov_b32 m0, s30
	v_lshl_add_u64 v[6:7], v[246:247], 0, s[84:85]
	global_load_lds_dwordx4 v[6:7], off
	s_waitcnt vmcnt(8)
	s_waitcnt lgkmcnt(0)
	s_barrier
	v_mfma_f32_16x16x32_bf16 v[64:67], v[174:177], v[208:211], v[64:67]
	v_mfma_f32_16x16x32_bf16 v[60:63], v[184:187], v[208:211], v[60:63]
	v_mfma_f32_16x16x32_bf16 v[48:51], v[174:177], v[216:219], v[48:51]
	v_mfma_f32_16x16x32_bf16 v[44:47], v[184:187], v[216:219], v[44:47]
	v_mfma_f32_16x16x32_bf16 v[32:35], v[174:177], v[224:227], v[32:35]
	v_mfma_f32_16x16x32_bf16 v[28:31], v[184:187], v[224:227], v[28:31]
	v_mfma_f32_16x16x32_bf16 v[16:19], v[174:177], v[232:235], v[16:19]
	v_mfma_f32_16x16x32_bf16 v[12:15], v[184:187], v[232:235], v[12:15]
	v_mfma_f32_16x16x32_bf16 v[64:67], v[178:181], v[212:215], v[64:67]
	v_mfma_f32_16x16x32_bf16 v[60:63], v[188:191], v[212:215], v[60:63]
	v_mfma_f32_16x16x32_bf16 v[48:51], v[178:181], v[220:223], v[48:51]
	v_mfma_f32_16x16x32_bf16 v[44:47], v[188:191], v[220:223], v[44:47]
	v_mfma_f32_16x16x32_bf16 v[32:35], v[178:181], v[228:231], v[32:35]
	v_mfma_f32_16x16x32_bf16 v[28:31], v[188:191], v[228:231], v[28:31]
	v_mfma_f32_16x16x32_bf16 v[16:19], v[178:181], v[236:239], v[16:19]
	v_mfma_f32_16x16x32_bf16 v[12:15], v[188:191], v[236:239], v[12:15]
	v_mfma_f32_16x16x32_bf16 v[56:59], v[192:195], v[208:211], v[56:59]
	v_mfma_f32_16x16x32_bf16 v[52:55], v[200:203], v[208:211], v[52:55]
	v_mfma_f32_16x16x32_bf16 v[40:43], v[192:195], v[216:219], v[40:43]
	v_mfma_f32_16x16x32_bf16 v[36:39], v[200:203], v[216:219], v[36:39]
	v_mfma_f32_16x16x32_bf16 v[24:27], v[192:195], v[224:227], v[24:27]
	v_mfma_f32_16x16x32_bf16 v[20:23], v[200:203], v[224:227], v[20:23]
	v_mfma_f32_16x16x32_bf16 v[6:9], v[192:195], v[232:235], v[8:11]
	v_mfma_f32_16x16x32_bf16 v[2:5], v[200:203], v[232:235], v[2:5]
	v_mfma_f32_16x16x32_bf16 v[56:59], v[196:199], v[212:215], v[56:59]
	v_mfma_f32_16x16x32_bf16 v[52:55], v[204:207], v[212:215], v[52:55]
	v_mfma_f32_16x16x32_bf16 v[40:43], v[196:199], v[220:223], v[40:43]
	v_mfma_f32_16x16x32_bf16 v[36:39], v[204:207], v[220:223], v[36:39]
	v_mfma_f32_16x16x32_bf16 v[24:27], v[196:199], v[228:231], v[24:27]
	v_mfma_f32_16x16x32_bf16 v[20:23], v[204:207], v[228:231], v[20:23]
	v_mfma_f32_16x16x32_bf16 v[8:11], v[196:199], v[236:239], v[6:9]
	v_mfma_f32_16x16x32_bf16 v[4:7], v[204:207], v[236:239], v[2:5]
	s_barrier
	s_add_u32 s18, s18, 0x100
	s_addc_u32 s19, s19, 0
	s_cmp_ge_u32 s42, s41
	s_cbranch_scc0 .LBB0_580
	s_add_u32 s16, s16, 0x200
	s_addc_u32 s17, s17, 0
	s_cmp_lt_u32 s40, 28
	s_cbranch_scc0 .LBB0_583
	s_mov_b32 s40, s41
	s_cmp_eq_u32 s40, 0
	s_cbranch_scc0 .LBB0_578
	s_branch .LBB0_579

; #define PG8_STAGE(bufoff, gbase, voff) do { _Pragma("unroll") for (int _i = 0; _i < 2; ++_i) \
;         __builtin_amdgcn_global_load_lds((const unsigned*)((const char*)(gbase) + (voff)[_i]), (LAS unsigned*)(lds + (bufoff) + ldsw + _i * 8192), 16, 0, 0); } while (0)
; #define PG8_LDA(dst, b, h) do { _Pragma("unroll") for (int m = 0; m < 4; ++m) _Pragma("unroll") for (int k = 0; k < 2; ++k) dst[m][k] = *(const LAS bf16x8*)(lds + PG8_SA(b, h) + aoff + m * 2048 + k * 1024); } while (0)
; #define PG8_LDB(dst, b, h) do { _Pragma("unroll") for (int n = 0; n < 2; ++n) _Pragma("unroll") for (int k = 0; k < 2; ++k) dst[n][k] = *(const LAS bf16x8*)(lds + PG8_SB(b, h) + boff + n * 2048 + k * 1024); } while (0)
; #define PG8_MMA(ai, bj, At, Bt) do { __builtin_amdgcn_s_setprio(1); _Pragma("unroll") for (int m = 0; m < 4; ++m) _Pragma("unroll") for (int n = 0; n < 2; ++n) _Pragma("unroll") for (int k = 0; k < 2; ++k) \
;         acc[ai][bj][m][n] = __builtin_amdgcn_mfma_f32_16x16x32_bf16(Bt[n][k], At[m][k], acc[ai][bj][m][n], 0, 0, 0); __builtin_amdgcn_s_setprio(0); } while (0)
; #define PG8_WAIT_V(n) asm volatile("s_waitcnt vmcnt(" #n ")" ::: "memory")
; #define PG8_WAIT_L(n) asm volatile("s_waitcnt lgkmcnt(" #n ")" ::: "memory")
; #define PG8_BAR __builtin_amdgcn_s_barrier()
; #define PG8_SCHED __builtin_amdgcn_sched_barrier(0)
; template <class Epi, bool ALIGN_EPI = PG8_ALIGN, bool SP2 = PG8_SP2>
; __device__ __forceinline__ void gemm_phase(LAS uchar* lds, const Gemm g, const StaticOrder& S, const Epi& E) {
;     ...
;             const bool last = (t == nt - 2);
;             const char* a1 = cA + (size_t)(t + 1) * kstep;
;             const char* a2 = last ? nA : cA + (size_t)(t + 2) * kstep; const char* b2 = last ? nB : cB + (size_t)(t + 2) * kstep;
;             const char* a3 = a2 + kstep; const char* b3 = b2 + kstep;
;             if constexpr (SP2) {
;             PG8_LDB(B0, 0, 0); PG8_LDB(B1, 0, 1); PG8_SCHED; PG8_LDA(At, 0, 0); PG8_STAGE(PG8_SA(1, 1), a1 + hstepA, voffA);
;             PG8_WAIT_V(8); PG8_WAIT_L(0); PG8_BAR; PG8_MMA(0, 0, At, B0); PG8_MMA(0, 1, At, B1); PG8_BAR; PG8_SCHED;
;             PG8_LDA(At, 0, 1); PG8_STAGE(PG8_SB(0, 0), b2, voffB); PG8_STAGE(PG8_SB(0, 1), b2 + hstepB, voffB); PG8_STAGE(PG8_SA(0, 0), a2, voffA);
.LBB0_668:
	s_add_u32 s36, s14, 0x100
	s_addc_u32 s37, s15, 0
	s_mov_b32 s38, -2
	s_add_u32 s14, s12, 0x100
	s_addc_u32 s15, s13, 0
	s_add_i32 s39, 0, 0x10000
	s_cmp_eq_u32 s38, 12
	s_cselect_b32 s19, s5, s15
	s_cselect_b32 s18, s4, s14
	s_cselect_b32 s17, s11, s37
	s_cselect_b32 s16, s10, s36
	s_add_i32 s40, 0, 0x14000
	v_add_u32_e32 v174, s39, v139
	v_add_u32_e32 v192, s40, v139
	ds_read_b128 v[160:163], v174
	ds_read_b128 v[164:167], v174 offset:1024
	ds_read_b128 v[168:171], v174 offset:2048
	ds_read_b128 v[174:177], v174 offset:3072
	ds_read_b128 v[178:181], v192
	ds_read_b128 v[184:187], v192 offset:1024
	ds_read_b128 v[188:191], v192 offset:2048
	ds_read_b128 v[192:195], v192 offset:3072
	v_lshl_add_u64 v[228:229], s[12:13], 0, v[156:157]
	s_add_i32 m0, s23, 0xc000
	ds_read_b128 v[196:199], v173
	ds_read_b128 v[200:203], v173 offset:1024
	ds_read_b128 v[204:207], v173 offset:2048
	ds_read_b128 v[208:211], v173 offset:3072
	ds_read_b128 v[212:215], v173 offset:4096
	ds_read_b128 v[216:219], v173 offset:5120
	ds_read_b128 v[220:223], v173 offset:6144
	ds_read_b128 v[224:227], v173 offset:7168
	global_load_lds_dwordx4 v[228:229], off
	s_add_i32 m0, s23, 0xe000
	v_lshl_add_u64 v[228:229], s[12:13], 0, v[158:159]
	global_load_lds_dwordx4 v[228:229], off
	s_waitcnt vmcnt(8)
	s_waitcnt lgkmcnt(0)
	s_barrier
	v_mfma_f32_16x16x32_bf16 v[126:129], v[160:163], v[196:199], 0
	v_mfma_f32_16x16x32_bf16 v[122:125], v[168:171], v[196:199], 0
	v_mfma_f32_16x16x32_bf16 v[118:121], v[160:163], v[204:207], 0
	v_mfma_f32_16x16x32_bf16 v[110:113], v[168:171], v[204:207], 0
	v_mfma_f32_16x16x32_bf16 v[102:105], v[160:163], v[212:215], 0
	v_mfma_f32_16x16x32_bf16 v[94:97], v[168:171], v[212:215], 0
	v_mfma_f32_16x16x32_bf16 v[86:89], v[160:163], v[220:223], 0
	v_mfma_f32_16x16x32_bf16 v[78:81], v[168:171], v[220:223], 0
	v_mfma_f32_16x16x32_bf16 v[126:129], v[164:167], v[200:203], v[126:129]
	v_mfma_f32_16x16x32_bf16 v[122:125], v[174:177], v[200:203], v[122:125]
	v_mfma_f32_16x16x32_bf16 v[118:121], v[164:167], v[208:211], v[118:121]
	v_mfma_f32_16x16x32_bf16 v[110:113], v[174:177], v[208:211], v[110:113]
	v_mfma_f32_16x16x32_bf16 v[102:105], v[164:167], v[216:219], v[102:105]
	v_mfma_f32_16x16x32_bf16 v[94:97], v[174:177], v[216:219], v[94:97]
	v_mfma_f32_16x16x32_bf16 v[86:89], v[164:167], v[224:227], v[86:89]
	v_mfma_f32_16x16x32_bf16 v[78:81], v[174:177], v[224:227], v[78:81]
	v_mfma_f32_16x16x32_bf16 v[114:117], v[178:181], v[196:199], 0
	v_mfma_f32_16x16x32_bf16 v[106:109], v[188:191], v[196:199], 0
	v_mfma_f32_16x16x32_bf16 v[98:101], v[178:181], v[204:207], 0
	v_mfma_f32_16x16x32_bf16 v[90:93], v[188:191], v[204:207], 0
	v_mfma_f32_16x16x32_bf16 v[82:85], v[178:181], v[212:215], 0
	v_mfma_f32_16x16x32_bf16 v[74:77], v[188:191], v[212:215], 0
	v_mfma_f32_16x16x32_bf16 v[70:73], v[178:181], v[220:223], 0
	v_mfma_f32_16x16x32_bf16 v[66:69], v[188:191], v[220:223], 0
	v_mfma_f32_16x16x32_bf16 v[114:117], v[184:187], v[200:203], v[114:117]
	v_mfma_f32_16x16x32_bf16 v[106:109], v[192:195], v[200:203], v[106:109]
	v_mfma_f32_16x16x32_bf16 v[98:101], v[184:187], v[208:211], v[98:101]
	v_mfma_f32_16x16x32_bf16 v[90:93], v[192:195], v[208:211], v[90:93]
	v_mfma_f32_16x16x32_bf16 v[82:85], v[184:187], v[216:219], v[82:85]
	v_mfma_f32_16x16x32_bf16 v[74:77], v[192:195], v[216:219], v[74:77]
	v_mfma_f32_16x16x32_bf16 v[70:73], v[184:187], v[224:227], v[70:73]
	v_mfma_f32_16x16x32_bf16 v[66:69], v[192:195], v[224:227], v[66:69]
	s_barrier
	s_add_i32 s12, s39, s21
	v_lshl_add_u64 v[228:229], s[16:17], 0, v[134:135]
	s_mov_b32 m0, s12
	ds_read_b128 v[196:199], v173 offset:16384
	ds_read_b128 v[200:203], v173 offset:17408
	ds_read_b128 v[204:207], v173 offset:18432
	ds_read_b128 v[208:211], v173 offset:19456
	ds_read_b128 v[212:215], v173 offset:20480
	ds_read_b128 v[216:219], v173 offset:21504
	ds_read_b128 v[220:223], v173 offset:22528
	ds_read_b128 v[224:227], v173 offset:23552
	global_load_lds_dwordx4 v[228:229], off
	s_add_i32 m0, s12, 0x2000
	s_add_u32 s12, s16, 0x44000
	v_lshl_add_u64 v[230:231], s[16:17], 0, v[130:131]
	s_addc_u32 s13, s17, 0
	s_add_i32 s39, s40, s21
	global_load_lds_dwordx4 v[230:231], off
	v_lshl_add_u64 v[232:233], s[12:13], 0, v[134:135]
	s_mov_b32 m0, s39
	global_load_lds_dwordx4 v[232:233], off
	s_add_i32 m0, s39, 0x2000
	v_lshl_add_u64 v[232:233], s[12:13], 0, v[130:131]
	global_load_lds_dwordx4 v[232:233], off
	s_mov_b32 m0, s23
	v_lshl_add_u64 v[232:233], s[18:19], 0, v[152:153]
	global_load_lds_dwordx4 v[232:233], off
	s_mov_b32 m0, s24
	v_lshl_add_u64 v[234:235], s[18:19], 0, v[132:133]
	global_load_lds_dwordx4 v[234:235], off
	s_waitcnt vmcnt(8)
	s_waitcnt lgkmcnt(0)
	s_barrier
; #define PG8_STAGE(bufoff, gbase, voff) do { _Pragma("unroll") for (int _i = 0; _i < 2; ++_i) \
;         __builtin_amdgcn_global_load_lds((const unsigned*)((const char*)(gbase) + (voff)[_i]), (LAS unsigned*)(lds + (bufoff) + ldsw + _i * 8192), 16, 0, 0); } while (0)
; #define PG8_LDA(dst, b, h) do { _Pragma("unroll") for (int m = 0; m < 4; ++m) _Pragma("unroll") for (int k = 0; k < 2; ++k) dst[m][k] = *(const LAS bf16x8*)(lds + PG8_SA(b, h) + aoff + m * 2048 + k * 1024); } while (0)
; #define PG8_LDB(dst, b, h) do { _Pragma("unroll") for (int n = 0; n < 2; ++n) _Pragma("unroll") for (int k = 0; k < 2; ++k) dst[n][k] = *(const LAS bf16x8*)(lds + PG8_SB(b, h) + boff + n * 2048 + k * 1024); } while (0)
; #define PG8_MMA(ai, bj, At, Bt) do { __builtin_amdgcn_s_setprio(1); _Pragma("unroll") for (int m = 0; m < 4; ++m) _Pragma("unroll") for (int n = 0; n < 2; ++n) _Pragma("unroll") for (int k = 0; k < 2; ++k) \
;         acc[ai][bj][m][n] = __builtin_amdgcn_mfma_f32_16x16x32_bf16(Bt[n][k], At[m][k], acc[ai][bj][m][n], 0, 0, 0); __builtin_amdgcn_s_setprio(0); } while (0)
; #define PG8_WAIT_V(n) asm volatile("s_waitcnt vmcnt(" #n ")" ::: "memory")
; #define PG8_WAIT_L(n) asm volatile("s_waitcnt lgkmcnt(" #n ")" ::: "memory")
; #define PG8_BAR __builtin_amdgcn_s_barrier()
; #define PG8_SCHED __builtin_amdgcn_sched_barrier(0)
; template <class Epi, bool ALIGN_EPI = PG8_ALIGN, bool SP2 = PG8_SP2>
; __device__ __forceinline__ void gemm_phase(LAS uchar* lds, const Gemm g, const StaticOrder& S, const Epi& E) {
;     ...
;             PG8_WAIT_V(8); PG8_WAIT_L(0); PG8_BAR; PG8_MMA(1, 0, At, B0); PG8_MMA(1, 1, At, B1); PG8_BAR; PG8_SCHED;
;             PG8_LDB(B0, 1, 0); PG8_LDB(B1, 1, 1); PG8_SCHED; PG8_LDA(At, 1, 0); PG8_STAGE(PG8_SA(0, 1), a2 + hstepA, voffA);
;             PG8_WAIT_V(8); PG8_WAIT_L(0); PG8_BAR; PG8_MMA(0, 0, At, B0); PG8_MMA(0, 1, At, B1); PG8_BAR; PG8_SCHED;
	v_mfma_f32_16x16x32_bf16 v[62:65], v[160:163], v[196:199], 0
	v_mfma_f32_16x16x32_bf16 v[58:61], v[168:171], v[196:199], 0
	v_mfma_f32_16x16x32_bf16 v[54:57], v[160:163], v[204:207], 0
	v_mfma_f32_16x16x32_bf16 v[46:49], v[168:171], v[204:207], 0
	v_mfma_f32_16x16x32_bf16 v[38:41], v[160:163], v[212:215], 0
	v_mfma_f32_16x16x32_bf16 v[30:33], v[168:171], v[212:215], 0
	v_mfma_f32_16x16x32_bf16 v[22:25], v[160:163], v[220:223], 0
	v_mfma_f32_16x16x32_bf16 v[14:17], v[168:171], v[220:223], 0
	v_mfma_f32_16x16x32_bf16 v[62:65], v[164:167], v[200:203], v[62:65]
	v_mfma_f32_16x16x32_bf16 v[58:61], v[174:177], v[200:203], v[58:61]
	v_mfma_f32_16x16x32_bf16 v[54:57], v[164:167], v[208:211], v[54:57]
	v_mfma_f32_16x16x32_bf16 v[46:49], v[174:177], v[208:211], v[46:49]
	v_mfma_f32_16x16x32_bf16 v[38:41], v[164:167], v[216:219], v[38:41]
	v_mfma_f32_16x16x32_bf16 v[30:33], v[174:177], v[216:219], v[30:33]
	v_mfma_f32_16x16x32_bf16 v[22:25], v[164:167], v[224:227], v[22:25]
	v_mfma_f32_16x16x32_bf16 v[14:17], v[174:177], v[224:227], v[14:17]
	v_mfma_f32_16x16x32_bf16 v[50:53], v[178:181], v[196:199], 0
	v_mfma_f32_16x16x32_bf16 v[42:45], v[188:191], v[196:199], 0
	v_mfma_f32_16x16x32_bf16 v[34:37], v[178:181], v[204:207], 0
	v_mfma_f32_16x16x32_bf16 v[26:29], v[188:191], v[204:207], 0
	v_mfma_f32_16x16x32_bf16 v[18:21], v[178:181], v[212:215], 0
	v_mfma_f32_16x16x32_bf16 v[10:13], v[188:191], v[212:215], 0
	v_mfma_f32_16x16x32_bf16 v[6:9], v[178:181], v[220:223], 0
	v_mfma_f32_16x16x32_bf16 v[2:5], v[188:191], v[220:223], 0
	v_mfma_f32_16x16x32_bf16 v[50:53], v[184:187], v[200:203], v[50:53]
	v_mfma_f32_16x16x32_bf16 v[42:45], v[192:195], v[200:203], v[42:45]
	v_mfma_f32_16x16x32_bf16 v[34:37], v[184:187], v[208:211], v[34:37]
	v_mfma_f32_16x16x32_bf16 v[26:29], v[192:195], v[208:211], v[26:29]
	v_mfma_f32_16x16x32_bf16 v[18:21], v[184:187], v[216:219], v[18:21]
	v_mfma_f32_16x16x32_bf16 v[10:13], v[192:195], v[216:219], v[10:13]
	v_mfma_f32_16x16x32_bf16 v[6:9], v[184:187], v[224:227], v[6:9]
	v_mfma_f32_16x16x32_bf16 v[2:5], v[192:195], v[224:227], v[2:5]
	s_barrier
	s_add_i32 s39, 0, 0x18000
	s_add_i32 s40, 0, 0x1c000
	v_add_u32_e32 v174, s39, v139
	v_add_u32_e32 v192, s40, v139
	ds_read_b128 v[160:163], v174
	ds_read_b128 v[164:167], v174 offset:1024
	ds_read_b128 v[168:171], v174 offset:2048
	ds_read_b128 v[174:177], v174 offset:3072
	ds_read_b128 v[178:181], v192
	ds_read_b128 v[184:187], v192 offset:1024
	ds_read_b128 v[188:191], v192 offset:2048
	ds_read_b128 v[192:195], v192 offset:3072
	s_add_u32 s12, s18, 0x44000
	s_addc_u32 s13, s19, 0
	s_mov_b32 m0, s25
	v_lshl_add_u64 v[236:237], s[12:13], 0, v[152:153]
	ds_read_b128 v[196:199], v173 offset:32768
	ds_read_b128 v[200:203], v173 offset:33792
	ds_read_b128 v[204:207], v173 offset:34816
	ds_read_b128 v[208:211], v173 offset:35840
	ds_read_b128 v[212:215], v173 offset:36864
	ds_read_b128 v[216:219], v173 offset:37888
	ds_read_b128 v[220:223], v173 offset:38912
	ds_read_b128 v[224:227], v173 offset:39936
	global_load_lds_dwordx4 v[236:237], off
	s_mov_b32 m0, s26
	v_lshl_add_u64 v[236:237], s[12:13], 0, v[132:133]
	global_load_lds_dwordx4 v[236:237], off
	s_waitcnt vmcnt(8)
	s_waitcnt lgkmcnt(0)
	s_barrier
	v_mfma_f32_16x16x32_bf16 v[126:129], v[160:163], v[196:199], v[126:129]
	v_mfma_f32_16x16x32_bf16 v[122:125], v[168:171], v[196:199], v[122:125]
	v_mfma_f32_16x16x32_bf16 v[118:121], v[160:163], v[204:207], v[118:121]
	v_mfma_f32_16x16x32_bf16 v[110:113], v[168:171], v[204:207], v[110:113]
	v_mfma_f32_16x16x32_bf16 v[102:105], v[160:163], v[212:215], v[102:105]
	v_mfma_f32_16x16x32_bf16 v[94:97], v[168:171], v[212:215], v[94:97]
	v_mfma_f32_16x16x32_bf16 v[86:89], v[160:163], v[220:223], v[86:89]
	v_mfma_f32_16x16x32_bf16 v[78:81], v[168:171], v[220:223], v[78:81]
	v_mfma_f32_16x16x32_bf16 v[126:129], v[164:167], v[200:203], v[126:129]
	v_mfma_f32_16x16x32_bf16 v[122:125], v[174:177], v[200:203], v[122:125]
	v_mfma_f32_16x16x32_bf16 v[118:121], v[164:167], v[208:211], v[118:121]
	v_mfma_f32_16x16x32_bf16 v[110:113], v[174:177], v[208:211], v[110:113]
	v_mfma_f32_16x16x32_bf16 v[102:105], v[164:167], v[216:219], v[102:105]
	v_mfma_f32_16x16x32_bf16 v[94:97], v[174:177], v[216:219], v[94:97]
	v_mfma_f32_16x16x32_bf16 v[86:89], v[164:167], v[224:227], v[86:89]
	v_mfma_f32_16x16x32_bf16 v[78:81], v[174:177], v[224:227], v[78:81]
	v_mfma_f32_16x16x32_bf16 v[114:117], v[178:181], v[196:199], v[114:117]
	v_mfma_f32_16x16x32_bf16 v[106:109], v[188:191], v[196:199], v[106:109]
	v_mfma_f32_16x16x32_bf16 v[98:101], v[178:181], v[204:207], v[98:101]
	v_mfma_f32_16x16x32_bf16 v[90:93], v[188:191], v[204:207], v[90:93]
	v_mfma_f32_16x16x32_bf16 v[82:85], v[178:181], v[212:215], v[82:85]
	v_mfma_f32_16x16x32_bf16 v[74:77], v[188:191], v[212:215], v[74:77]
	v_mfma_f32_16x16x32_bf16 v[70:73], v[178:181], v[220:223], v[70:73]
	v_mfma_f32_16x16x32_bf16 v[66:69], v[188:191], v[220:223], v[66:69]
	v_mfma_f32_16x16x32_bf16 v[114:117], v[184:187], v[200:203], v[114:117]
	v_mfma_f32_16x16x32_bf16 v[106:109], v[192:195], v[200:203], v[106:109]
	v_mfma_f32_16x16x32_bf16 v[98:101], v[184:187], v[208:211], v[98:101]
	v_mfma_f32_16x16x32_bf16 v[90:93], v[192:195], v[208:211], v[90:93]
	v_mfma_f32_16x16x32_bf16 v[82:85], v[184:187], v[216:219], v[82:85]
	v_mfma_f32_16x16x32_bf16 v[74:77], v[192:195], v[216:219], v[74:77]
	v_mfma_f32_16x16x32_bf16 v[70:73], v[184:187], v[224:227], v[70:73]
	v_mfma_f32_16x16x32_bf16 v[66:69], v[192:195], v[224:227], v[66:69]
	s_barrier
; #define PG8_STAGE(bufoff, gbase, voff) do { _Pragma("unroll") for (int _i = 0; _i < 2; ++_i) \
;         __builtin_amdgcn_global_load_lds((const unsigned*)((const char*)(gbase) + (voff)[_i]), (LAS unsigned*)(lds + (bufoff) + ldsw + _i * 8192), 16, 0, 0); } while (0)
; #define PG8_LDA(dst, b, h) do { _Pragma("unroll") for (int m = 0; m < 4; ++m) _Pragma("unroll") for (int k = 0; k < 2; ++k) dst[m][k] = *(const LAS bf16x8*)(lds + PG8_SA(b, h) + aoff + m * 2048 + k * 1024); } while (0)
; #define PG8_LDB(dst, b, h) do { _Pragma("unroll") for (int n = 0; n < 2; ++n) _Pragma("unroll") for (int k = 0; k < 2; ++k) dst[n][k] = *(const LAS bf16x8*)(lds + PG8_SB(b, h) + boff + n * 2048 + k * 1024); } while (0)
; #define PG8_BAR __builtin_amdgcn_s_barrier()
; template <class Epi, bool ALIGN_EPI = PG8_ALIGN, bool SP2 = PG8_SP2>
; __device__ __forceinline__ void gemm_phase(LAS uchar* lds, const Gemm g, const StaticOrder& S, const Epi& E) {
;     ...
;         for (int t = tb; t < tb + tblk; t += 2) {
;             const bool last = (t == nt - 2);
;             const char* a1 = cA + (size_t)(t + 1) * kstep;
;             const char* a2 = last ? nA : cA + (size_t)(t + 2) * kstep; const char* b2 = last ? nB : cB + (size_t)(t + 2) * kstep;
;             const char* a3 = a2 + kstep; const char* b3 = b2 + kstep;
;             if constexpr (SP2) {
;             PG8_LDB(B0, 0, 0); PG8_LDB(B1, 0, 1); PG8_SCHED; PG8_LDA(At, 0, 0); PG8_STAGE(PG8_SA(1, 1), a1 + hstepA, voffA);
;             PG8_WAIT_V(8); PG8_WAIT_L(0); PG8_BAR; PG8_MMA(0, 0, At, B0); PG8_MMA(0, 1, At, B1); PG8_BAR; PG8_SCHED;
;             PG8_LDA(At, 0, 1); PG8_STAGE(PG8_SB(0, 0), b2, voffB); PG8_STAGE(PG8_SB(0, 1), b2 + hstepB, voffB); PG8_STAGE(PG8_SA(0, 0), a2, voffA);
;             PG8_WAIT_V(8); PG8_WAIT_L(0); PG8_BAR; PG8_MMA(1, 0, At, B0); PG8_MMA(1, 1, At, B1); PG8_BAR; PG8_SCHED;
;             PG8_LDB(B0, 1, 0); PG8_LDB(B1, 1, 1); PG8_SCHED; PG8_LDA(At, 1, 0); PG8_STAGE(PG8_SA(0, 1), a2 + hstepA, voffA);
;             PG8_WAIT_V(8); PG8_WAIT_L(0); PG8_BAR; PG8_MMA(0, 0, At, B0); PG8_MMA(0, 1, At, B1); PG8_BAR; PG8_SCHED;
;             PG8_LDA(At, 1, 1); PG8_STAGE(PG8_SB(1, 0), b3, voffB); PG8_STAGE(PG8_SB(1, 1), b3 + hstepB, voffB); PG8_STAGE(PG8_SA(1, 0), a3, voffA);
;             PG8_WAIT_V(8); PG8_WAIT_L(0); PG8_BAR; PG8_MMA(1, 0, At, B0); PG8_MMA(1, 1, At, B1); PG8_BAR; PG8_SCHED;
	s_add_i32 s12, s39, s21
	v_lshl_add_u64 v[228:229], v[228:229], 0, s[84:85]
	s_mov_b32 m0, s12
	ds_read_b128 v[196:199], v173 offset:49152
	ds_read_b128 v[200:203], v173 offset:50176
	ds_read_b128 v[204:207], v173 offset:51200
	ds_read_b128 v[208:211], v173 offset:52224
	ds_read_b128 v[212:215], v173 offset:53248
	ds_read_b128 v[216:219], v173 offset:54272
	ds_read_b128 v[220:223], v173 offset:55296
	ds_read_b128 v[224:227], v173 offset:56320
	global_load_lds_dwordx4 v[228:229], off
	s_add_i32 m0, s12, 0x2000
	s_add_u32 s12, s16, 0x44080
	v_lshl_add_u64 v[228:229], v[230:231], 0, s[84:85]
	s_addc_u32 s13, s17, 0
	s_add_i32 s16, s40, s21
	global_load_lds_dwordx4 v[228:229], off
	s_mov_b32 m0, s16
	v_lshl_add_u64 v[228:229], s[12:13], 0, v[134:135]
	global_load_lds_dwordx4 v[228:229], off
	s_add_i32 m0, s16, 0x2000
	v_lshl_add_u64 v[228:229], s[12:13], 0, v[130:131]
	global_load_lds_dwordx4 v[228:229], off
	s_mov_b32 m0, s27
	v_lshl_add_u64 v[228:229], v[232:233], 0, s[84:85]
	global_load_lds_dwordx4 v[228:229], off
	s_mov_b32 m0, s28
	v_lshl_add_u64 v[228:229], v[234:235], 0, s[84:85]
	global_load_lds_dwordx4 v[228:229], off
	s_waitcnt vmcnt(8)
	s_waitcnt lgkmcnt(0)
	s_barrier
	v_mfma_f32_16x16x32_bf16 v[62:65], v[160:163], v[196:199], v[62:65]
	v_mfma_f32_16x16x32_bf16 v[58:61], v[168:171], v[196:199], v[58:61]
	v_mfma_f32_16x16x32_bf16 v[54:57], v[160:163], v[204:207], v[54:57]
	v_mfma_f32_16x16x32_bf16 v[46:49], v[168:171], v[204:207], v[46:49]
	v_mfma_f32_16x16x32_bf16 v[38:41], v[160:163], v[212:215], v[38:41]
	v_mfma_f32_16x16x32_bf16 v[30:33], v[168:171], v[212:215], v[30:33]
	v_mfma_f32_16x16x32_bf16 v[22:25], v[160:163], v[220:223], v[22:25]
	v_mfma_f32_16x16x32_bf16 v[14:17], v[168:171], v[220:223], v[14:17]
	v_mfma_f32_16x16x32_bf16 v[62:65], v[164:167], v[200:203], v[62:65]
	v_mfma_f32_16x16x32_bf16 v[58:61], v[174:177], v[200:203], v[58:61]
	v_mfma_f32_16x16x32_bf16 v[54:57], v[164:167], v[208:211], v[54:57]
	v_mfma_f32_16x16x32_bf16 v[46:49], v[174:177], v[208:211], v[46:49]
	v_mfma_f32_16x16x32_bf16 v[38:41], v[164:167], v[216:219], v[38:41]
	v_mfma_f32_16x16x32_bf16 v[30:33], v[174:177], v[216:219], v[30:33]
	v_mfma_f32_16x16x32_bf16 v[22:25], v[164:167], v[224:227], v[22:25]
	v_mfma_f32_16x16x32_bf16 v[14:17], v[174:177], v[224:227], v[14:17]
	v_mfma_f32_16x16x32_bf16 v[50:53], v[178:181], v[196:199], v[50:53]
	v_mfma_f32_16x16x32_bf16 v[42:45], v[188:191], v[196:199], v[42:45]
	v_mfma_f32_16x16x32_bf16 v[34:37], v[178:181], v[204:207], v[34:37]
	v_mfma_f32_16x16x32_bf16 v[26:29], v[188:191], v[204:207], v[26:29]
	v_mfma_f32_16x16x32_bf16 v[18:21], v[178:181], v[212:215], v[18:21]
	v_mfma_f32_16x16x32_bf16 v[10:13], v[188:191], v[212:215], v[10:13]
	v_mfma_f32_16x16x32_bf16 v[6:9], v[178:181], v[220:223], v[6:9]
	v_mfma_f32_16x16x32_bf16 v[2:5], v[188:191], v[220:223], v[2:5]
	v_mfma_f32_16x16x32_bf16 v[50:53], v[184:187], v[200:203], v[50:53]
	v_mfma_f32_16x16x32_bf16 v[42:45], v[192:195], v[200:203], v[42:45]
	v_mfma_f32_16x16x32_bf16 v[34:37], v[184:187], v[208:211], v[34:37]
	v_mfma_f32_16x16x32_bf16 v[26:29], v[192:195], v[208:211], v[26:29]
	v_mfma_f32_16x16x32_bf16 v[18:21], v[184:187], v[216:219], v[18:21]
	v_mfma_f32_16x16x32_bf16 v[10:13], v[192:195], v[216:219], v[10:13]
	v_mfma_f32_16x16x32_bf16 v[6:9], v[184:187], v[224:227], v[6:9]
	v_mfma_f32_16x16x32_bf16 v[2:5], v[192:195], v[224:227], v[2:5]
	s_barrier
	s_add_i32 s38, s38, 2
	s_add_u32 s36, s36, 0x100
	s_addc_u32 s37, s37, 0
	s_cmp_gt_u32 s38, 13
	s_mov_b64 s[12:13], s[14:15]
.LBB0_669:
	s_add_u32 s14, s12, 0x100
	s_addc_u32 s15, s13, 0
	s_add_i32 s39, 0, 0x10000
	s_cmp_eq_u32 s38, 12
	s_cselect_b32 s19, s5, s15
	s_cselect_b32 s18, s4, s14
	s_cselect_b32 s17, s11, s37
	s_cselect_b32 s16, s10, s36
	s_add_i32 s40, 0, 0x14000
	v_add_u32_e32 v174, s39, v139
	v_add_u32_e32 v192, s40, v139
	ds_read_b128 v[160:163], v174
	ds_read_b128 v[164:167], v174 offset:1024
	ds_read_b128 v[168:171], v174 offset:2048
	ds_read_b128 v[174:177], v174 offset:3072
	ds_read_b128 v[178:181], v192
	ds_read_b128 v[184:187], v192 offset:1024
	ds_read_b128 v[188:191], v192 offset:2048
	ds_read_b128 v[192:195], v192 offset:3072
	v_lshl_add_u64 v[228:229], s[12:13], 0, v[156:157]
	s_add_i32 m0, s23, 0xc000
	ds_read_b128 v[196:199], v173
	ds_read_b128 v[200:203], v173 offset:1024
	ds_read_b128 v[204:207], v173 offset:2048
	ds_read_b128 v[208:211], v173 offset:3072
	ds_read_b128 v[212:215], v173 offset:4096
	ds_read_b128 v[216:219], v173 offset:5120
	ds_read_b128 v[220:223], v173 offset:6144
	ds_read_b128 v[224:227], v173 offset:7168
	global_load_lds_dwordx4 v[228:229], off
	s_add_i32 m0, s23, 0xe000
	v_lshl_add_u64 v[228:229], s[12:13], 0, v[158:159]
	global_load_lds_dwordx4 v[228:229], off
	s_waitcnt vmcnt(8)
	s_waitcnt lgkmcnt(0)
	s_barrier
; #define PG8_STAGE(bufoff, gbase, voff) do { _Pragma("unroll") for (int _i = 0; _i < 2; ++_i) \
;         __builtin_amdgcn_global_load_lds((const unsigned*)((const char*)(gbase) + (voff)[_i]), (LAS unsigned*)(lds + (bufoff) + ldsw + _i * 8192), 16, 0, 0); } while (0)
; #define PG8_LDA(dst, b, h) do { _Pragma("unroll") for (int m = 0; m < 4; ++m) _Pragma("unroll") for (int k = 0; k < 2; ++k) dst[m][k] = *(const LAS bf16x8*)(lds + PG8_SA(b, h) + aoff + m * 2048 + k * 1024); } while (0)
; #define PG8_MMA(ai, bj, At, Bt) do { __builtin_amdgcn_s_setprio(1); _Pragma("unroll") for (int m = 0; m < 4; ++m) _Pragma("unroll") for (int n = 0; n < 2; ++n) _Pragma("unroll") for (int k = 0; k < 2; ++k) \
;         acc[ai][bj][m][n] = __builtin_amdgcn_mfma_f32_16x16x32_bf16(Bt[n][k], At[m][k], acc[ai][bj][m][n], 0, 0, 0); __builtin_amdgcn_s_setprio(0); } while (0)
; #define PG8_WAIT_V(n) asm volatile("s_waitcnt vmcnt(" #n ")" ::: "memory")
; #define PG8_WAIT_L(n) asm volatile("s_waitcnt lgkmcnt(" #n ")" ::: "memory")
; #define PG8_BAR __builtin_amdgcn_s_barrier()
; #define PG8_SCHED __builtin_amdgcn_sched_barrier(0)
; template <class Epi, bool ALIGN_EPI = PG8_ALIGN, bool SP2 = PG8_SP2>
; __device__ __forceinline__ void gemm_phase(LAS uchar* lds, const Gemm g, const StaticOrder& S, const Epi& E) {
;     ...
;             PG8_WAIT_V(8); PG8_WAIT_L(0); PG8_BAR; PG8_MMA(0, 0, At, B0); PG8_MMA(0, 1, At, B1); PG8_BAR; PG8_SCHED;
;             PG8_LDA(At, 0, 1); PG8_STAGE(PG8_SB(0, 0), b2, voffB); PG8_STAGE(PG8_SB(0, 1), b2 + hstepB, voffB); PG8_STAGE(PG8_SA(0, 0), a2, voffA);
;             PG8_WAIT_V(8); PG8_WAIT_L(0); PG8_BAR; PG8_MMA(1, 0, At, B0); PG8_MMA(1, 1, At, B1); PG8_BAR; PG8_SCHED;
	v_mfma_f32_16x16x32_bf16 v[126:129], v[160:163], v[196:199], v[126:129]
	v_mfma_f32_16x16x32_bf16 v[122:125], v[168:171], v[196:199], v[122:125]
	v_mfma_f32_16x16x32_bf16 v[118:121], v[160:163], v[204:207], v[118:121]
	v_mfma_f32_16x16x32_bf16 v[110:113], v[168:171], v[204:207], v[110:113]
	v_mfma_f32_16x16x32_bf16 v[102:105], v[160:163], v[212:215], v[102:105]
	v_mfma_f32_16x16x32_bf16 v[94:97], v[168:171], v[212:215], v[94:97]
	v_mfma_f32_16x16x32_bf16 v[86:89], v[160:163], v[220:223], v[86:89]
	v_mfma_f32_16x16x32_bf16 v[78:81], v[168:171], v[220:223], v[78:81]
	v_mfma_f32_16x16x32_bf16 v[126:129], v[164:167], v[200:203], v[126:129]
	v_mfma_f32_16x16x32_bf16 v[122:125], v[174:177], v[200:203], v[122:125]
	v_mfma_f32_16x16x32_bf16 v[118:121], v[164:167], v[208:211], v[118:121]
	v_mfma_f32_16x16x32_bf16 v[110:113], v[174:177], v[208:211], v[110:113]
	v_mfma_f32_16x16x32_bf16 v[102:105], v[164:167], v[216:219], v[102:105]
	v_mfma_f32_16x16x32_bf16 v[94:97], v[174:177], v[216:219], v[94:97]
	v_mfma_f32_16x16x32_bf16 v[86:89], v[164:167], v[224:227], v[86:89]
	v_mfma_f32_16x16x32_bf16 v[78:81], v[174:177], v[224:227], v[78:81]
	v_mfma_f32_16x16x32_bf16 v[114:117], v[178:181], v[196:199], v[114:117]
	v_mfma_f32_16x16x32_bf16 v[106:109], v[188:191], v[196:199], v[106:109]
	v_mfma_f32_16x16x32_bf16 v[98:101], v[178:181], v[204:207], v[98:101]
	v_mfma_f32_16x16x32_bf16 v[90:93], v[188:191], v[204:207], v[90:93]
	v_mfma_f32_16x16x32_bf16 v[82:85], v[178:181], v[212:215], v[82:85]
	v_mfma_f32_16x16x32_bf16 v[74:77], v[188:191], v[212:215], v[74:77]
	v_mfma_f32_16x16x32_bf16 v[70:73], v[178:181], v[220:223], v[70:73]
	v_mfma_f32_16x16x32_bf16 v[66:69], v[188:191], v[220:223], v[66:69]
	v_mfma_f32_16x16x32_bf16 v[114:117], v[184:187], v[200:203], v[114:117]
	v_mfma_f32_16x16x32_bf16 v[106:109], v[192:195], v[200:203], v[106:109]
	v_mfma_f32_16x16x32_bf16 v[98:101], v[184:187], v[208:211], v[98:101]
	v_mfma_f32_16x16x32_bf16 v[90:93], v[192:195], v[208:211], v[90:93]
	v_mfma_f32_16x16x32_bf16 v[82:85], v[184:187], v[216:219], v[82:85]
	v_mfma_f32_16x16x32_bf16 v[74:77], v[192:195], v[216:219], v[74:77]
	v_mfma_f32_16x16x32_bf16 v[70:73], v[184:187], v[224:227], v[70:73]
	v_mfma_f32_16x16x32_bf16 v[66:69], v[192:195], v[224:227], v[66:69]
	s_barrier
	s_add_i32 s12, s39, s21
	v_lshl_add_u64 v[228:229], s[16:17], 0, v[134:135]
	s_mov_b32 m0, s12
	ds_read_b128 v[196:199], v173 offset:16384
	ds_read_b128 v[200:203], v173 offset:17408
	ds_read_b128 v[204:207], v173 offset:18432
	ds_read_b128 v[208:211], v173 offset:19456
	ds_read_b128 v[212:215], v173 offset:20480
	ds_read_b128 v[216:219], v173 offset:21504
	ds_read_b128 v[220:223], v173 offset:22528
	ds_read_b128 v[224:227], v173 offset:23552
	global_load_lds_dwordx4 v[228:229], off
	s_add_i32 m0, s12, 0x2000
	s_add_u32 s12, s16, 0x44000
	v_lshl_add_u64 v[230:231], s[16:17], 0, v[130:131]
	s_addc_u32 s13, s17, 0
	s_add_i32 s39, s40, s21
	global_load_lds_dwordx4 v[230:231], off
	v_lshl_add_u64 v[232:233], s[12:13], 0, v[134:135]
	s_mov_b32 m0, s39
	global_load_lds_dwordx4 v[232:233], off
	s_add_i32 m0, s39, 0x2000
	v_lshl_add_u64 v[232:233], s[12:13], 0, v[130:131]
	global_load_lds_dwordx4 v[232:233], off
	s_mov_b32 m0, s23
	v_lshl_add_u64 v[232:233], s[18:19], 0, v[152:153]
	global_load_lds_dwordx4 v[232:233], off
	s_mov_b32 m0, s24
	v_lshl_add_u64 v[234:235], s[18:19], 0, v[132:133]
	global_load_lds_dwordx4 v[234:235], off
	s_waitcnt vmcnt(8)
	s_waitcnt lgkmcnt(0)
	s_barrier
	v_mfma_f32_16x16x32_bf16 v[62:65], v[160:163], v[196:199], v[62:65]
	v_mfma_f32_16x16x32_bf16 v[58:61], v[168:171], v[196:199], v[58:61]
	v_mfma_f32_16x16x32_bf16 v[54:57], v[160:163], v[204:207], v[54:57]
	v_mfma_f32_16x16x32_bf16 v[46:49], v[168:171], v[204:207], v[46:49]
	v_mfma_f32_16x16x32_bf16 v[38:41], v[160:163], v[212:215], v[38:41]
	v_mfma_f32_16x16x32_bf16 v[30:33], v[168:171], v[212:215], v[30:33]
	v_mfma_f32_16x16x32_bf16 v[22:25], v[160:163], v[220:223], v[22:25]
	v_mfma_f32_16x16x32_bf16 v[14:17], v[168:171], v[220:223], v[14:17]
	v_mfma_f32_16x16x32_bf16 v[62:65], v[164:167], v[200:203], v[62:65]
	v_mfma_f32_16x16x32_bf16 v[58:61], v[174:177], v[200:203], v[58:61]
	v_mfma_f32_16x16x32_bf16 v[54:57], v[164:167], v[208:211], v[54:57]
	v_mfma_f32_16x16x32_bf16 v[46:49], v[174:177], v[208:211], v[46:49]
	v_mfma_f32_16x16x32_bf16 v[38:41], v[164:167], v[216:219], v[38:41]
	v_mfma_f32_16x16x32_bf16 v[30:33], v[174:177], v[216:219], v[30:33]
	v_mfma_f32_16x16x32_bf16 v[22:25], v[164:167], v[224:227], v[22:25]
	v_mfma_f32_16x16x32_bf16 v[14:17], v[174:177], v[224:227], v[14:17]
	v_mfma_f32_16x16x32_bf16 v[50:53], v[178:181], v[196:199], v[50:53]
	v_mfma_f32_16x16x32_bf16 v[42:45], v[188:191], v[196:199], v[42:45]
	v_mfma_f32_16x16x32_bf16 v[34:37], v[178:181], v[204:207], v[34:37]
	v_mfma_f32_16x16x32_bf16 v[26:29], v[188:191], v[204:207], v[26:29]
	v_mfma_f32_16x16x32_bf16 v[18:21], v[178:181], v[212:215], v[18:21]
	v_mfma_f32_16x16x32_bf16 v[10:13], v[188:191], v[212:215], v[10:13]
	v_mfma_f32_16x16x32_bf16 v[6:9], v[178:181], v[220:223], v[6:9]
	v_mfma_f32_16x16x32_bf16 v[2:5], v[188:191], v[220:223], v[2:5]
	v_mfma_f32_16x16x32_bf16 v[50:53], v[184:187], v[200:203], v[50:53]
	v_mfma_f32_16x16x32_bf16 v[42:45], v[192:195], v[200:203], v[42:45]
	v_mfma_f32_16x16x32_bf16 v[34:37], v[184:187], v[208:211], v[34:37]
	v_mfma_f32_16x16x32_bf16 v[26:29], v[192:195], v[208:211], v[26:29]
	v_mfma_f32_16x16x32_bf16 v[18:21], v[184:187], v[216:219], v[18:21]
	v_mfma_f32_16x16x32_bf16 v[10:13], v[192:195], v[216:219], v[10:13]
	v_mfma_f32_16x16x32_bf16 v[6:9], v[184:187], v[224:227], v[6:9]
	v_mfma_f32_16x16x32_bf16 v[2:5], v[192:195], v[224:227], v[2:5]
	s_barrier
; #define PG8_STAGE(bufoff, gbase, voff) do { _Pragma("unroll") for (int _i = 0; _i < 2; ++_i) \
;         __builtin_amdgcn_global_load_lds((const unsigned*)((const char*)(gbase) + (voff)[_i]), (LAS unsigned*)(lds + (bufoff) + ldsw + _i * 8192), 16, 0, 0); } while (0)
; #define PG8_LDA(dst, b, h) do { _Pragma("unroll") for (int m = 0; m < 4; ++m) _Pragma("unroll") for (int k = 0; k < 2; ++k) dst[m][k] = *(const LAS bf16x8*)(lds + PG8_SA(b, h) + aoff + m * 2048 + k * 1024); } while (0)
; #define PG8_LDB(dst, b, h) do { _Pragma("unroll") for (int n = 0; n < 2; ++n) _Pragma("unroll") for (int k = 0; k < 2; ++k) dst[n][k] = *(const LAS bf16x8*)(lds + PG8_SB(b, h) + boff + n * 2048 + k * 1024); } while (0)
; #define PG8_MMA(ai, bj, At, Bt) do { __builtin_amdgcn_s_setprio(1); _Pragma("unroll") for (int m = 0; m < 4; ++m) _Pragma("unroll") for (int n = 0; n < 2; ++n) _Pragma("unroll") for (int k = 0; k < 2; ++k) \
;         acc[ai][bj][m][n] = __builtin_amdgcn_mfma_f32_16x16x32_bf16(Bt[n][k], At[m][k], acc[ai][bj][m][n], 0, 0, 0); __builtin_amdgcn_s_setprio(0); } while (0)
; #define PG8_WAIT_V(n) asm volatile("s_waitcnt vmcnt(" #n ")" ::: "memory")
; #define PG8_WAIT_L(n) asm volatile("s_waitcnt lgkmcnt(" #n ")" ::: "memory")
; #define PG8_BAR __builtin_amdgcn_s_barrier()
; #define PG8_SCHED __builtin_amdgcn_sched_barrier(0)
; template <class Epi, bool ALIGN_EPI = PG8_ALIGN, bool SP2 = PG8_SP2>
; __device__ __forceinline__ void gemm_phase(LAS uchar* lds, const Gemm g, const StaticOrder& S, const Epi& E) {
;     ...
;             PG8_LDB(B0, 1, 0); PG8_LDB(B1, 1, 1); PG8_SCHED; PG8_LDA(At, 1, 0); PG8_STAGE(PG8_SA(0, 1), a2 + hstepA, voffA);
;             PG8_WAIT_V(8); PG8_WAIT_L(0); PG8_BAR; PG8_MMA(0, 0, At, B0); PG8_MMA(0, 1, At, B1); PG8_BAR; PG8_SCHED;
;             PG8_LDA(At, 1, 1); PG8_STAGE(PG8_SB(1, 0), b3, voffB); PG8_STAGE(PG8_SB(1, 1), b3 + hstepB, voffB); PG8_STAGE(PG8_SA(1, 0), a3, voffA);
;             PG8_WAIT_V(8); PG8_WAIT_L(0); PG8_BAR; PG8_MMA(1, 0, At, B0); PG8_MMA(1, 1, At, B1); PG8_BAR; PG8_SCHED;
;     ...
;         if constexpr (ALIGN_EPI) { if (wr == 0) PG8_BAR; }
	s_add_i32 s39, 0, 0x18000
	s_add_i32 s40, 0, 0x1c000
	v_add_u32_e32 v174, s39, v139
	v_add_u32_e32 v192, s40, v139
	ds_read_b128 v[160:163], v174
	ds_read_b128 v[164:167], v174 offset:1024
	ds_read_b128 v[168:171], v174 offset:2048
	ds_read_b128 v[174:177], v174 offset:3072
	ds_read_b128 v[178:181], v192
	ds_read_b128 v[184:187], v192 offset:1024
	ds_read_b128 v[188:191], v192 offset:2048
	ds_read_b128 v[192:195], v192 offset:3072
	s_add_u32 s12, s18, 0x44000
	s_addc_u32 s13, s19, 0
	s_mov_b32 m0, s25
	v_lshl_add_u64 v[236:237], s[12:13], 0, v[152:153]
	ds_read_b128 v[196:199], v173 offset:32768
	ds_read_b128 v[200:203], v173 offset:33792
	ds_read_b128 v[204:207], v173 offset:34816
	ds_read_b128 v[208:211], v173 offset:35840
	ds_read_b128 v[212:215], v173 offset:36864
	ds_read_b128 v[216:219], v173 offset:37888
	ds_read_b128 v[220:223], v173 offset:38912
	ds_read_b128 v[224:227], v173 offset:39936
	global_load_lds_dwordx4 v[236:237], off
	s_mov_b32 m0, s26
	v_lshl_add_u64 v[236:237], s[12:13], 0, v[132:133]
	global_load_lds_dwordx4 v[236:237], off
	s_waitcnt vmcnt(8)
	s_waitcnt lgkmcnt(0)
	s_barrier
	v_mfma_f32_16x16x32_bf16 v[126:129], v[160:163], v[196:199], v[126:129]
	v_mfma_f32_16x16x32_bf16 v[122:125], v[168:171], v[196:199], v[122:125]
	v_mfma_f32_16x16x32_bf16 v[118:121], v[160:163], v[204:207], v[118:121]
	v_mfma_f32_16x16x32_bf16 v[110:113], v[168:171], v[204:207], v[110:113]
	v_mfma_f32_16x16x32_bf16 v[102:105], v[160:163], v[212:215], v[102:105]
	v_mfma_f32_16x16x32_bf16 v[94:97], v[168:171], v[212:215], v[94:97]
	v_mfma_f32_16x16x32_bf16 v[86:89], v[160:163], v[220:223], v[86:89]
	v_mfma_f32_16x16x32_bf16 v[78:81], v[168:171], v[220:223], v[78:81]
	v_mfma_f32_16x16x32_bf16 v[126:129], v[164:167], v[200:203], v[126:129]
	v_mfma_f32_16x16x32_bf16 v[122:125], v[174:177], v[200:203], v[122:125]
	v_mfma_f32_16x16x32_bf16 v[118:121], v[164:167], v[208:211], v[118:121]
	v_mfma_f32_16x16x32_bf16 v[110:113], v[174:177], v[208:211], v[110:113]
	v_mfma_f32_16x16x32_bf16 v[102:105], v[164:167], v[216:219], v[102:105]
	v_mfma_f32_16x16x32_bf16 v[94:97], v[174:177], v[216:219], v[94:97]
	v_mfma_f32_16x16x32_bf16 v[86:89], v[164:167], v[224:227], v[86:89]
	v_mfma_f32_16x16x32_bf16 v[78:81], v[174:177], v[224:227], v[78:81]
	v_mfma_f32_16x16x32_bf16 v[114:117], v[178:181], v[196:199], v[114:117]
	v_mfma_f32_16x16x32_bf16 v[106:109], v[188:191], v[196:199], v[106:109]
	v_mfma_f32_16x16x32_bf16 v[98:101], v[178:181], v[204:207], v[98:101]
	v_mfma_f32_16x16x32_bf16 v[90:93], v[188:191], v[204:207], v[90:93]
	v_mfma_f32_16x16x32_bf16 v[82:85], v[178:181], v[212:215], v[82:85]
	v_mfma_f32_16x16x32_bf16 v[74:77], v[188:191], v[212:215], v[74:77]
	v_mfma_f32_16x16x32_bf16 v[70:73], v[178:181], v[220:223], v[70:73]
	v_mfma_f32_16x16x32_bf16 v[66:69], v[188:191], v[220:223], v[66:69]
	v_mfma_f32_16x16x32_bf16 v[114:117], v[184:187], v[200:203], v[114:117]
	v_mfma_f32_16x16x32_bf16 v[106:109], v[192:195], v[200:203], v[106:109]
	v_mfma_f32_16x16x32_bf16 v[98:101], v[184:187], v[208:211], v[98:101]
	v_mfma_f32_16x16x32_bf16 v[90:93], v[192:195], v[208:211], v[90:93]
	v_mfma_f32_16x16x32_bf16 v[82:85], v[184:187], v[216:219], v[82:85]
	v_mfma_f32_16x16x32_bf16 v[74:77], v[192:195], v[216:219], v[74:77]
	v_mfma_f32_16x16x32_bf16 v[70:73], v[184:187], v[224:227], v[70:73]
	v_mfma_f32_16x16x32_bf16 v[66:69], v[192:195], v[224:227], v[66:69]
	s_barrier
	s_add_i32 s12, s39, s21
	v_lshl_add_u64 v[228:229], v[228:229], 0, s[84:85]
	s_mov_b32 m0, s12
	ds_read_b128 v[196:199], v173 offset:49152
	ds_read_b128 v[200:203], v173 offset:50176
	ds_read_b128 v[204:207], v173 offset:51200
	ds_read_b128 v[208:211], v173 offset:52224
	ds_read_b128 v[212:215], v173 offset:53248
	ds_read_b128 v[216:219], v173 offset:54272
	ds_read_b128 v[220:223], v173 offset:55296
	ds_read_b128 v[224:227], v173 offset:56320
	global_load_lds_dwordx4 v[228:229], off
	s_add_i32 m0, s12, 0x2000
	s_add_u32 s12, s16, 0x44080
	v_lshl_add_u64 v[228:229], v[230:231], 0, s[84:85]
	s_addc_u32 s13, s17, 0
	s_add_i32 s16, s40, s21
	global_load_lds_dwordx4 v[228:229], off
	s_mov_b32 m0, s16
	v_lshl_add_u64 v[228:229], s[12:13], 0, v[134:135]
	global_load_lds_dwordx4 v[228:229], off
	s_add_i32 m0, s16, 0x2000
	v_lshl_add_u64 v[228:229], s[12:13], 0, v[130:131]
	global_load_lds_dwordx4 v[228:229], off
	s_mov_b32 m0, s27
	v_lshl_add_u64 v[228:229], v[232:233], 0, s[84:85]
	global_load_lds_dwordx4 v[228:229], off
	s_mov_b32 m0, s28
	v_lshl_add_u64 v[228:229], v[234:235], 0, s[84:85]
	global_load_lds_dwordx4 v[228:229], off
	s_waitcnt vmcnt(8)
	s_waitcnt lgkmcnt(0)
	s_barrier
	v_mfma_f32_16x16x32_bf16 v[62:65], v[160:163], v[196:199], v[62:65]
	v_mfma_f32_16x16x32_bf16 v[58:61], v[168:171], v[196:199], v[58:61]
	v_mfma_f32_16x16x32_bf16 v[54:57], v[160:163], v[204:207], v[54:57]
	v_mfma_f32_16x16x32_bf16 v[46:49], v[168:171], v[204:207], v[46:49]
	v_mfma_f32_16x16x32_bf16 v[38:41], v[160:163], v[212:215], v[38:41]
	v_mfma_f32_16x16x32_bf16 v[30:33], v[168:171], v[212:215], v[30:33]
	v_mfma_f32_16x16x32_bf16 v[22:25], v[160:163], v[220:223], v[22:25]
	v_mfma_f32_16x16x32_bf16 v[14:17], v[168:171], v[220:223], v[14:17]
	v_mfma_f32_16x16x32_bf16 v[62:65], v[164:167], v[200:203], v[62:65]
	v_mfma_f32_16x16x32_bf16 v[58:61], v[174:177], v[200:203], v[58:61]
	v_mfma_f32_16x16x32_bf16 v[54:57], v[164:167], v[208:211], v[54:57]
	v_mfma_f32_16x16x32_bf16 v[46:49], v[174:177], v[208:211], v[46:49]
	v_mfma_f32_16x16x32_bf16 v[38:41], v[164:167], v[216:219], v[38:41]
	v_mfma_f32_16x16x32_bf16 v[30:33], v[174:177], v[216:219], v[30:33]
	v_mfma_f32_16x16x32_bf16 v[22:25], v[164:167], v[224:227], v[22:25]
	v_mfma_f32_16x16x32_bf16 v[14:17], v[174:177], v[224:227], v[14:17]
	v_mfma_f32_16x16x32_bf16 v[50:53], v[178:181], v[196:199], v[50:53]
	v_mfma_f32_16x16x32_bf16 v[42:45], v[188:191], v[196:199], v[42:45]
	v_mfma_f32_16x16x32_bf16 v[34:37], v[178:181], v[204:207], v[34:37]
	v_mfma_f32_16x16x32_bf16 v[26:29], v[188:191], v[204:207], v[26:29]
	v_mfma_f32_16x16x32_bf16 v[18:21], v[178:181], v[212:215], v[18:21]
	v_mfma_f32_16x16x32_bf16 v[10:13], v[188:191], v[212:215], v[10:13]
	v_mfma_f32_16x16x32_bf16 v[6:9], v[178:181], v[220:223], v[6:9]
	v_mfma_f32_16x16x32_bf16 v[2:5], v[188:191], v[220:223], v[2:5]
	v_mfma_f32_16x16x32_bf16 v[50:53], v[184:187], v[200:203], v[50:53]
	v_mfma_f32_16x16x32_bf16 v[42:45], v[192:195], v[200:203], v[42:45]
	v_mfma_f32_16x16x32_bf16 v[34:37], v[184:187], v[208:211], v[34:37]
	v_mfma_f32_16x16x32_bf16 v[26:29], v[192:195], v[208:211], v[26:29]
	v_mfma_f32_16x16x32_bf16 v[18:21], v[184:187], v[216:219], v[18:21]
	v_mfma_f32_16x16x32_bf16 v[10:13], v[192:195], v[216:219], v[10:13]
	v_mfma_f32_16x16x32_bf16 v[6:9], v[184:187], v[224:227], v[6:9]
	v_mfma_f32_16x16x32_bf16 v[2:5], v[192:195], v[224:227], v[2:5]
	s_barrier
	s_add_i32 s38, s38, 2
	s_add_u32 s36, s36, 0x100
	s_addc_u32 s37, s37, 0
	s_cmp_gt_u32 s38, 13
	s_mov_b64 s[12:13], s[14:15]
	s_cbranch_scc0 .LBB0_669
	s_and_b64 vcc, exec, s[8:9]
	s_cbranch_vccz .LBB0_672
	s_barrier

; #define PG8_STAGE(bufoff, gbase, voff) do { _Pragma("unroll") for (int _i = 0; _i < 2; ++_i) \
;         __builtin_amdgcn_global_load_lds((const unsigned*)((const char*)(gbase) + (voff)[_i]), (LAS unsigned*)(lds + (bufoff) + ldsw + _i * 8192), 16, 0, 0); } while (0)
; #define PG8_LDA(dst, b, h) do { _Pragma("unroll") for (int m = 0; m < 4; ++m) _Pragma("unroll") for (int k = 0; k < 2; ++k) dst[m][k] = *(const LAS bf16x8*)(lds + PG8_SA(b, h) + aoff + m * 2048 + k * 1024); } while (0)
; #define PG8_LDB(dst, b, h) do { _Pragma("unroll") for (int n = 0; n < 2; ++n) _Pragma("unroll") for (int k = 0; k < 2; ++k) dst[n][k] = *(const LAS bf16x8*)(lds + PG8_SB(b, h) + boff + n * 2048 + k * 1024); } while (0)
; #define PG8_MMA(ai, bj, At, Bt) do { __builtin_amdgcn_s_setprio(1); _Pragma("unroll") for (int m = 0; m < 4; ++m) _Pragma("unroll") for (int n = 0; n < 2; ++n) _Pragma("unroll") for (int k = 0; k < 2; ++k) \
;         acc[ai][bj][m][n] = __builtin_amdgcn_mfma_f32_16x16x32_bf16(Bt[n][k], At[m][k], acc[ai][bj][m][n], 0, 0, 0); __builtin_amdgcn_s_setprio(0); } while (0)
; #define PG8_WAIT_V(n) asm volatile("s_waitcnt vmcnt(" #n ")" ::: "memory")
; #define PG8_WAIT_L(n) asm volatile("s_waitcnt lgkmcnt(" #n ")" ::: "memory")
; #define PG8_BAR __builtin_amdgcn_s_barrier()
; #define PG8_SCHED __builtin_amdgcn_sched_barrier(0)
; template <class Epi, bool ALIGN_EPI = PG8_ALIGN, bool SP2 = PG8_SP2>
; __device__ __forceinline__ void gemm_phase(LAS uchar* lds, const Gemm g, const StaticOrder& S, const Epi& E) {
;     ...
;             const bool last = (t == nt - 2);
;             const char* a1 = cA + (size_t)(t + 1) * kstep;
;             const char* a2 = last ? nA : cA + (size_t)(t + 2) * kstep; const char* b2 = last ? nB : cB + (size_t)(t + 2) * kstep;
;             const char* a3 = a2 + kstep; const char* b3 = b2 + kstep;
;             if constexpr (SP2) {
;             PG8_LDB(B0, 0, 0); PG8_LDB(B1, 0, 1); PG8_SCHED; PG8_LDA(At, 0, 0); PG8_STAGE(PG8_SA(1, 1), a1 + hstepA, voffA);
;             PG8_WAIT_V(8); PG8_WAIT_L(0); PG8_BAR; PG8_MMA(0, 0, At, B0); PG8_MMA(0, 1, At, B1); PG8_BAR; PG8_SCHED;
;             PG8_LDA(At, 0, 1); PG8_STAGE(PG8_SB(0, 0), b2, voffB); PG8_STAGE(PG8_SB(0, 1), b2 + hstepB, voffB); PG8_STAGE(PG8_SA(0, 0), a2, voffA);
.LBB0_836:
	s_add_u32 s36, s14, 0x100
	s_addc_u32 s37, s15, 0
	s_mov_b32 s38, -2
	s_add_u32 s14, s12, 0x100
	s_addc_u32 s15, s13, 0
	s_add_i32 s39, 0, 0x10000
	s_cmp_eq_u32 s38, 12
	s_cselect_b32 s19, s5, s15
	s_cselect_b32 s18, s4, s14
	s_cselect_b32 s17, s11, s37
	s_cselect_b32 s16, s10, s36
	s_add_i32 s40, 0, 0x14000
	v_add_u32_e32 v174, s39, v139
	v_add_u32_e32 v192, s40, v139
	ds_read_b128 v[160:163], v174
	ds_read_b128 v[166:169], v174 offset:1024
	ds_read_b128 v[170:173], v174 offset:2048
	ds_read_b128 v[174:177], v174 offset:3072
	ds_read_b128 v[178:181], v192
	ds_read_b128 v[184:187], v192 offset:1024
	ds_read_b128 v[188:191], v192 offset:2048
	ds_read_b128 v[192:195], v192 offset:3072
	v_lshl_add_u64 v[228:229], s[12:13], 0, v[156:157]
	s_add_i32 m0, s23, 0xc000
	ds_read_b128 v[196:199], v165
	ds_read_b128 v[200:203], v165 offset:1024
	ds_read_b128 v[204:207], v165 offset:2048
	ds_read_b128 v[208:211], v165 offset:3072
	ds_read_b128 v[212:215], v165 offset:4096
	ds_read_b128 v[216:219], v165 offset:5120
	ds_read_b128 v[220:223], v165 offset:6144
	ds_read_b128 v[224:227], v165 offset:7168
	global_load_lds_dwordx4 v[228:229], off
	s_add_i32 m0, s23, 0xe000
	v_lshl_add_u64 v[228:229], s[12:13], 0, v[158:159]
	global_load_lds_dwordx4 v[228:229], off
	s_waitcnt vmcnt(8)
	s_waitcnt lgkmcnt(0)
	s_barrier
	v_mfma_f32_16x16x32_bf16 v[126:129], v[160:163], v[196:199], 0
	v_mfma_f32_16x16x32_bf16 v[122:125], v[170:173], v[196:199], 0
	v_mfma_f32_16x16x32_bf16 v[118:121], v[160:163], v[204:207], 0
	v_mfma_f32_16x16x32_bf16 v[110:113], v[170:173], v[204:207], 0
	v_mfma_f32_16x16x32_bf16 v[102:105], v[160:163], v[212:215], 0
	v_mfma_f32_16x16x32_bf16 v[94:97], v[170:173], v[212:215], 0
	v_mfma_f32_16x16x32_bf16 v[86:89], v[160:163], v[220:223], 0
	v_mfma_f32_16x16x32_bf16 v[78:81], v[170:173], v[220:223], 0
	v_mfma_f32_16x16x32_bf16 v[126:129], v[166:169], v[200:203], v[126:129]
	v_mfma_f32_16x16x32_bf16 v[122:125], v[174:177], v[200:203], v[122:125]
	v_mfma_f32_16x16x32_bf16 v[118:121], v[166:169], v[208:211], v[118:121]
	v_mfma_f32_16x16x32_bf16 v[110:113], v[174:177], v[208:211], v[110:113]
	v_mfma_f32_16x16x32_bf16 v[102:105], v[166:169], v[216:219], v[102:105]
	v_mfma_f32_16x16x32_bf16 v[94:97], v[174:177], v[216:219], v[94:97]
	v_mfma_f32_16x16x32_bf16 v[86:89], v[166:169], v[224:227], v[86:89]
	v_mfma_f32_16x16x32_bf16 v[78:81], v[174:177], v[224:227], v[78:81]
	v_mfma_f32_16x16x32_bf16 v[114:117], v[178:181], v[196:199], 0
	v_mfma_f32_16x16x32_bf16 v[106:109], v[188:191], v[196:199], 0
	v_mfma_f32_16x16x32_bf16 v[98:101], v[178:181], v[204:207], 0
	v_mfma_f32_16x16x32_bf16 v[90:93], v[188:191], v[204:207], 0
	v_mfma_f32_16x16x32_bf16 v[82:85], v[178:181], v[212:215], 0
	v_mfma_f32_16x16x32_bf16 v[74:77], v[188:191], v[212:215], 0
	v_mfma_f32_16x16x32_bf16 v[70:73], v[178:181], v[220:223], 0
	v_mfma_f32_16x16x32_bf16 v[66:69], v[188:191], v[220:223], 0
	v_mfma_f32_16x16x32_bf16 v[114:117], v[184:187], v[200:203], v[114:117]
	v_mfma_f32_16x16x32_bf16 v[106:109], v[192:195], v[200:203], v[106:109]
	v_mfma_f32_16x16x32_bf16 v[98:101], v[184:187], v[208:211], v[98:101]
	v_mfma_f32_16x16x32_bf16 v[90:93], v[192:195], v[208:211], v[90:93]
	v_mfma_f32_16x16x32_bf16 v[82:85], v[184:187], v[216:219], v[82:85]
	v_mfma_f32_16x16x32_bf16 v[74:77], v[192:195], v[216:219], v[74:77]
	v_mfma_f32_16x16x32_bf16 v[70:73], v[184:187], v[224:227], v[70:73]
	v_mfma_f32_16x16x32_bf16 v[66:69], v[192:195], v[224:227], v[66:69]
	s_barrier
	s_add_i32 s12, s39, s22
	v_lshl_add_u64 v[228:229], s[16:17], 0, v[132:133]
	s_mov_b32 m0, s12
	ds_read_b128 v[196:199], v165 offset:16384
	ds_read_b128 v[200:203], v165 offset:17408
	ds_read_b128 v[204:207], v165 offset:18432
	ds_read_b128 v[208:211], v165 offset:19456
	ds_read_b128 v[212:215], v165 offset:20480
	ds_read_b128 v[216:219], v165 offset:21504
	ds_read_b128 v[220:223], v165 offset:22528
	ds_read_b128 v[224:227], v165 offset:23552
	global_load_lds_dwordx4 v[228:229], off
	s_add_i32 m0, s12, 0x2000
	s_add_u32 s12, s16, 0x44000
	v_lshl_add_u64 v[230:231], s[16:17], 0, v[152:153]
	s_addc_u32 s13, s17, 0
	s_add_i32 s39, s40, s22
	global_load_lds_dwordx4 v[230:231], off
	v_lshl_add_u64 v[232:233], s[12:13], 0, v[132:133]
	s_mov_b32 m0, s39
	global_load_lds_dwordx4 v[232:233], off
	s_add_i32 m0, s39, 0x2000
	v_lshl_add_u64 v[232:233], s[12:13], 0, v[152:153]
	global_load_lds_dwordx4 v[232:233], off
	s_mov_b32 m0, s23
	v_lshl_add_u64 v[232:233], s[18:19], 0, v[130:131]
	global_load_lds_dwordx4 v[232:233], off
	s_mov_b32 m0, s24
	v_lshl_add_u64 v[234:235], s[18:19], 0, v[134:135]
	global_load_lds_dwordx4 v[234:235], off
	s_waitcnt vmcnt(8)
	s_waitcnt lgkmcnt(0)
	s_barrier
; #define PG8_STAGE(bufoff, gbase, voff) do { _Pragma("unroll") for (int _i = 0; _i < 2; ++_i) \
;         __builtin_amdgcn_global_load_lds((const unsigned*)((const char*)(gbase) + (voff)[_i]), (LAS unsigned*)(lds + (bufoff) + ldsw + _i * 8192), 16, 0, 0); } while (0)
; #define PG8_LDA(dst, b, h) do { _Pragma("unroll") for (int m = 0; m < 4; ++m) _Pragma("unroll") for (int k = 0; k < 2; ++k) dst[m][k] = *(const LAS bf16x8*)(lds + PG8_SA(b, h) + aoff + m * 2048 + k * 1024); } while (0)
; #define PG8_LDB(dst, b, h) do { _Pragma("unroll") for (int n = 0; n < 2; ++n) _Pragma("unroll") for (int k = 0; k < 2; ++k) dst[n][k] = *(const LAS bf16x8*)(lds + PG8_SB(b, h) + boff + n * 2048 + k * 1024); } while (0)
; #define PG8_MMA(ai, bj, At, Bt) do { __builtin_amdgcn_s_setprio(1); _Pragma("unroll") for (int m = 0; m < 4; ++m) _Pragma("unroll") for (int n = 0; n < 2; ++n) _Pragma("unroll") for (int k = 0; k < 2; ++k) \
;         acc[ai][bj][m][n] = __builtin_amdgcn_mfma_f32_16x16x32_bf16(Bt[n][k], At[m][k], acc[ai][bj][m][n], 0, 0, 0); __builtin_amdgcn_s_setprio(0); } while (0)
; #define PG8_WAIT_V(n) asm volatile("s_waitcnt vmcnt(" #n ")" ::: "memory")
; #define PG8_WAIT_L(n) asm volatile("s_waitcnt lgkmcnt(" #n ")" ::: "memory")
; #define PG8_BAR __builtin_amdgcn_s_barrier()
; #define PG8_SCHED __builtin_amdgcn_sched_barrier(0)
; template <class Epi, bool ALIGN_EPI = PG8_ALIGN, bool SP2 = PG8_SP2>
; __device__ __forceinline__ void gemm_phase(LAS uchar* lds, const Gemm g, const StaticOrder& S, const Epi& E) {
;     ...
;             PG8_WAIT_V(8); PG8_WAIT_L(0); PG8_BAR; PG8_MMA(1, 0, At, B0); PG8_MMA(1, 1, At, B1); PG8_BAR; PG8_SCHED;
;             PG8_LDB(B0, 1, 0); PG8_LDB(B1, 1, 1); PG8_SCHED; PG8_LDA(At, 1, 0); PG8_STAGE(PG8_SA(0, 1), a2 + hstepA, voffA);
;             PG8_WAIT_V(8); PG8_WAIT_L(0); PG8_BAR; PG8_MMA(0, 0, At, B0); PG8_MMA(0, 1, At, B1); PG8_BAR; PG8_SCHED;
	v_mfma_f32_16x16x32_bf16 v[62:65], v[160:163], v[196:199], 0
	v_mfma_f32_16x16x32_bf16 v[58:61], v[170:173], v[196:199], 0
	v_mfma_f32_16x16x32_bf16 v[54:57], v[160:163], v[204:207], 0
	v_mfma_f32_16x16x32_bf16 v[46:49], v[170:173], v[204:207], 0
	v_mfma_f32_16x16x32_bf16 v[38:41], v[160:163], v[212:215], 0
	v_mfma_f32_16x16x32_bf16 v[30:33], v[170:173], v[212:215], 0
	v_mfma_f32_16x16x32_bf16 v[22:25], v[160:163], v[220:223], 0
	v_mfma_f32_16x16x32_bf16 v[14:17], v[170:173], v[220:223], 0
	v_mfma_f32_16x16x32_bf16 v[62:65], v[166:169], v[200:203], v[62:65]
	v_mfma_f32_16x16x32_bf16 v[58:61], v[174:177], v[200:203], v[58:61]
	v_mfma_f32_16x16x32_bf16 v[54:57], v[166:169], v[208:211], v[54:57]
	v_mfma_f32_16x16x32_bf16 v[46:49], v[174:177], v[208:211], v[46:49]
	v_mfma_f32_16x16x32_bf16 v[38:41], v[166:169], v[216:219], v[38:41]
	v_mfma_f32_16x16x32_bf16 v[30:33], v[174:177], v[216:219], v[30:33]
	v_mfma_f32_16x16x32_bf16 v[22:25], v[166:169], v[224:227], v[22:25]
	v_mfma_f32_16x16x32_bf16 v[14:17], v[174:177], v[224:227], v[14:17]
	v_mfma_f32_16x16x32_bf16 v[50:53], v[178:181], v[196:199], 0
	v_mfma_f32_16x16x32_bf16 v[42:45], v[188:191], v[196:199], 0
	v_mfma_f32_16x16x32_bf16 v[34:37], v[178:181], v[204:207], 0
	v_mfma_f32_16x16x32_bf16 v[26:29], v[188:191], v[204:207], 0
	v_mfma_f32_16x16x32_bf16 v[18:21], v[178:181], v[212:215], 0
	v_mfma_f32_16x16x32_bf16 v[10:13], v[188:191], v[212:215], 0
	v_mfma_f32_16x16x32_bf16 v[6:9], v[178:181], v[220:223], 0
	v_mfma_f32_16x16x32_bf16 v[2:5], v[188:191], v[220:223], 0
	v_mfma_f32_16x16x32_bf16 v[50:53], v[184:187], v[200:203], v[50:53]
	v_mfma_f32_16x16x32_bf16 v[42:45], v[192:195], v[200:203], v[42:45]
	v_mfma_f32_16x16x32_bf16 v[34:37], v[184:187], v[208:211], v[34:37]
	v_mfma_f32_16x16x32_bf16 v[26:29], v[192:195], v[208:211], v[26:29]
	v_mfma_f32_16x16x32_bf16 v[18:21], v[184:187], v[216:219], v[18:21]
	v_mfma_f32_16x16x32_bf16 v[10:13], v[192:195], v[216:219], v[10:13]
	v_mfma_f32_16x16x32_bf16 v[6:9], v[184:187], v[224:227], v[6:9]
	v_mfma_f32_16x16x32_bf16 v[2:5], v[192:195], v[224:227], v[2:5]
	s_barrier
	s_add_i32 s39, 0, 0x18000
	s_add_i32 s40, 0, 0x1c000
	v_add_u32_e32 v174, s39, v139
	v_add_u32_e32 v192, s40, v139
	ds_read_b128 v[160:163], v174
	ds_read_b128 v[166:169], v174 offset:1024
	ds_read_b128 v[170:173], v174 offset:2048
	ds_read_b128 v[174:177], v174 offset:3072
	ds_read_b128 v[178:181], v192
	ds_read_b128 v[184:187], v192 offset:1024
	ds_read_b128 v[188:191], v192 offset:2048
	ds_read_b128 v[192:195], v192 offset:3072
	s_add_u32 s12, s18, 0x44000
	s_addc_u32 s13, s19, 0
	s_mov_b32 m0, s25
	v_lshl_add_u64 v[236:237], s[12:13], 0, v[130:131]
	ds_read_b128 v[196:199], v165 offset:32768
	ds_read_b128 v[200:203], v165 offset:33792
	ds_read_b128 v[204:207], v165 offset:34816
	ds_read_b128 v[208:211], v165 offset:35840
	ds_read_b128 v[212:215], v165 offset:36864
	ds_read_b128 v[216:219], v165 offset:37888
	ds_read_b128 v[220:223], v165 offset:38912
	ds_read_b128 v[224:227], v165 offset:39936
	global_load_lds_dwordx4 v[236:237], off
	s_mov_b32 m0, s26
	v_lshl_add_u64 v[236:237], s[12:13], 0, v[134:135]
	global_load_lds_dwordx4 v[236:237], off
	s_waitcnt vmcnt(8)
	s_waitcnt lgkmcnt(0)
	s_barrier
	v_mfma_f32_16x16x32_bf16 v[126:129], v[160:163], v[196:199], v[126:129]
	v_mfma_f32_16x16x32_bf16 v[122:125], v[170:173], v[196:199], v[122:125]
	v_mfma_f32_16x16x32_bf16 v[118:121], v[160:163], v[204:207], v[118:121]
	v_mfma_f32_16x16x32_bf16 v[110:113], v[170:173], v[204:207], v[110:113]
	v_mfma_f32_16x16x32_bf16 v[102:105], v[160:163], v[212:215], v[102:105]
	v_mfma_f32_16x16x32_bf16 v[94:97], v[170:173], v[212:215], v[94:97]
	v_mfma_f32_16x16x32_bf16 v[86:89], v[160:163], v[220:223], v[86:89]
	v_mfma_f32_16x16x32_bf16 v[78:81], v[170:173], v[220:223], v[78:81]
	v_mfma_f32_16x16x32_bf16 v[126:129], v[166:169], v[200:203], v[126:129]
	v_mfma_f32_16x16x32_bf16 v[122:125], v[174:177], v[200:203], v[122:125]
	v_mfma_f32_16x16x32_bf16 v[118:121], v[166:169], v[208:211], v[118:121]
	v_mfma_f32_16x16x32_bf16 v[110:113], v[174:177], v[208:211], v[110:113]
	v_mfma_f32_16x16x32_bf16 v[102:105], v[166:169], v[216:219], v[102:105]
	v_mfma_f32_16x16x32_bf16 v[94:97], v[174:177], v[216:219], v[94:97]
	v_mfma_f32_16x16x32_bf16 v[86:89], v[166:169], v[224:227], v[86:89]
	v_mfma_f32_16x16x32_bf16 v[78:81], v[174:177], v[224:227], v[78:81]
	v_mfma_f32_16x16x32_bf16 v[114:117], v[178:181], v[196:199], v[114:117]
	v_mfma_f32_16x16x32_bf16 v[106:109], v[188:191], v[196:199], v[106:109]
	v_mfma_f32_16x16x32_bf16 v[98:101], v[178:181], v[204:207], v[98:101]
	v_mfma_f32_16x16x32_bf16 v[90:93], v[188:191], v[204:207], v[90:93]
	v_mfma_f32_16x16x32_bf16 v[82:85], v[178:181], v[212:215], v[82:85]
	v_mfma_f32_16x16x32_bf16 v[74:77], v[188:191], v[212:215], v[74:77]
	v_mfma_f32_16x16x32_bf16 v[70:73], v[178:181], v[220:223], v[70:73]
	v_mfma_f32_16x16x32_bf16 v[66:69], v[188:191], v[220:223], v[66:69]
	v_mfma_f32_16x16x32_bf16 v[114:117], v[184:187], v[200:203], v[114:117]
	v_mfma_f32_16x16x32_bf16 v[106:109], v[192:195], v[200:203], v[106:109]
	v_mfma_f32_16x16x32_bf16 v[98:101], v[184:187], v[208:211], v[98:101]
	v_mfma_f32_16x16x32_bf16 v[90:93], v[192:195], v[208:211], v[90:93]
	v_mfma_f32_16x16x32_bf16 v[82:85], v[184:187], v[216:219], v[82:85]
	v_mfma_f32_16x16x32_bf16 v[74:77], v[192:195], v[216:219], v[74:77]
	v_mfma_f32_16x16x32_bf16 v[70:73], v[184:187], v[224:227], v[70:73]
	v_mfma_f32_16x16x32_bf16 v[66:69], v[192:195], v[224:227], v[66:69]
	s_barrier
; #define PG8_STAGE(bufoff, gbase, voff) do { _Pragma("unroll") for (int _i = 0; _i < 2; ++_i) \
;         __builtin_amdgcn_global_load_lds((const unsigned*)((const char*)(gbase) + (voff)[_i]), (LAS unsigned*)(lds + (bufoff) + ldsw + _i * 8192), 16, 0, 0); } while (0)
; #define PG8_LDA(dst, b, h) do { _Pragma("unroll") for (int m = 0; m < 4; ++m) _Pragma("unroll") for (int k = 0; k < 2; ++k) dst[m][k] = *(const LAS bf16x8*)(lds + PG8_SA(b, h) + aoff + m * 2048 + k * 1024); } while (0)
; #define PG8_LDB(dst, b, h) do { _Pragma("unroll") for (int n = 0; n < 2; ++n) _Pragma("unroll") for (int k = 0; k < 2; ++k) dst[n][k] = *(const LAS bf16x8*)(lds + PG8_SB(b, h) + boff + n * 2048 + k * 1024); } while (0)
; #define PG8_BAR __builtin_amdgcn_s_barrier()
; template <class Epi, bool ALIGN_EPI = PG8_ALIGN, bool SP2 = PG8_SP2>
; __device__ __forceinline__ void gemm_phase(LAS uchar* lds, const Gemm g, const StaticOrder& S, const Epi& E) {
;     ...
;         for (int t = tb; t < tb + tblk; t += 2) {
;             const bool last = (t == nt - 2);
;             const char* a1 = cA + (size_t)(t + 1) * kstep;
;             const char* a2 = last ? nA : cA + (size_t)(t + 2) * kstep; const char* b2 = last ? nB : cB + (size_t)(t + 2) * kstep;
;             const char* a3 = a2 + kstep; const char* b3 = b2 + kstep;
;             if constexpr (SP2) {
;             PG8_LDB(B0, 0, 0); PG8_LDB(B1, 0, 1); PG8_SCHED; PG8_LDA(At, 0, 0); PG8_STAGE(PG8_SA(1, 1), a1 + hstepA, voffA);
;             PG8_WAIT_V(8); PG8_WAIT_L(0); PG8_BAR; PG8_MMA(0, 0, At, B0); PG8_MMA(0, 1, At, B1); PG8_BAR; PG8_SCHED;
;             PG8_LDA(At, 0, 1); PG8_STAGE(PG8_SB(0, 0), b2, voffB); PG8_STAGE(PG8_SB(0, 1), b2 + hstepB, voffB); PG8_STAGE(PG8_SA(0, 0), a2, voffA);
;             PG8_WAIT_V(8); PG8_WAIT_L(0); PG8_BAR; PG8_MMA(1, 0, At, B0); PG8_MMA(1, 1, At, B1); PG8_BAR; PG8_SCHED;
;             PG8_LDB(B0, 1, 0); PG8_LDB(B1, 1, 1); PG8_SCHED; PG8_LDA(At, 1, 0); PG8_STAGE(PG8_SA(0, 1), a2 + hstepA, voffA);
;             PG8_WAIT_V(8); PG8_WAIT_L(0); PG8_BAR; PG8_MMA(0, 0, At, B0); PG8_MMA(0, 1, At, B1); PG8_BAR; PG8_SCHED;
;             PG8_LDA(At, 1, 1); PG8_STAGE(PG8_SB(1, 0), b3, voffB); PG8_STAGE(PG8_SB(1, 1), b3 + hstepB, voffB); PG8_STAGE(PG8_SA(1, 0), a3, voffA);
;             PG8_WAIT_V(8); PG8_WAIT_L(0); PG8_BAR; PG8_MMA(1, 0, At, B0); PG8_MMA(1, 1, At, B1); PG8_BAR; PG8_SCHED;
	s_add_i32 s12, s39, s22
	v_lshl_add_u64 v[228:229], v[228:229], 0, s[84:85]
	s_mov_b32 m0, s12
	ds_read_b128 v[196:199], v165 offset:49152
	ds_read_b128 v[200:203], v165 offset:50176
	ds_read_b128 v[204:207], v165 offset:51200
	ds_read_b128 v[208:211], v165 offset:52224
	ds_read_b128 v[212:215], v165 offset:53248
	ds_read_b128 v[216:219], v165 offset:54272
	ds_read_b128 v[220:223], v165 offset:55296
	ds_read_b128 v[224:227], v165 offset:56320
	global_load_lds_dwordx4 v[228:229], off
	s_add_i32 m0, s12, 0x2000
	s_add_u32 s12, s16, 0x44080
	v_lshl_add_u64 v[228:229], v[230:231], 0, s[84:85]
	s_addc_u32 s13, s17, 0
	s_add_i32 s16, s40, s22
	global_load_lds_dwordx4 v[228:229], off
	s_mov_b32 m0, s16
	v_lshl_add_u64 v[228:229], s[12:13], 0, v[132:133]
	global_load_lds_dwordx4 v[228:229], off
	s_add_i32 m0, s16, 0x2000
	v_lshl_add_u64 v[228:229], s[12:13], 0, v[152:153]
	global_load_lds_dwordx4 v[228:229], off
	s_mov_b32 m0, s27
	v_lshl_add_u64 v[228:229], v[232:233], 0, s[84:85]
	global_load_lds_dwordx4 v[228:229], off
	s_mov_b32 m0, s28
	v_lshl_add_u64 v[228:229], v[234:235], 0, s[84:85]
	global_load_lds_dwordx4 v[228:229], off
	s_waitcnt vmcnt(8)
	s_waitcnt lgkmcnt(0)
	s_barrier
	v_mfma_f32_16x16x32_bf16 v[62:65], v[160:163], v[196:199], v[62:65]
	v_mfma_f32_16x16x32_bf16 v[58:61], v[170:173], v[196:199], v[58:61]
	v_mfma_f32_16x16x32_bf16 v[54:57], v[160:163], v[204:207], v[54:57]
	v_mfma_f32_16x16x32_bf16 v[46:49], v[170:173], v[204:207], v[46:49]
	v_mfma_f32_16x16x32_bf16 v[38:41], v[160:163], v[212:215], v[38:41]
	v_mfma_f32_16x16x32_bf16 v[30:33], v[170:173], v[212:215], v[30:33]
	v_mfma_f32_16x16x32_bf16 v[22:25], v[160:163], v[220:223], v[22:25]
	v_mfma_f32_16x16x32_bf16 v[14:17], v[170:173], v[220:223], v[14:17]
	v_mfma_f32_16x16x32_bf16 v[62:65], v[166:169], v[200:203], v[62:65]
	v_mfma_f32_16x16x32_bf16 v[58:61], v[174:177], v[200:203], v[58:61]
	v_mfma_f32_16x16x32_bf16 v[54:57], v[166:169], v[208:211], v[54:57]
	v_mfma_f32_16x16x32_bf16 v[46:49], v[174:177], v[208:211], v[46:49]
	v_mfma_f32_16x16x32_bf16 v[38:41], v[166:169], v[216:219], v[38:41]
	v_mfma_f32_16x16x32_bf16 v[30:33], v[174:177], v[216:219], v[30:33]
	v_mfma_f32_16x16x32_bf16 v[22:25], v[166:169], v[224:227], v[22:25]
	v_mfma_f32_16x16x32_bf16 v[14:17], v[174:177], v[224:227], v[14:17]
	v_mfma_f32_16x16x32_bf16 v[50:53], v[178:181], v[196:199], v[50:53]
	v_mfma_f32_16x16x32_bf16 v[42:45], v[188:191], v[196:199], v[42:45]
	v_mfma_f32_16x16x32_bf16 v[34:37], v[178:181], v[204:207], v[34:37]
	v_mfma_f32_16x16x32_bf16 v[26:29], v[188:191], v[204:207], v[26:29]
	v_mfma_f32_16x16x32_bf16 v[18:21], v[178:181], v[212:215], v[18:21]
	v_mfma_f32_16x16x32_bf16 v[10:13], v[188:191], v[212:215], v[10:13]
	v_mfma_f32_16x16x32_bf16 v[6:9], v[178:181], v[220:223], v[6:9]
	v_mfma_f32_16x16x32_bf16 v[2:5], v[188:191], v[220:223], v[2:5]
	v_mfma_f32_16x16x32_bf16 v[50:53], v[184:187], v[200:203], v[50:53]
	v_mfma_f32_16x16x32_bf16 v[42:45], v[192:195], v[200:203], v[42:45]
	v_mfma_f32_16x16x32_bf16 v[34:37], v[184:187], v[208:211], v[34:37]
	v_mfma_f32_16x16x32_bf16 v[26:29], v[192:195], v[208:211], v[26:29]
	v_mfma_f32_16x16x32_bf16 v[18:21], v[184:187], v[216:219], v[18:21]
	v_mfma_f32_16x16x32_bf16 v[10:13], v[192:195], v[216:219], v[10:13]
	v_mfma_f32_16x16x32_bf16 v[6:9], v[184:187], v[224:227], v[6:9]
	v_mfma_f32_16x16x32_bf16 v[2:5], v[192:195], v[224:227], v[2:5]
	s_barrier
	s_add_i32 s38, s38, 2
	s_add_u32 s36, s36, 0x100
	s_addc_u32 s37, s37, 0
	s_cmp_gt_u32 s38, 13
	s_mov_b64 s[12:13], s[14:15]
.LBB0_837:
	s_add_u32 s14, s12, 0x100
	s_addc_u32 s15, s13, 0
	s_add_i32 s39, 0, 0x10000
	s_cmp_eq_u32 s38, 12
	s_cselect_b32 s19, s5, s15
	s_cselect_b32 s18, s4, s14
	s_cselect_b32 s17, s11, s37
	s_cselect_b32 s16, s10, s36
	s_add_i32 s40, 0, 0x14000
	v_add_u32_e32 v174, s39, v139
	v_add_u32_e32 v192, s40, v139
	ds_read_b128 v[160:163], v174
	ds_read_b128 v[166:169], v174 offset:1024
	ds_read_b128 v[170:173], v174 offset:2048
	ds_read_b128 v[174:177], v174 offset:3072
	ds_read_b128 v[178:181], v192
	ds_read_b128 v[184:187], v192 offset:1024
	ds_read_b128 v[188:191], v192 offset:2048
	ds_read_b128 v[192:195], v192 offset:3072
	v_lshl_add_u64 v[228:229], s[12:13], 0, v[156:157]
	s_add_i32 m0, s23, 0xc000
	ds_read_b128 v[196:199], v165
	ds_read_b128 v[200:203], v165 offset:1024
	ds_read_b128 v[204:207], v165 offset:2048
	ds_read_b128 v[208:211], v165 offset:3072
	ds_read_b128 v[212:215], v165 offset:4096
	ds_read_b128 v[216:219], v165 offset:5120
	ds_read_b128 v[220:223], v165 offset:6144
	ds_read_b128 v[224:227], v165 offset:7168
	global_load_lds_dwordx4 v[228:229], off
	s_add_i32 m0, s23, 0xe000
	v_lshl_add_u64 v[228:229], s[12:13], 0, v[158:159]
	global_load_lds_dwordx4 v[228:229], off
	s_waitcnt vmcnt(8)
	s_waitcnt lgkmcnt(0)
	s_barrier
; #define PG8_STAGE(bufoff, gbase, voff) do { _Pragma("unroll") for (int _i = 0; _i < 2; ++_i) \
;         __builtin_amdgcn_global_load_lds((const unsigned*)((const char*)(gbase) + (voff)[_i]), (LAS unsigned*)(lds + (bufoff) + ldsw + _i * 8192), 16, 0, 0); } while (0)
; #define PG8_LDA(dst, b, h) do { _Pragma("unroll") for (int m = 0; m < 4; ++m) _Pragma("unroll") for (int k = 0; k < 2; ++k) dst[m][k] = *(const LAS bf16x8*)(lds + PG8_SA(b, h) + aoff + m * 2048 + k * 1024); } while (0)
; #define PG8_MMA(ai, bj, At, Bt) do { __builtin_amdgcn_s_setprio(1); _Pragma("unroll") for (int m = 0; m < 4; ++m) _Pragma("unroll") for (int n = 0; n < 2; ++n) _Pragma("unroll") for (int k = 0; k < 2; ++k) \
;         acc[ai][bj][m][n] = __builtin_amdgcn_mfma_f32_16x16x32_bf16(Bt[n][k], At[m][k], acc[ai][bj][m][n], 0, 0, 0); __builtin_amdgcn_s_setprio(0); } while (0)
; #define PG8_WAIT_V(n) asm volatile("s_waitcnt vmcnt(" #n ")" ::: "memory")
; #define PG8_WAIT_L(n) asm volatile("s_waitcnt lgkmcnt(" #n ")" ::: "memory")
; #define PG8_BAR __builtin_amdgcn_s_barrier()
; #define PG8_SCHED __builtin_amdgcn_sched_barrier(0)
; template <class Epi, bool ALIGN_EPI = PG8_ALIGN, bool SP2 = PG8_SP2>
; __device__ __forceinline__ void gemm_phase(LAS uchar* lds, const Gemm g, const StaticOrder& S, const Epi& E) {
;     ...
;             PG8_WAIT_V(8); PG8_WAIT_L(0); PG8_BAR; PG8_MMA(0, 0, At, B0); PG8_MMA(0, 1, At, B1); PG8_BAR; PG8_SCHED;
;             PG8_LDA(At, 0, 1); PG8_STAGE(PG8_SB(0, 0), b2, voffB); PG8_STAGE(PG8_SB(0, 1), b2 + hstepB, voffB); PG8_STAGE(PG8_SA(0, 0), a2, voffA);
;             PG8_WAIT_V(8); PG8_WAIT_L(0); PG8_BAR; PG8_MMA(1, 0, At, B0); PG8_MMA(1, 1, At, B1); PG8_BAR; PG8_SCHED;
	v_mfma_f32_16x16x32_bf16 v[126:129], v[160:163], v[196:199], v[126:129]
	v_mfma_f32_16x16x32_bf16 v[122:125], v[170:173], v[196:199], v[122:125]
	v_mfma_f32_16x16x32_bf16 v[118:121], v[160:163], v[204:207], v[118:121]
	v_mfma_f32_16x16x32_bf16 v[110:113], v[170:173], v[204:207], v[110:113]
	v_mfma_f32_16x16x32_bf16 v[102:105], v[160:163], v[212:215], v[102:105]
	v_mfma_f32_16x16x32_bf16 v[94:97], v[170:173], v[212:215], v[94:97]
	v_mfma_f32_16x16x32_bf16 v[86:89], v[160:163], v[220:223], v[86:89]
	v_mfma_f32_16x16x32_bf16 v[78:81], v[170:173], v[220:223], v[78:81]
	v_mfma_f32_16x16x32_bf16 v[126:129], v[166:169], v[200:203], v[126:129]
	v_mfma_f32_16x16x32_bf16 v[122:125], v[174:177], v[200:203], v[122:125]
	v_mfma_f32_16x16x32_bf16 v[118:121], v[166:169], v[208:211], v[118:121]
	v_mfma_f32_16x16x32_bf16 v[110:113], v[174:177], v[208:211], v[110:113]
	v_mfma_f32_16x16x32_bf16 v[102:105], v[166:169], v[216:219], v[102:105]
	v_mfma_f32_16x16x32_bf16 v[94:97], v[174:177], v[216:219], v[94:97]
	v_mfma_f32_16x16x32_bf16 v[86:89], v[166:169], v[224:227], v[86:89]
	v_mfma_f32_16x16x32_bf16 v[78:81], v[174:177], v[224:227], v[78:81]
	v_mfma_f32_16x16x32_bf16 v[114:117], v[178:181], v[196:199], v[114:117]
	v_mfma_f32_16x16x32_bf16 v[106:109], v[188:191], v[196:199], v[106:109]
	v_mfma_f32_16x16x32_bf16 v[98:101], v[178:181], v[204:207], v[98:101]
	v_mfma_f32_16x16x32_bf16 v[90:93], v[188:191], v[204:207], v[90:93]
	v_mfma_f32_16x16x32_bf16 v[82:85], v[178:181], v[212:215], v[82:85]
	v_mfma_f32_16x16x32_bf16 v[74:77], v[188:191], v[212:215], v[74:77]
	v_mfma_f32_16x16x32_bf16 v[70:73], v[178:181], v[220:223], v[70:73]
	v_mfma_f32_16x16x32_bf16 v[66:69], v[188:191], v[220:223], v[66:69]
	v_mfma_f32_16x16x32_bf16 v[114:117], v[184:187], v[200:203], v[114:117]
	v_mfma_f32_16x16x32_bf16 v[106:109], v[192:195], v[200:203], v[106:109]
	v_mfma_f32_16x16x32_bf16 v[98:101], v[184:187], v[208:211], v[98:101]
	v_mfma_f32_16x16x32_bf16 v[90:93], v[192:195], v[208:211], v[90:93]
	v_mfma_f32_16x16x32_bf16 v[82:85], v[184:187], v[216:219], v[82:85]
	v_mfma_f32_16x16x32_bf16 v[74:77], v[192:195], v[216:219], v[74:77]
	v_mfma_f32_16x16x32_bf16 v[70:73], v[184:187], v[224:227], v[70:73]
	v_mfma_f32_16x16x32_bf16 v[66:69], v[192:195], v[224:227], v[66:69]
	s_barrier
	s_add_i32 s12, s39, s22
	v_lshl_add_u64 v[228:229], s[16:17], 0, v[132:133]
	s_mov_b32 m0, s12
	ds_read_b128 v[196:199], v165 offset:16384
	ds_read_b128 v[200:203], v165 offset:17408
	ds_read_b128 v[204:207], v165 offset:18432
	ds_read_b128 v[208:211], v165 offset:19456
	ds_read_b128 v[212:215], v165 offset:20480
	ds_read_b128 v[216:219], v165 offset:21504
	ds_read_b128 v[220:223], v165 offset:22528
	ds_read_b128 v[224:227], v165 offset:23552
	global_load_lds_dwordx4 v[228:229], off
	s_add_i32 m0, s12, 0x2000
	s_add_u32 s12, s16, 0x44000
	v_lshl_add_u64 v[230:231], s[16:17], 0, v[152:153]
	s_addc_u32 s13, s17, 0
	s_add_i32 s39, s40, s22
	global_load_lds_dwordx4 v[230:231], off
	v_lshl_add_u64 v[232:233], s[12:13], 0, v[132:133]
	s_mov_b32 m0, s39
	global_load_lds_dwordx4 v[232:233], off
	s_add_i32 m0, s39, 0x2000
	v_lshl_add_u64 v[232:233], s[12:13], 0, v[152:153]
	global_load_lds_dwordx4 v[232:233], off
	s_mov_b32 m0, s23
	v_lshl_add_u64 v[232:233], s[18:19], 0, v[130:131]
	global_load_lds_dwordx4 v[232:233], off
	s_mov_b32 m0, s24
	v_lshl_add_u64 v[234:235], s[18:19], 0, v[134:135]
	global_load_lds_dwordx4 v[234:235], off
	s_waitcnt vmcnt(8)
	s_waitcnt lgkmcnt(0)
	s_barrier
	v_mfma_f32_16x16x32_bf16 v[62:65], v[160:163], v[196:199], v[62:65]
	v_mfma_f32_16x16x32_bf16 v[58:61], v[170:173], v[196:199], v[58:61]
	v_mfma_f32_16x16x32_bf16 v[54:57], v[160:163], v[204:207], v[54:57]
	v_mfma_f32_16x16x32_bf16 v[46:49], v[170:173], v[204:207], v[46:49]
	v_mfma_f32_16x16x32_bf16 v[38:41], v[160:163], v[212:215], v[38:41]
	v_mfma_f32_16x16x32_bf16 v[30:33], v[170:173], v[212:215], v[30:33]
	v_mfma_f32_16x16x32_bf16 v[22:25], v[160:163], v[220:223], v[22:25]
	v_mfma_f32_16x16x32_bf16 v[14:17], v[170:173], v[220:223], v[14:17]
	v_mfma_f32_16x16x32_bf16 v[62:65], v[166:169], v[200:203], v[62:65]
	v_mfma_f32_16x16x32_bf16 v[58:61], v[174:177], v[200:203], v[58:61]
	v_mfma_f32_16x16x32_bf16 v[54:57], v[166:169], v[208:211], v[54:57]
	v_mfma_f32_16x16x32_bf16 v[46:49], v[174:177], v[208:211], v[46:49]
	v_mfma_f32_16x16x32_bf16 v[38:41], v[166:169], v[216:219], v[38:41]
	v_mfma_f32_16x16x32_bf16 v[30:33], v[174:177], v[216:219], v[30:33]
	v_mfma_f32_16x16x32_bf16 v[22:25], v[166:169], v[224:227], v[22:25]
	v_mfma_f32_16x16x32_bf16 v[14:17], v[174:177], v[224:227], v[14:17]
	v_mfma_f32_16x16x32_bf16 v[50:53], v[178:181], v[196:199], v[50:53]
	v_mfma_f32_16x16x32_bf16 v[42:45], v[188:191], v[196:199], v[42:45]
	v_mfma_f32_16x16x32_bf16 v[34:37], v[178:181], v[204:207], v[34:37]
	v_mfma_f32_16x16x32_bf16 v[26:29], v[188:191], v[204:207], v[26:29]
	v_mfma_f32_16x16x32_bf16 v[18:21], v[178:181], v[212:215], v[18:21]
	v_mfma_f32_16x16x32_bf16 v[10:13], v[188:191], v[212:215], v[10:13]
	v_mfma_f32_16x16x32_bf16 v[6:9], v[178:181], v[220:223], v[6:9]
	v_mfma_f32_16x16x32_bf16 v[2:5], v[188:191], v[220:223], v[2:5]
	v_mfma_f32_16x16x32_bf16 v[50:53], v[184:187], v[200:203], v[50:53]
	v_mfma_f32_16x16x32_bf16 v[42:45], v[192:195], v[200:203], v[42:45]
	v_mfma_f32_16x16x32_bf16 v[34:37], v[184:187], v[208:211], v[34:37]
	v_mfma_f32_16x16x32_bf16 v[26:29], v[192:195], v[208:211], v[26:29]
	v_mfma_f32_16x16x32_bf16 v[18:21], v[184:187], v[216:219], v[18:21]
	v_mfma_f32_16x16x32_bf16 v[10:13], v[192:195], v[216:219], v[10:13]
	v_mfma_f32_16x16x32_bf16 v[6:9], v[184:187], v[224:227], v[6:9]
	v_mfma_f32_16x16x32_bf16 v[2:5], v[192:195], v[224:227], v[2:5]
	s_barrier
; #define PG8_STAGE(bufoff, gbase, voff) do { _Pragma("unroll") for (int _i = 0; _i < 2; ++_i) \
;         __builtin_amdgcn_global_load_lds((const unsigned*)((const char*)(gbase) + (voff)[_i]), (LAS unsigned*)(lds + (bufoff) + ldsw + _i * 8192), 16, 0, 0); } while (0)
; #define PG8_LDA(dst, b, h) do { _Pragma("unroll") for (int m = 0; m < 4; ++m) _Pragma("unroll") for (int k = 0; k < 2; ++k) dst[m][k] = *(const LAS bf16x8*)(lds + PG8_SA(b, h) + aoff + m * 2048 + k * 1024); } while (0)
; #define PG8_LDB(dst, b, h) do { _Pragma("unroll") for (int n = 0; n < 2; ++n) _Pragma("unroll") for (int k = 0; k < 2; ++k) dst[n][k] = *(const LAS bf16x8*)(lds + PG8_SB(b, h) + boff + n * 2048 + k * 1024); } while (0)
; #define PG8_MMA(ai, bj, At, Bt) do { __builtin_amdgcn_s_setprio(1); _Pragma("unroll") for (int m = 0; m < 4; ++m) _Pragma("unroll") for (int n = 0; n < 2; ++n) _Pragma("unroll") for (int k = 0; k < 2; ++k) \
;         acc[ai][bj][m][n] = __builtin_amdgcn_mfma_f32_16x16x32_bf16(Bt[n][k], At[m][k], acc[ai][bj][m][n], 0, 0, 0); __builtin_amdgcn_s_setprio(0); } while (0)
; #define PG8_WAIT_V(n) asm volatile("s_waitcnt vmcnt(" #n ")" ::: "memory")
; #define PG8_WAIT_L(n) asm volatile("s_waitcnt lgkmcnt(" #n ")" ::: "memory")
; #define PG8_BAR __builtin_amdgcn_s_barrier()
; #define PG8_SCHED __builtin_amdgcn_sched_barrier(0)
; template <class Epi, bool ALIGN_EPI = PG8_ALIGN, bool SP2 = PG8_SP2>
; __device__ __forceinline__ void gemm_phase(LAS uchar* lds, const Gemm g, const StaticOrder& S, const Epi& E) {
;     ...
;             PG8_LDB(B0, 1, 0); PG8_LDB(B1, 1, 1); PG8_SCHED; PG8_LDA(At, 1, 0); PG8_STAGE(PG8_SA(0, 1), a2 + hstepA, voffA);
;             PG8_WAIT_V(8); PG8_WAIT_L(0); PG8_BAR; PG8_MMA(0, 0, At, B0); PG8_MMA(0, 1, At, B1); PG8_BAR; PG8_SCHED;
;             PG8_LDA(At, 1, 1); PG8_STAGE(PG8_SB(1, 0), b3, voffB); PG8_STAGE(PG8_SB(1, 1), b3 + hstepB, voffB); PG8_STAGE(PG8_SA(1, 0), a3, voffA);
;             PG8_WAIT_V(8); PG8_WAIT_L(0); PG8_BAR; PG8_MMA(1, 0, At, B0); PG8_MMA(1, 1, At, B1); PG8_BAR; PG8_SCHED;
;     ...
;         if constexpr (ALIGN_EPI) { if (wr == 0) PG8_BAR; }
	s_add_i32 s39, 0, 0x18000
	s_add_i32 s40, 0, 0x1c000
	v_add_u32_e32 v174, s39, v139
	v_add_u32_e32 v192, s40, v139
	ds_read_b128 v[160:163], v174
	ds_read_b128 v[166:169], v174 offset:1024
	ds_read_b128 v[170:173], v174 offset:2048
	ds_read_b128 v[174:177], v174 offset:3072
	ds_read_b128 v[178:181], v192
	ds_read_b128 v[184:187], v192 offset:1024
	ds_read_b128 v[188:191], v192 offset:2048
	ds_read_b128 v[192:195], v192 offset:3072
	s_add_u32 s12, s18, 0x44000
	s_addc_u32 s13, s19, 0
	s_mov_b32 m0, s25
	v_lshl_add_u64 v[236:237], s[12:13], 0, v[130:131]
	ds_read_b128 v[196:199], v165 offset:32768
	ds_read_b128 v[200:203], v165 offset:33792
	ds_read_b128 v[204:207], v165 offset:34816
	ds_read_b128 v[208:211], v165 offset:35840
	ds_read_b128 v[212:215], v165 offset:36864
	ds_read_b128 v[216:219], v165 offset:37888
	ds_read_b128 v[220:223], v165 offset:38912
	ds_read_b128 v[224:227], v165 offset:39936
	global_load_lds_dwordx4 v[236:237], off
	s_mov_b32 m0, s26
	v_lshl_add_u64 v[236:237], s[12:13], 0, v[134:135]
	global_load_lds_dwordx4 v[236:237], off
	s_waitcnt vmcnt(8)
	s_waitcnt lgkmcnt(0)
	s_barrier
	v_mfma_f32_16x16x32_bf16 v[126:129], v[160:163], v[196:199], v[126:129]
	v_mfma_f32_16x16x32_bf16 v[122:125], v[170:173], v[196:199], v[122:125]
	v_mfma_f32_16x16x32_bf16 v[118:121], v[160:163], v[204:207], v[118:121]
	v_mfma_f32_16x16x32_bf16 v[110:113], v[170:173], v[204:207], v[110:113]
	v_mfma_f32_16x16x32_bf16 v[102:105], v[160:163], v[212:215], v[102:105]
	v_mfma_f32_16x16x32_bf16 v[94:97], v[170:173], v[212:215], v[94:97]
	v_mfma_f32_16x16x32_bf16 v[86:89], v[160:163], v[220:223], v[86:89]
	v_mfma_f32_16x16x32_bf16 v[78:81], v[170:173], v[220:223], v[78:81]
	v_mfma_f32_16x16x32_bf16 v[126:129], v[166:169], v[200:203], v[126:129]
	v_mfma_f32_16x16x32_bf16 v[122:125], v[174:177], v[200:203], v[122:125]
	v_mfma_f32_16x16x32_bf16 v[118:121], v[166:169], v[208:211], v[118:121]
	v_mfma_f32_16x16x32_bf16 v[110:113], v[174:177], v[208:211], v[110:113]
	v_mfma_f32_16x16x32_bf16 v[102:105], v[166:169], v[216:219], v[102:105]
	v_mfma_f32_16x16x32_bf16 v[94:97], v[174:177], v[216:219], v[94:97]
	v_mfma_f32_16x16x32_bf16 v[86:89], v[166:169], v[224:227], v[86:89]
	v_mfma_f32_16x16x32_bf16 v[78:81], v[174:177], v[224:227], v[78:81]
	v_mfma_f32_16x16x32_bf16 v[114:117], v[178:181], v[196:199], v[114:117]
	v_mfma_f32_16x16x32_bf16 v[106:109], v[188:191], v[196:199], v[106:109]
	v_mfma_f32_16x16x32_bf16 v[98:101], v[178:181], v[204:207], v[98:101]
	v_mfma_f32_16x16x32_bf16 v[90:93], v[188:191], v[204:207], v[90:93]
	v_mfma_f32_16x16x32_bf16 v[82:85], v[178:181], v[212:215], v[82:85]
	v_mfma_f32_16x16x32_bf16 v[74:77], v[188:191], v[212:215], v[74:77]
	v_mfma_f32_16x16x32_bf16 v[70:73], v[178:181], v[220:223], v[70:73]
	v_mfma_f32_16x16x32_bf16 v[66:69], v[188:191], v[220:223], v[66:69]
	v_mfma_f32_16x16x32_bf16 v[114:117], v[184:187], v[200:203], v[114:117]
	v_mfma_f32_16x16x32_bf16 v[106:109], v[192:195], v[200:203], v[106:109]
	v_mfma_f32_16x16x32_bf16 v[98:101], v[184:187], v[208:211], v[98:101]
	v_mfma_f32_16x16x32_bf16 v[90:93], v[192:195], v[208:211], v[90:93]
	v_mfma_f32_16x16x32_bf16 v[82:85], v[184:187], v[216:219], v[82:85]
	v_mfma_f32_16x16x32_bf16 v[74:77], v[192:195], v[216:219], v[74:77]
	v_mfma_f32_16x16x32_bf16 v[70:73], v[184:187], v[224:227], v[70:73]
	v_mfma_f32_16x16x32_bf16 v[66:69], v[192:195], v[224:227], v[66:69]
	s_barrier
	s_add_i32 s12, s39, s22
	v_lshl_add_u64 v[228:229], v[228:229], 0, s[84:85]
	s_mov_b32 m0, s12
	ds_read_b128 v[196:199], v165 offset:49152
	ds_read_b128 v[200:203], v165 offset:50176
	ds_read_b128 v[204:207], v165 offset:51200
	ds_read_b128 v[208:211], v165 offset:52224
	ds_read_b128 v[212:215], v165 offset:53248
	ds_read_b128 v[216:219], v165 offset:54272
	ds_read_b128 v[220:223], v165 offset:55296
	ds_read_b128 v[224:227], v165 offset:56320
	global_load_lds_dwordx4 v[228:229], off
	s_add_i32 m0, s12, 0x2000
	s_add_u32 s12, s16, 0x44080
	v_lshl_add_u64 v[228:229], v[230:231], 0, s[84:85]
	s_addc_u32 s13, s17, 0
	s_add_i32 s16, s40, s22
	global_load_lds_dwordx4 v[228:229], off
	s_mov_b32 m0, s16
	v_lshl_add_u64 v[228:229], s[12:13], 0, v[132:133]
	global_load_lds_dwordx4 v[228:229], off
	s_add_i32 m0, s16, 0x2000
	v_lshl_add_u64 v[228:229], s[12:13], 0, v[152:153]
	global_load_lds_dwordx4 v[228:229], off
	s_mov_b32 m0, s27
	v_lshl_add_u64 v[228:229], v[232:233], 0, s[84:85]
	global_load_lds_dwordx4 v[228:229], off
	s_mov_b32 m0, s28
	v_lshl_add_u64 v[228:229], v[234:235], 0, s[84:85]
	global_load_lds_dwordx4 v[228:229], off
	s_waitcnt vmcnt(8)
	s_waitcnt lgkmcnt(0)
	s_barrier
	v_mfma_f32_16x16x32_bf16 v[62:65], v[160:163], v[196:199], v[62:65]
	v_mfma_f32_16x16x32_bf16 v[58:61], v[170:173], v[196:199], v[58:61]
	v_mfma_f32_16x16x32_bf16 v[54:57], v[160:163], v[204:207], v[54:57]
	v_mfma_f32_16x16x32_bf16 v[46:49], v[170:173], v[204:207], v[46:49]
	v_mfma_f32_16x16x32_bf16 v[38:41], v[160:163], v[212:215], v[38:41]
	v_mfma_f32_16x16x32_bf16 v[30:33], v[170:173], v[212:215], v[30:33]
	v_mfma_f32_16x16x32_bf16 v[22:25], v[160:163], v[220:223], v[22:25]
	v_mfma_f32_16x16x32_bf16 v[14:17], v[170:173], v[220:223], v[14:17]
	v_mfma_f32_16x16x32_bf16 v[62:65], v[166:169], v[200:203], v[62:65]
	v_mfma_f32_16x16x32_bf16 v[58:61], v[174:177], v[200:203], v[58:61]
	v_mfma_f32_16x16x32_bf16 v[54:57], v[166:169], v[208:211], v[54:57]
	v_mfma_f32_16x16x32_bf16 v[46:49], v[174:177], v[208:211], v[46:49]
	v_mfma_f32_16x16x32_bf16 v[38:41], v[166:169], v[216:219], v[38:41]
	v_mfma_f32_16x16x32_bf16 v[30:33], v[174:177], v[216:219], v[30:33]
	v_mfma_f32_16x16x32_bf16 v[22:25], v[166:169], v[224:227], v[22:25]
	v_mfma_f32_16x16x32_bf16 v[14:17], v[174:177], v[224:227], v[14:17]
	v_mfma_f32_16x16x32_bf16 v[50:53], v[178:181], v[196:199], v[50:53]
	v_mfma_f32_16x16x32_bf16 v[42:45], v[188:191], v[196:199], v[42:45]
	v_mfma_f32_16x16x32_bf16 v[34:37], v[178:181], v[204:207], v[34:37]
	v_mfma_f32_16x16x32_bf16 v[26:29], v[188:191], v[204:207], v[26:29]
	v_mfma_f32_16x16x32_bf16 v[18:21], v[178:181], v[212:215], v[18:21]
	v_mfma_f32_16x16x32_bf16 v[10:13], v[188:191], v[212:215], v[10:13]
	v_mfma_f32_16x16x32_bf16 v[6:9], v[178:181], v[220:223], v[6:9]
	v_mfma_f32_16x16x32_bf16 v[2:5], v[188:191], v[220:223], v[2:5]
	v_mfma_f32_16x16x32_bf16 v[50:53], v[184:187], v[200:203], v[50:53]
	v_mfma_f32_16x16x32_bf16 v[42:45], v[192:195], v[200:203], v[42:45]
	v_mfma_f32_16x16x32_bf16 v[34:37], v[184:187], v[208:211], v[34:37]
	v_mfma_f32_16x16x32_bf16 v[26:29], v[192:195], v[208:211], v[26:29]
	v_mfma_f32_16x16x32_bf16 v[18:21], v[184:187], v[216:219], v[18:21]
	v_mfma_f32_16x16x32_bf16 v[10:13], v[192:195], v[216:219], v[10:13]
	v_mfma_f32_16x16x32_bf16 v[6:9], v[184:187], v[224:227], v[6:9]
	v_mfma_f32_16x16x32_bf16 v[2:5], v[192:195], v[224:227], v[2:5]
	s_barrier
	s_add_i32 s38, s38, 2
	s_add_u32 s36, s36, 0x100
	s_addc_u32 s37, s37, 0
	s_cmp_gt_u32 s38, 13
	s_mov_b64 s[12:13], s[14:15]
	s_cbranch_scc0 .LBB0_837
	s_and_b64 vcc, exec, s[8:9]
	s_cbranch_vccz .LBB0_840
	s_barrier

; #define PG8_STAGE(bufoff, gbase, voff) do { _Pragma("unroll") for (int _i = 0; _i < 2; ++_i) \
;         __builtin_amdgcn_global_load_lds((const unsigned*)((const char*)(gbase) + (voff)[_i]), (LAS unsigned*)(lds + (bufoff) + ldsw + _i * 8192), 16, 0, 0); } while (0)
; #define PG8_LDA(dst, b, h) do { _Pragma("unroll") for (int m = 0; m < 4; ++m) _Pragma("unroll") for (int k = 0; k < 2; ++k) dst[m][k] = *(const LAS bf16x8*)(lds + PG8_SA(b, h) + aoff + m * 2048 + k * 1024); } while (0)
; #define PG8_MMA(ai, bj, At, Bt) do { __builtin_amdgcn_s_setprio(1); _Pragma("unroll") for (int m = 0; m < 4; ++m) _Pragma("unroll") for (int n = 0; n < 2; ++n) _Pragma("unroll") for (int k = 0; k < 2; ++k) \
;         acc[ai][bj][m][n] = __builtin_amdgcn_mfma_f32_16x16x32_bf16(Bt[n][k], At[m][k], acc[ai][bj][m][n], 0, 0, 0); __builtin_amdgcn_s_setprio(0); } while (0)
; #define PG8_WAIT_V(n) asm volatile("s_waitcnt vmcnt(" #n ")" ::: "memory")
; #define PG8_WAIT_L(n) asm volatile("s_waitcnt lgkmcnt(" #n ")" ::: "memory")
; #define PG8_BAR __builtin_amdgcn_s_barrier()
; #define PG8_SCHED __builtin_amdgcn_sched_barrier(0)
; template <class Epi, bool ALIGN_EPI = PG8_ALIGN, bool SP2 = PG8_SP2>
; __device__ __forceinline__ void gemm_phase(LAS uchar* lds, const Gemm g, const StaticOrder& S, const Epi& E) {
;     ...
;             PG8_WAIT_V(8); PG8_WAIT_L(0); PG8_BAR; PG8_MMA(0, 0, At, B0); PG8_MMA(0, 1, At, B1); PG8_BAR; PG8_SCHED;
;             PG8_LDA(At, 0, 1); PG8_STAGE(PG8_SB(0, 0), b2, voffB); PG8_STAGE(PG8_SB(0, 1), b2 + hstepB, voffB); PG8_STAGE(PG8_SA(0, 0), a2, voffA);
.Lrw_done_1050_0_pl:
	s_waitcnt lgkmcnt(0)
	s_barrier
	v_mfma_f32_16x16x32_bf16 v[126:129], v[164:167], v[200:203], 0
	v_mfma_f32_16x16x32_bf16 v[118:121], v[172:175], v[200:203], 0
	v_mfma_f32_16x16x32_bf16 v[110:113], v[164:167], v[208:211], 0
	v_mfma_f32_16x16x32_bf16 v[102:105], v[172:175], v[208:211], 0
	v_mfma_f32_16x16x32_bf16 v[94:97], v[164:167], v[216:219], 0
	v_mfma_f32_16x16x32_bf16 v[86:89], v[172:175], v[216:219], 0
	v_mfma_f32_16x16x32_bf16 v[78:81], v[164:167], v[224:227], 0
	v_mfma_f32_16x16x32_bf16 v[70:73], v[172:175], v[224:227], 0
	v_mfma_f32_16x16x32_bf16 v[126:129], v[168:171], v[204:207], v[126:129]
	v_mfma_f32_16x16x32_bf16 v[118:121], v[176:179], v[204:207], v[118:121]
	v_mfma_f32_16x16x32_bf16 v[110:113], v[168:171], v[212:215], v[110:113]
	v_mfma_f32_16x16x32_bf16 v[102:105], v[176:179], v[212:215], v[102:105]
	v_mfma_f32_16x16x32_bf16 v[94:97], v[168:171], v[220:223], v[94:97]
	v_mfma_f32_16x16x32_bf16 v[86:89], v[176:179], v[220:223], v[86:89]
	v_mfma_f32_16x16x32_bf16 v[78:81], v[168:171], v[228:231], v[78:81]
	v_mfma_f32_16x16x32_bf16 v[70:73], v[176:179], v[228:231], v[70:73]
	v_mfma_f32_16x16x32_bf16 v[122:125], v[184:187], v[200:203], 0
	v_mfma_f32_16x16x32_bf16 v[114:117], v[192:195], v[200:203], 0
	v_mfma_f32_16x16x32_bf16 v[106:109], v[184:187], v[208:211], 0
	v_mfma_f32_16x16x32_bf16 v[98:101], v[192:195], v[208:211], 0
	v_mfma_f32_16x16x32_bf16 v[90:93], v[184:187], v[216:219], 0
	v_mfma_f32_16x16x32_bf16 v[82:85], v[192:195], v[216:219], 0
	v_mfma_f32_16x16x32_bf16 v[74:77], v[184:187], v[224:227], 0
	v_mfma_f32_16x16x32_bf16 v[66:69], v[192:195], v[224:227], 0
	v_mfma_f32_16x16x32_bf16 v[122:125], v[188:191], v[204:207], v[122:125]
	v_mfma_f32_16x16x32_bf16 v[114:117], v[196:199], v[204:207], v[114:117]
	v_mfma_f32_16x16x32_bf16 v[106:109], v[188:191], v[212:215], v[106:109]
	v_mfma_f32_16x16x32_bf16 v[98:101], v[196:199], v[212:215], v[98:101]
	v_mfma_f32_16x16x32_bf16 v[90:93], v[188:191], v[220:223], v[90:93]
	v_mfma_f32_16x16x32_bf16 v[82:85], v[196:199], v[220:223], v[82:85]
	v_mfma_f32_16x16x32_bf16 v[74:77], v[188:191], v[228:231], v[74:77]
	v_mfma_f32_16x16x32_bf16 v[66:69], v[196:199], v[228:231], v[66:69]
	s_barrier
	s_add_i32 s12, s39, s21
	v_lshl_add_u64 v[160:161], s[16:17], 0, v[134:135]
	s_mov_b32 m0, s12
	ds_read_b128 v[200:203], v163 offset:16384
	ds_read_b128 v[204:207], v163 offset:17408
	ds_read_b128 v[208:211], v163 offset:18432
	ds_read_b128 v[212:215], v163 offset:19456
	ds_read_b128 v[216:219], v163 offset:20480
	ds_read_b128 v[220:223], v163 offset:21504
	ds_read_b128 v[224:227], v163 offset:22528
	ds_read_b128 v[228:231], v163 offset:23552
	global_load_lds_dwordx4 v[160:161], off
	s_add_i32 m0, s12, 0x2000
	s_add_u32 s12, s16, 0x44000
	v_lshl_add_u64 v[180:181], s[16:17], 0, v[130:131]
	s_addc_u32 s13, s17, 0
	s_add_i32 s39, s40, s21
	global_load_lds_dwordx4 v[180:181], off
	v_lshl_add_u64 v[232:233], s[12:13], 0, v[134:135]
	s_mov_b32 m0, s39
	global_load_lds_dwordx4 v[232:233], off
	s_add_i32 m0, s39, 0x2000
	v_lshl_add_u64 v[232:233], s[12:13], 0, v[130:131]
	global_load_lds_dwordx4 v[232:233], off
	s_mov_b32 m0, s23
	v_lshl_add_u64 v[232:233], s[18:19], 0, v[154:155]
	global_load_lds_dwordx4 v[232:233], off
	s_mov_b32 m0, s24
	v_lshl_add_u64 v[234:235], s[18:19], 0, v[132:133]
	global_load_lds_dwordx4 v[234:235], off
	s_cmp_lt_u32 s29, 2
	s_cbranch_scc1 .Lrw_std_1050_1_pl
	s_waitcnt vmcnt(16)
	s_branch .Lrw_done_1050_1_pl

; #define PG8_STAGE(bufoff, gbase, voff) do { _Pragma("unroll") for (int _i = 0; _i < 2; ++_i) \
;         __builtin_amdgcn_global_load_lds((const unsigned*)((const char*)(gbase) + (voff)[_i]), (LAS unsigned*)(lds + (bufoff) + ldsw + _i * 8192), 16, 0, 0); } while (0)
; #define PG8_LDA(dst, b, h) do { _Pragma("unroll") for (int m = 0; m < 4; ++m) _Pragma("unroll") for (int k = 0; k < 2; ++k) dst[m][k] = *(const LAS bf16x8*)(lds + PG8_SA(b, h) + aoff + m * 2048 + k * 1024); } while (0)
; #define PG8_LDB(dst, b, h) do { _Pragma("unroll") for (int n = 0; n < 2; ++n) _Pragma("unroll") for (int k = 0; k < 2; ++k) dst[n][k] = *(const LAS bf16x8*)(lds + PG8_SB(b, h) + boff + n * 2048 + k * 1024); } while (0)
; #define PG8_MMA(ai, bj, At, Bt) do { __builtin_amdgcn_s_setprio(1); _Pragma("unroll") for (int m = 0; m < 4; ++m) _Pragma("unroll") for (int n = 0; n < 2; ++n) _Pragma("unroll") for (int k = 0; k < 2; ++k) \
;         acc[ai][bj][m][n] = __builtin_amdgcn_mfma_f32_16x16x32_bf16(Bt[n][k], At[m][k], acc[ai][bj][m][n], 0, 0, 0); __builtin_amdgcn_s_setprio(0); } while (0)
; #define PG8_WAIT_V(n) asm volatile("s_waitcnt vmcnt(" #n ")" ::: "memory")
; #define PG8_WAIT_L(n) asm volatile("s_waitcnt lgkmcnt(" #n ")" ::: "memory")
; #define PG8_BAR __builtin_amdgcn_s_barrier()
; #define PG8_SCHED __builtin_amdgcn_sched_barrier(0)
; template <class Epi, bool ALIGN_EPI = PG8_ALIGN, bool SP2 = PG8_SP2>
; __device__ __forceinline__ void gemm_phase(LAS uchar* lds, const Gemm g, const StaticOrder& S, const Epi& E) {
;     ...
;             PG8_WAIT_V(8); PG8_WAIT_L(0); PG8_BAR; PG8_MMA(1, 0, At, B0); PG8_MMA(1, 1, At, B1); PG8_BAR; PG8_SCHED;
;             PG8_LDB(B0, 1, 0); PG8_LDB(B1, 1, 1); PG8_SCHED; PG8_LDA(At, 1, 0); PG8_STAGE(PG8_SA(0, 1), a2 + hstepA, voffA);
;             PG8_WAIT_V(8); PG8_WAIT_L(0); PG8_BAR; PG8_MMA(0, 0, At, B0); PG8_MMA(0, 1, At, B1); PG8_BAR; PG8_SCHED;
.Lrw_done_1050_1_pl:
	s_waitcnt lgkmcnt(0)
	s_barrier
	v_mfma_f32_16x16x32_bf16 v[62:65], v[164:167], v[200:203], 0
	v_mfma_f32_16x16x32_bf16 v[54:57], v[172:175], v[200:203], 0
	v_mfma_f32_16x16x32_bf16 v[46:49], v[164:167], v[208:211], 0
	v_mfma_f32_16x16x32_bf16 v[38:41], v[172:175], v[208:211], 0
	v_mfma_f32_16x16x32_bf16 v[30:33], v[164:167], v[216:219], 0
	v_mfma_f32_16x16x32_bf16 v[22:25], v[172:175], v[216:219], 0
	v_mfma_f32_16x16x32_bf16 v[14:17], v[164:167], v[224:227], 0
	v_mfma_f32_16x16x32_bf16 v[6:9], v[172:175], v[224:227], 0
	v_mfma_f32_16x16x32_bf16 v[62:65], v[168:171], v[204:207], v[62:65]
	v_mfma_f32_16x16x32_bf16 v[54:57], v[176:179], v[204:207], v[54:57]
	v_mfma_f32_16x16x32_bf16 v[46:49], v[168:171], v[212:215], v[46:49]
	v_mfma_f32_16x16x32_bf16 v[38:41], v[176:179], v[212:215], v[38:41]
	v_mfma_f32_16x16x32_bf16 v[30:33], v[168:171], v[220:223], v[30:33]
	v_mfma_f32_16x16x32_bf16 v[22:25], v[176:179], v[220:223], v[22:25]
	v_mfma_f32_16x16x32_bf16 v[14:17], v[168:171], v[228:231], v[14:17]
	v_mfma_f32_16x16x32_bf16 v[6:9], v[176:179], v[228:231], v[6:9]
	v_mfma_f32_16x16x32_bf16 v[58:61], v[184:187], v[200:203], 0
	v_mfma_f32_16x16x32_bf16 v[50:53], v[192:195], v[200:203], 0
	v_mfma_f32_16x16x32_bf16 v[42:45], v[184:187], v[208:211], 0
	v_mfma_f32_16x16x32_bf16 v[34:37], v[192:195], v[208:211], 0
	v_mfma_f32_16x16x32_bf16 v[26:29], v[184:187], v[216:219], 0
	v_mfma_f32_16x16x32_bf16 v[18:21], v[192:195], v[216:219], 0
	v_mfma_f32_16x16x32_bf16 v[10:13], v[184:187], v[224:227], 0
	v_mfma_f32_16x16x32_bf16 v[2:5], v[192:195], v[224:227], 0
	v_mfma_f32_16x16x32_bf16 v[58:61], v[188:191], v[204:207], v[58:61]
	v_mfma_f32_16x16x32_bf16 v[50:53], v[196:199], v[204:207], v[50:53]
	v_mfma_f32_16x16x32_bf16 v[42:45], v[188:191], v[212:215], v[42:45]
	v_mfma_f32_16x16x32_bf16 v[34:37], v[196:199], v[212:215], v[34:37]
	v_mfma_f32_16x16x32_bf16 v[26:29], v[188:191], v[220:223], v[26:29]
	v_mfma_f32_16x16x32_bf16 v[18:21], v[196:199], v[220:223], v[18:21]
	v_mfma_f32_16x16x32_bf16 v[10:13], v[188:191], v[228:231], v[10:13]
	v_mfma_f32_16x16x32_bf16 v[2:5], v[196:199], v[228:231], v[2:5]
	s_barrier
	s_add_i32 s39, 0, 0x18000
	v_add_u32_e32 v144, s39, v139
	s_add_i32 s40, 0, 0x1c000
	ds_read_b128 v[164:167], v144
	ds_read_b128 v[168:171], v144 offset:1024
	ds_read_b128 v[172:175], v144 offset:2048
	ds_read_b128 v[176:179], v144 offset:3072
	v_add_u32_e32 v144, s40, v139
	ds_read_b128 v[184:187], v144
	ds_read_b128 v[188:191], v144 offset:1024
	ds_read_b128 v[192:195], v144 offset:2048
	ds_read_b128 v[196:199], v144 offset:3072
	s_add_u32 s12, s18, 0x44000
	s_addc_u32 s13, s19, 0
	s_mov_b32 m0, s25
	v_lshl_add_u64 v[236:237], s[12:13], 0, v[154:155]
	ds_read_b128 v[200:203], v163 offset:32768
	ds_read_b128 v[204:207], v163 offset:33792
	ds_read_b128 v[208:211], v163 offset:34816
	ds_read_b128 v[212:215], v163 offset:35840
	ds_read_b128 v[216:219], v163 offset:36864
	ds_read_b128 v[220:223], v163 offset:37888
	ds_read_b128 v[224:227], v163 offset:38912
	ds_read_b128 v[228:231], v163 offset:39936
	global_load_lds_dwordx4 v[236:237], off
	s_mov_b32 m0, s26
	v_lshl_add_u64 v[236:237], s[12:13], 0, v[132:133]
	global_load_lds_dwordx4 v[236:237], off
	s_waitcnt vmcnt(8)
	s_waitcnt lgkmcnt(0)
	s_barrier
	v_mfma_f32_16x16x32_bf16 v[126:129], v[164:167], v[200:203], v[126:129]
	v_mfma_f32_16x16x32_bf16 v[118:121], v[172:175], v[200:203], v[118:121]
	v_mfma_f32_16x16x32_bf16 v[110:113], v[164:167], v[208:211], v[110:113]
	v_mfma_f32_16x16x32_bf16 v[102:105], v[172:175], v[208:211], v[102:105]
	v_mfma_f32_16x16x32_bf16 v[94:97], v[164:167], v[216:219], v[94:97]
	v_mfma_f32_16x16x32_bf16 v[86:89], v[172:175], v[216:219], v[86:89]
	v_mfma_f32_16x16x32_bf16 v[78:81], v[164:167], v[224:227], v[78:81]
	v_mfma_f32_16x16x32_bf16 v[70:73], v[172:175], v[224:227], v[70:73]
	v_mfma_f32_16x16x32_bf16 v[126:129], v[168:171], v[204:207], v[126:129]
	v_mfma_f32_16x16x32_bf16 v[118:121], v[176:179], v[204:207], v[118:121]
	v_mfma_f32_16x16x32_bf16 v[110:113], v[168:171], v[212:215], v[110:113]
	v_mfma_f32_16x16x32_bf16 v[102:105], v[176:179], v[212:215], v[102:105]
	v_mfma_f32_16x16x32_bf16 v[94:97], v[168:171], v[220:223], v[94:97]
	v_mfma_f32_16x16x32_bf16 v[86:89], v[176:179], v[220:223], v[86:89]
	v_mfma_f32_16x16x32_bf16 v[78:81], v[168:171], v[228:231], v[78:81]
	v_mfma_f32_16x16x32_bf16 v[70:73], v[176:179], v[228:231], v[70:73]
	v_mfma_f32_16x16x32_bf16 v[122:125], v[184:187], v[200:203], v[122:125]
	v_mfma_f32_16x16x32_bf16 v[114:117], v[192:195], v[200:203], v[114:117]
	v_mfma_f32_16x16x32_bf16 v[106:109], v[184:187], v[208:211], v[106:109]
	v_mfma_f32_16x16x32_bf16 v[98:101], v[192:195], v[208:211], v[98:101]
	v_mfma_f32_16x16x32_bf16 v[90:93], v[184:187], v[216:219], v[90:93]
	v_mfma_f32_16x16x32_bf16 v[82:85], v[192:195], v[216:219], v[82:85]
	v_mfma_f32_16x16x32_bf16 v[74:77], v[184:187], v[224:227], v[74:77]
	v_mfma_f32_16x16x32_bf16 v[66:69], v[192:195], v[224:227], v[66:69]
	v_mfma_f32_16x16x32_bf16 v[122:125], v[188:191], v[204:207], v[122:125]
	v_mfma_f32_16x16x32_bf16 v[114:117], v[196:199], v[204:207], v[114:117]
	v_mfma_f32_16x16x32_bf16 v[106:109], v[188:191], v[212:215], v[106:109]
	v_mfma_f32_16x16x32_bf16 v[98:101], v[196:199], v[212:215], v[98:101]
	v_mfma_f32_16x16x32_bf16 v[90:93], v[188:191], v[220:223], v[90:93]
	v_mfma_f32_16x16x32_bf16 v[82:85], v[196:199], v[220:223], v[82:85]
	v_mfma_f32_16x16x32_bf16 v[74:77], v[188:191], v[228:231], v[74:77]
	v_mfma_f32_16x16x32_bf16 v[66:69], v[196:199], v[228:231], v[66:69]
	s_barrier
; #define PG8_STAGE(bufoff, gbase, voff) do { _Pragma("unroll") for (int _i = 0; _i < 2; ++_i) \
;         __builtin_amdgcn_global_load_lds((const unsigned*)((const char*)(gbase) + (voff)[_i]), (LAS unsigned*)(lds + (bufoff) + ldsw + _i * 8192), 16, 0, 0); } while (0)
; #define PG8_LDA(dst, b, h) do { _Pragma("unroll") for (int m = 0; m < 4; ++m) _Pragma("unroll") for (int k = 0; k < 2; ++k) dst[m][k] = *(const LAS bf16x8*)(lds + PG8_SA(b, h) + aoff + m * 2048 + k * 1024); } while (0)
; #define PG8_LDB(dst, b, h) do { _Pragma("unroll") for (int n = 0; n < 2; ++n) _Pragma("unroll") for (int k = 0; k < 2; ++k) dst[n][k] = *(const LAS bf16x8*)(lds + PG8_SB(b, h) + boff + n * 2048 + k * 1024); } while (0)
; #define PG8_BAR __builtin_amdgcn_s_barrier()
; template <class Epi, bool ALIGN_EPI = PG8_ALIGN, bool SP2 = PG8_SP2>
; __device__ __forceinline__ void gemm_phase(LAS uchar* lds, const Gemm g, const StaticOrder& S, const Epi& E) {
;     ...
;         for (int t = tb; t < tb + tblk; t += 2) {
;             const bool last = (t == nt - 2);
;             const char* a1 = cA + (size_t)(t + 1) * kstep;
;             const char* a2 = last ? nA : cA + (size_t)(t + 2) * kstep; const char* b2 = last ? nB : cB + (size_t)(t + 2) * kstep;
;             const char* a3 = a2 + kstep; const char* b3 = b2 + kstep;
;             if constexpr (SP2) {
;             PG8_LDB(B0, 0, 0); PG8_LDB(B1, 0, 1); PG8_SCHED; PG8_LDA(At, 0, 0); PG8_STAGE(PG8_SA(1, 1), a1 + hstepA, voffA);
;             PG8_WAIT_V(8); PG8_WAIT_L(0); PG8_BAR; PG8_MMA(0, 0, At, B0); PG8_MMA(0, 1, At, B1); PG8_BAR; PG8_SCHED;
;             PG8_LDA(At, 0, 1); PG8_STAGE(PG8_SB(0, 0), b2, voffB); PG8_STAGE(PG8_SB(0, 1), b2 + hstepB, voffB); PG8_STAGE(PG8_SA(0, 0), a2, voffA);
;             PG8_WAIT_V(8); PG8_WAIT_L(0); PG8_BAR; PG8_MMA(1, 0, At, B0); PG8_MMA(1, 1, At, B1); PG8_BAR; PG8_SCHED;
;             PG8_LDB(B0, 1, 0); PG8_LDB(B1, 1, 1); PG8_SCHED; PG8_LDA(At, 1, 0); PG8_STAGE(PG8_SA(0, 1), a2 + hstepA, voffA);
;             PG8_WAIT_V(8); PG8_WAIT_L(0); PG8_BAR; PG8_MMA(0, 0, At, B0); PG8_MMA(0, 1, At, B1); PG8_BAR; PG8_SCHED;
;             PG8_LDA(At, 1, 1); PG8_STAGE(PG8_SB(1, 0), b3, voffB); PG8_STAGE(PG8_SB(1, 1), b3 + hstepB, voffB); PG8_STAGE(PG8_SA(1, 0), a3, voffA);
;             PG8_WAIT_V(8); PG8_WAIT_L(0); PG8_BAR; PG8_MMA(1, 0, At, B0); PG8_MMA(1, 1, At, B1); PG8_BAR; PG8_SCHED;
	s_add_i32 s12, s39, s21
	v_lshl_add_u64 v[160:161], v[160:161], 0, s[84:85]
	s_mov_b32 m0, s12
	ds_read_b128 v[200:203], v163 offset:49152
	ds_read_b128 v[204:207], v163 offset:50176
	ds_read_b128 v[208:211], v163 offset:51200
	ds_read_b128 v[212:215], v163 offset:52224
	ds_read_b128 v[216:219], v163 offset:53248
	ds_read_b128 v[220:223], v163 offset:54272
	ds_read_b128 v[224:227], v163 offset:55296
	ds_read_b128 v[228:231], v163 offset:56320
	global_load_lds_dwordx4 v[160:161], off
	s_add_i32 m0, s12, 0x2000
	s_add_u32 s12, s16, 0x44080
	v_lshl_add_u64 v[160:161], v[180:181], 0, s[84:85]
	s_addc_u32 s13, s17, 0
	s_add_i32 s16, s40, s21
	global_load_lds_dwordx4 v[160:161], off
	s_mov_b32 m0, s16
	v_lshl_add_u64 v[160:161], s[12:13], 0, v[134:135]
	global_load_lds_dwordx4 v[160:161], off
	s_add_i32 m0, s16, 0x2000
	v_lshl_add_u64 v[160:161], s[12:13], 0, v[130:131]
	global_load_lds_dwordx4 v[160:161], off
	s_mov_b32 m0, s27
	v_lshl_add_u64 v[160:161], v[232:233], 0, s[84:85]
	global_load_lds_dwordx4 v[160:161], off
	s_mov_b32 m0, s28
	v_lshl_add_u64 v[160:161], v[234:235], 0, s[84:85]
	global_load_lds_dwordx4 v[160:161], off
	s_waitcnt vmcnt(8)
	s_waitcnt lgkmcnt(0)
	s_barrier
	v_mfma_f32_16x16x32_bf16 v[62:65], v[164:167], v[200:203], v[62:65]
	v_mfma_f32_16x16x32_bf16 v[54:57], v[172:175], v[200:203], v[54:57]
	v_mfma_f32_16x16x32_bf16 v[46:49], v[164:167], v[208:211], v[46:49]
	v_mfma_f32_16x16x32_bf16 v[38:41], v[172:175], v[208:211], v[38:41]
	v_mfma_f32_16x16x32_bf16 v[30:33], v[164:167], v[216:219], v[30:33]
	v_mfma_f32_16x16x32_bf16 v[22:25], v[172:175], v[216:219], v[22:25]
	v_mfma_f32_16x16x32_bf16 v[14:17], v[164:167], v[224:227], v[14:17]
	v_mfma_f32_16x16x32_bf16 v[6:9], v[172:175], v[224:227], v[6:9]
	v_mfma_f32_16x16x32_bf16 v[62:65], v[168:171], v[204:207], v[62:65]
	v_mfma_f32_16x16x32_bf16 v[54:57], v[176:179], v[204:207], v[54:57]
	v_mfma_f32_16x16x32_bf16 v[46:49], v[168:171], v[212:215], v[46:49]
	v_mfma_f32_16x16x32_bf16 v[38:41], v[176:179], v[212:215], v[38:41]
	v_mfma_f32_16x16x32_bf16 v[30:33], v[168:171], v[220:223], v[30:33]
	v_mfma_f32_16x16x32_bf16 v[22:25], v[176:179], v[220:223], v[22:25]
	v_mfma_f32_16x16x32_bf16 v[14:17], v[168:171], v[228:231], v[14:17]
	v_mfma_f32_16x16x32_bf16 v[6:9], v[176:179], v[228:231], v[6:9]
	v_mfma_f32_16x16x32_bf16 v[58:61], v[184:187], v[200:203], v[58:61]
	v_mfma_f32_16x16x32_bf16 v[50:53], v[192:195], v[200:203], v[50:53]
	v_mfma_f32_16x16x32_bf16 v[42:45], v[184:187], v[208:211], v[42:45]
	v_mfma_f32_16x16x32_bf16 v[34:37], v[192:195], v[208:211], v[34:37]
	v_mfma_f32_16x16x32_bf16 v[26:29], v[184:187], v[216:219], v[26:29]
	v_mfma_f32_16x16x32_bf16 v[18:21], v[192:195], v[216:219], v[18:21]
	v_mfma_f32_16x16x32_bf16 v[10:13], v[184:187], v[224:227], v[10:13]
	v_mfma_f32_16x16x32_bf16 v[2:5], v[192:195], v[224:227], v[2:5]
	v_mfma_f32_16x16x32_bf16 v[58:61], v[188:191], v[204:207], v[58:61]
	v_mfma_f32_16x16x32_bf16 v[50:53], v[196:199], v[204:207], v[50:53]
	v_mfma_f32_16x16x32_bf16 v[42:45], v[188:191], v[212:215], v[42:45]
	v_mfma_f32_16x16x32_bf16 v[34:37], v[196:199], v[212:215], v[34:37]
	v_mfma_f32_16x16x32_bf16 v[26:29], v[188:191], v[220:223], v[26:29]
	v_mfma_f32_16x16x32_bf16 v[18:21], v[196:199], v[220:223], v[18:21]
	v_mfma_f32_16x16x32_bf16 v[10:13], v[188:191], v[228:231], v[10:13]
	v_mfma_f32_16x16x32_bf16 v[2:5], v[196:199], v[228:231], v[2:5]
	s_barrier
	s_add_i32 s38, s38, 2
	s_add_u32 s36, s36, 0x100
	s_addc_u32 s37, s37, 0
	s_cmp_gt_u32 s38, 13
	s_mov_b64 s[12:13], s[14:15]
.LBB0_1050:
	s_add_u32 s14, s12, 0x100
	s_addc_u32 s15, s13, 0
	s_add_i32 s39, 0, 0x10000
	s_cmp_eq_u32 s38, 12
	s_cselect_b32 s19, s1, s15
	s_cselect_b32 s18, s0, s14
	v_add_u32_e32 v144, s39, v139
	s_cselect_b32 s17, s11, s37
	s_cselect_b32 s16, s10, s36
	s_add_i32 s40, 0, 0x14000
	ds_read_b128 v[164:167], v144
	ds_read_b128 v[168:171], v144 offset:1024
	ds_read_b128 v[172:175], v144 offset:2048
	ds_read_b128 v[176:179], v144 offset:3072
	v_add_u32_e32 v144, s40, v139
	ds_read_b128 v[184:187], v144
	ds_read_b128 v[188:191], v144 offset:1024
	ds_read_b128 v[192:195], v144 offset:2048
	ds_read_b128 v[196:199], v144 offset:3072
	v_lshl_add_u64 v[160:161], s[12:13], 0, v[156:157]
	s_add_i32 m0, s23, 0xc000
	ds_read_b128 v[200:203], v163
	ds_read_b128 v[204:207], v163 offset:1024
	ds_read_b128 v[208:211], v163 offset:2048
	ds_read_b128 v[212:215], v163 offset:3072
	ds_read_b128 v[216:219], v163 offset:4096
	ds_read_b128 v[220:223], v163 offset:5120
	ds_read_b128 v[224:227], v163 offset:6144
	ds_read_b128 v[228:231], v163 offset:7168
	global_load_lds_dwordx4 v[160:161], off
	s_add_i32 m0, s23, 0xe000
	v_lshl_add_u64 v[160:161], s[12:13], 0, v[158:159]
	global_load_lds_dwordx4 v[160:161], off
	s_waitcnt vmcnt(8)
	s_waitcnt lgkmcnt(0)
	s_barrier
; #define PG8_STAGE(bufoff, gbase, voff) do { _Pragma("unroll") for (int _i = 0; _i < 2; ++_i) \
;         __builtin_amdgcn_global_load_lds((const unsigned*)((const char*)(gbase) + (voff)[_i]), (LAS unsigned*)(lds + (bufoff) + ldsw + _i * 8192), 16, 0, 0); } while (0)
; #define PG8_LDA(dst, b, h) do { _Pragma("unroll") for (int m = 0; m < 4; ++m) _Pragma("unroll") for (int k = 0; k < 2; ++k) dst[m][k] = *(const LAS bf16x8*)(lds + PG8_SA(b, h) + aoff + m * 2048 + k * 1024); } while (0)
; #define PG8_MMA(ai, bj, At, Bt) do { __builtin_amdgcn_s_setprio(1); _Pragma("unroll") for (int m = 0; m < 4; ++m) _Pragma("unroll") for (int n = 0; n < 2; ++n) _Pragma("unroll") for (int k = 0; k < 2; ++k) \
;         acc[ai][bj][m][n] = __builtin_amdgcn_mfma_f32_16x16x32_bf16(Bt[n][k], At[m][k], acc[ai][bj][m][n], 0, 0, 0); __builtin_amdgcn_s_setprio(0); } while (0)
; #define PG8_WAIT_V(n) asm volatile("s_waitcnt vmcnt(" #n ")" ::: "memory")
; #define PG8_WAIT_L(n) asm volatile("s_waitcnt lgkmcnt(" #n ")" ::: "memory")
; #define PG8_BAR __builtin_amdgcn_s_barrier()
; #define PG8_SCHED __builtin_amdgcn_sched_barrier(0)
; template <class Epi, bool ALIGN_EPI = PG8_ALIGN, bool SP2 = PG8_SP2>
; __device__ __forceinline__ void gemm_phase(LAS uchar* lds, const Gemm g, const StaticOrder& S, const Epi& E) {
;     ...
;             PG8_WAIT_V(8); PG8_WAIT_L(0); PG8_BAR; PG8_MMA(0, 0, At, B0); PG8_MMA(0, 1, At, B1); PG8_BAR; PG8_SCHED;
;             PG8_LDA(At, 0, 1); PG8_STAGE(PG8_SB(0, 0), b2, voffB); PG8_STAGE(PG8_SB(0, 1), b2 + hstepB, voffB); PG8_STAGE(PG8_SA(0, 0), a2, voffA);
;             PG8_WAIT_V(8); PG8_WAIT_L(0); PG8_BAR; PG8_MMA(1, 0, At, B0); PG8_MMA(1, 1, At, B1); PG8_BAR; PG8_SCHED;
	v_mfma_f32_16x16x32_bf16 v[126:129], v[164:167], v[200:203], v[126:129]
	v_mfma_f32_16x16x32_bf16 v[118:121], v[172:175], v[200:203], v[118:121]
	v_mfma_f32_16x16x32_bf16 v[110:113], v[164:167], v[208:211], v[110:113]
	v_mfma_f32_16x16x32_bf16 v[102:105], v[172:175], v[208:211], v[102:105]
	v_mfma_f32_16x16x32_bf16 v[94:97], v[164:167], v[216:219], v[94:97]
	v_mfma_f32_16x16x32_bf16 v[86:89], v[172:175], v[216:219], v[86:89]
	v_mfma_f32_16x16x32_bf16 v[78:81], v[164:167], v[224:227], v[78:81]
	v_mfma_f32_16x16x32_bf16 v[70:73], v[172:175], v[224:227], v[70:73]
	v_mfma_f32_16x16x32_bf16 v[126:129], v[168:171], v[204:207], v[126:129]
	v_mfma_f32_16x16x32_bf16 v[118:121], v[176:179], v[204:207], v[118:121]
	v_mfma_f32_16x16x32_bf16 v[110:113], v[168:171], v[212:215], v[110:113]
	v_mfma_f32_16x16x32_bf16 v[102:105], v[176:179], v[212:215], v[102:105]
	v_mfma_f32_16x16x32_bf16 v[94:97], v[168:171], v[220:223], v[94:97]
	v_mfma_f32_16x16x32_bf16 v[86:89], v[176:179], v[220:223], v[86:89]
	v_mfma_f32_16x16x32_bf16 v[78:81], v[168:171], v[228:231], v[78:81]
	v_mfma_f32_16x16x32_bf16 v[70:73], v[176:179], v[228:231], v[70:73]
	v_mfma_f32_16x16x32_bf16 v[122:125], v[184:187], v[200:203], v[122:125]
	v_mfma_f32_16x16x32_bf16 v[114:117], v[192:195], v[200:203], v[114:117]
	v_mfma_f32_16x16x32_bf16 v[106:109], v[184:187], v[208:211], v[106:109]
	v_mfma_f32_16x16x32_bf16 v[98:101], v[192:195], v[208:211], v[98:101]
	v_mfma_f32_16x16x32_bf16 v[90:93], v[184:187], v[216:219], v[90:93]
	v_mfma_f32_16x16x32_bf16 v[82:85], v[192:195], v[216:219], v[82:85]
	v_mfma_f32_16x16x32_bf16 v[74:77], v[184:187], v[224:227], v[74:77]
	v_mfma_f32_16x16x32_bf16 v[66:69], v[192:195], v[224:227], v[66:69]
	v_mfma_f32_16x16x32_bf16 v[122:125], v[188:191], v[204:207], v[122:125]
	v_mfma_f32_16x16x32_bf16 v[114:117], v[196:199], v[204:207], v[114:117]
	v_mfma_f32_16x16x32_bf16 v[106:109], v[188:191], v[212:215], v[106:109]
	v_mfma_f32_16x16x32_bf16 v[98:101], v[196:199], v[212:215], v[98:101]
	v_mfma_f32_16x16x32_bf16 v[90:93], v[188:191], v[220:223], v[90:93]
	v_mfma_f32_16x16x32_bf16 v[82:85], v[196:199], v[220:223], v[82:85]
	v_mfma_f32_16x16x32_bf16 v[74:77], v[188:191], v[228:231], v[74:77]
	v_mfma_f32_16x16x32_bf16 v[66:69], v[196:199], v[228:231], v[66:69]
	s_barrier
	s_add_i32 s12, s39, s21
	v_lshl_add_u64 v[160:161], s[16:17], 0, v[134:135]
	s_mov_b32 m0, s12
	ds_read_b128 v[200:203], v163 offset:16384
	ds_read_b128 v[204:207], v163 offset:17408
	ds_read_b128 v[208:211], v163 offset:18432
	ds_read_b128 v[212:215], v163 offset:19456
	ds_read_b128 v[216:219], v163 offset:20480
	ds_read_b128 v[220:223], v163 offset:21504
	ds_read_b128 v[224:227], v163 offset:22528
	ds_read_b128 v[228:231], v163 offset:23552
	global_load_lds_dwordx4 v[160:161], off
	s_add_i32 m0, s12, 0x2000
	s_add_u32 s12, s16, 0x44000
	v_lshl_add_u64 v[180:181], s[16:17], 0, v[130:131]
	s_addc_u32 s13, s17, 0
	s_add_i32 s39, s40, s21
	global_load_lds_dwordx4 v[180:181], off
	v_lshl_add_u64 v[232:233], s[12:13], 0, v[134:135]
	s_mov_b32 m0, s39
	global_load_lds_dwordx4 v[232:233], off
	s_add_i32 m0, s39, 0x2000
	v_lshl_add_u64 v[232:233], s[12:13], 0, v[130:131]
	global_load_lds_dwordx4 v[232:233], off
	s_mov_b32 m0, s23
	v_lshl_add_u64 v[232:233], s[18:19], 0, v[154:155]
	global_load_lds_dwordx4 v[232:233], off
	s_mov_b32 m0, s24
	v_lshl_add_u64 v[234:235], s[18:19], 0, v[132:133]
	global_load_lds_dwordx4 v[234:235], off
	s_waitcnt vmcnt(8)
	s_waitcnt lgkmcnt(0)
	s_barrier
	v_mfma_f32_16x16x32_bf16 v[62:65], v[164:167], v[200:203], v[62:65]
	v_mfma_f32_16x16x32_bf16 v[54:57], v[172:175], v[200:203], v[54:57]
	v_mfma_f32_16x16x32_bf16 v[46:49], v[164:167], v[208:211], v[46:49]
	v_mfma_f32_16x16x32_bf16 v[38:41], v[172:175], v[208:211], v[38:41]
	v_mfma_f32_16x16x32_bf16 v[30:33], v[164:167], v[216:219], v[30:33]
	v_mfma_f32_16x16x32_bf16 v[22:25], v[172:175], v[216:219], v[22:25]
	v_mfma_f32_16x16x32_bf16 v[14:17], v[164:167], v[224:227], v[14:17]
	v_mfma_f32_16x16x32_bf16 v[6:9], v[172:175], v[224:227], v[6:9]
	v_mfma_f32_16x16x32_bf16 v[62:65], v[168:171], v[204:207], v[62:65]
	v_mfma_f32_16x16x32_bf16 v[54:57], v[176:179], v[204:207], v[54:57]
	v_mfma_f32_16x16x32_bf16 v[46:49], v[168:171], v[212:215], v[46:49]
	v_mfma_f32_16x16x32_bf16 v[38:41], v[176:179], v[212:215], v[38:41]
	v_mfma_f32_16x16x32_bf16 v[30:33], v[168:171], v[220:223], v[30:33]
	v_mfma_f32_16x16x32_bf16 v[22:25], v[176:179], v[220:223], v[22:25]
	v_mfma_f32_16x16x32_bf16 v[14:17], v[168:171], v[228:231], v[14:17]
	v_mfma_f32_16x16x32_bf16 v[6:9], v[176:179], v[228:231], v[6:9]
	v_mfma_f32_16x16x32_bf16 v[58:61], v[184:187], v[200:203], v[58:61]
	v_mfma_f32_16x16x32_bf16 v[50:53], v[192:195], v[200:203], v[50:53]
	v_mfma_f32_16x16x32_bf16 v[42:45], v[184:187], v[208:211], v[42:45]
	v_mfma_f32_16x16x32_bf16 v[34:37], v[192:195], v[208:211], v[34:37]
	v_mfma_f32_16x16x32_bf16 v[26:29], v[184:187], v[216:219], v[26:29]
	v_mfma_f32_16x16x32_bf16 v[18:21], v[192:195], v[216:219], v[18:21]
	v_mfma_f32_16x16x32_bf16 v[10:13], v[184:187], v[224:227], v[10:13]
	v_mfma_f32_16x16x32_bf16 v[2:5], v[192:195], v[224:227], v[2:5]
	v_mfma_f32_16x16x32_bf16 v[58:61], v[188:191], v[204:207], v[58:61]
	v_mfma_f32_16x16x32_bf16 v[50:53], v[196:199], v[204:207], v[50:53]
	v_mfma_f32_16x16x32_bf16 v[42:45], v[188:191], v[212:215], v[42:45]
	v_mfma_f32_16x16x32_bf16 v[34:37], v[196:199], v[212:215], v[34:37]
	v_mfma_f32_16x16x32_bf16 v[26:29], v[188:191], v[220:223], v[26:29]
	v_mfma_f32_16x16x32_bf16 v[18:21], v[196:199], v[220:223], v[18:21]
	v_mfma_f32_16x16x32_bf16 v[10:13], v[188:191], v[228:231], v[10:13]
	v_mfma_f32_16x16x32_bf16 v[2:5], v[196:199], v[228:231], v[2:5]
	s_barrier
; #define PG8_STAGE(bufoff, gbase, voff) do { _Pragma("unroll") for (int _i = 0; _i < 2; ++_i) \
;         __builtin_amdgcn_global_load_lds((const unsigned*)((const char*)(gbase) + (voff)[_i]), (LAS unsigned*)(lds + (bufoff) + ldsw + _i * 8192), 16, 0, 0); } while (0)
; #define PG8_LDA(dst, b, h) do { _Pragma("unroll") for (int m = 0; m < 4; ++m) _Pragma("unroll") for (int k = 0; k < 2; ++k) dst[m][k] = *(const LAS bf16x8*)(lds + PG8_SA(b, h) + aoff + m * 2048 + k * 1024); } while (0)
; #define PG8_LDB(dst, b, h) do { _Pragma("unroll") for (int n = 0; n < 2; ++n) _Pragma("unroll") for (int k = 0; k < 2; ++k) dst[n][k] = *(const LAS bf16x8*)(lds + PG8_SB(b, h) + boff + n * 2048 + k * 1024); } while (0)
; #define PG8_MMA(ai, bj, At, Bt) do { __builtin_amdgcn_s_setprio(1); _Pragma("unroll") for (int m = 0; m < 4; ++m) _Pragma("unroll") for (int n = 0; n < 2; ++n) _Pragma("unroll") for (int k = 0; k < 2; ++k) \
;         acc[ai][bj][m][n] = __builtin_amdgcn_mfma_f32_16x16x32_bf16(Bt[n][k], At[m][k], acc[ai][bj][m][n], 0, 0, 0); __builtin_amdgcn_s_setprio(0); } while (0)
; #define PG8_WAIT_V(n) asm volatile("s_waitcnt vmcnt(" #n ")" ::: "memory")
; #define PG8_WAIT_L(n) asm volatile("s_waitcnt lgkmcnt(" #n ")" ::: "memory")
; #define PG8_BAR __builtin_amdgcn_s_barrier()
; #define PG8_SCHED __builtin_amdgcn_sched_barrier(0)
; template <class Epi, bool ALIGN_EPI = PG8_ALIGN, bool SP2 = PG8_SP2>
; __device__ __forceinline__ void gemm_phase(LAS uchar* lds, const Gemm g, const StaticOrder& S, const Epi& E) {
;     ...
;         for (int t = tb; t < tb + tblk; t += 2) {
;             const bool last = (t == nt - 2);
;             const char* a1 = cA + (size_t)(t + 1) * kstep;
;             const char* a2 = last ? nA : cA + (size_t)(t + 2) * kstep; const char* b2 = last ? nB : cB + (size_t)(t + 2) * kstep;
;     ...
;             PG8_LDB(B0, 1, 0); PG8_LDB(B1, 1, 1); PG8_SCHED; PG8_LDA(At, 1, 0); PG8_STAGE(PG8_SA(0, 1), a2 + hstepA, voffA);
;             PG8_WAIT_V(8); PG8_WAIT_L(0); PG8_BAR; PG8_MMA(0, 0, At, B0); PG8_MMA(0, 1, At, B1); PG8_BAR; PG8_SCHED;
;             PG8_LDA(At, 1, 1); PG8_STAGE(PG8_SB(1, 0), b3, voffB); PG8_STAGE(PG8_SB(1, 1), b3 + hstepB, voffB); PG8_STAGE(PG8_SA(1, 0), a3, voffA);
;             PG8_WAIT_V(8); PG8_WAIT_L(0); PG8_BAR; PG8_MMA(1, 0, At, B0); PG8_MMA(1, 1, At, B1); PG8_BAR; PG8_SCHED;
	s_add_i32 s39, 0, 0x18000
	v_add_u32_e32 v144, s39, v139
	s_add_i32 s40, 0, 0x1c000
	ds_read_b128 v[164:167], v144
	ds_read_b128 v[168:171], v144 offset:1024
	ds_read_b128 v[172:175], v144 offset:2048
	ds_read_b128 v[176:179], v144 offset:3072
	v_add_u32_e32 v144, s40, v139
	ds_read_b128 v[184:187], v144
	ds_read_b128 v[188:191], v144 offset:1024
	ds_read_b128 v[192:195], v144 offset:2048
	ds_read_b128 v[196:199], v144 offset:3072
	s_add_u32 s12, s18, 0x44000
	s_addc_u32 s13, s19, 0
	s_mov_b32 m0, s25
	v_lshl_add_u64 v[236:237], s[12:13], 0, v[154:155]
	ds_read_b128 v[200:203], v163 offset:32768
	ds_read_b128 v[204:207], v163 offset:33792
	ds_read_b128 v[208:211], v163 offset:34816
	ds_read_b128 v[212:215], v163 offset:35840
	ds_read_b128 v[216:219], v163 offset:36864
	ds_read_b128 v[220:223], v163 offset:37888
	ds_read_b128 v[224:227], v163 offset:38912
	ds_read_b128 v[228:231], v163 offset:39936
	global_load_lds_dwordx4 v[236:237], off
	s_mov_b32 m0, s26
	v_lshl_add_u64 v[236:237], s[12:13], 0, v[132:133]
	global_load_lds_dwordx4 v[236:237], off
	s_waitcnt vmcnt(8)
	s_waitcnt lgkmcnt(0)
	s_barrier
	v_mfma_f32_16x16x32_bf16 v[126:129], v[164:167], v[200:203], v[126:129]
	v_mfma_f32_16x16x32_bf16 v[118:121], v[172:175], v[200:203], v[118:121]
	v_mfma_f32_16x16x32_bf16 v[110:113], v[164:167], v[208:211], v[110:113]
	v_mfma_f32_16x16x32_bf16 v[102:105], v[172:175], v[208:211], v[102:105]
	v_mfma_f32_16x16x32_bf16 v[94:97], v[164:167], v[216:219], v[94:97]
	v_mfma_f32_16x16x32_bf16 v[86:89], v[172:175], v[216:219], v[86:89]
	v_mfma_f32_16x16x32_bf16 v[78:81], v[164:167], v[224:227], v[78:81]
	v_mfma_f32_16x16x32_bf16 v[70:73], v[172:175], v[224:227], v[70:73]
	v_mfma_f32_16x16x32_bf16 v[126:129], v[168:171], v[204:207], v[126:129]
	v_mfma_f32_16x16x32_bf16 v[118:121], v[176:179], v[204:207], v[118:121]
	v_mfma_f32_16x16x32_bf16 v[110:113], v[168:171], v[212:215], v[110:113]
	v_mfma_f32_16x16x32_bf16 v[102:105], v[176:179], v[212:215], v[102:105]
	v_mfma_f32_16x16x32_bf16 v[94:97], v[168:171], v[220:223], v[94:97]
	v_mfma_f32_16x16x32_bf16 v[86:89], v[176:179], v[220:223], v[86:89]
	v_mfma_f32_16x16x32_bf16 v[78:81], v[168:171], v[228:231], v[78:81]
	v_mfma_f32_16x16x32_bf16 v[70:73], v[176:179], v[228:231], v[70:73]
	v_mfma_f32_16x16x32_bf16 v[122:125], v[184:187], v[200:203], v[122:125]
	v_mfma_f32_16x16x32_bf16 v[114:117], v[192:195], v[200:203], v[114:117]
	v_mfma_f32_16x16x32_bf16 v[106:109], v[184:187], v[208:211], v[106:109]
	v_mfma_f32_16x16x32_bf16 v[98:101], v[192:195], v[208:211], v[98:101]
	v_mfma_f32_16x16x32_bf16 v[90:93], v[184:187], v[216:219], v[90:93]
	v_mfma_f32_16x16x32_bf16 v[82:85], v[192:195], v[216:219], v[82:85]
	v_mfma_f32_16x16x32_bf16 v[74:77], v[184:187], v[224:227], v[74:77]
	v_mfma_f32_16x16x32_bf16 v[66:69], v[192:195], v[224:227], v[66:69]
	v_mfma_f32_16x16x32_bf16 v[122:125], v[188:191], v[204:207], v[122:125]
	v_mfma_f32_16x16x32_bf16 v[114:117], v[196:199], v[204:207], v[114:117]
	v_mfma_f32_16x16x32_bf16 v[106:109], v[188:191], v[212:215], v[106:109]
	v_mfma_f32_16x16x32_bf16 v[98:101], v[196:199], v[212:215], v[98:101]
	v_mfma_f32_16x16x32_bf16 v[90:93], v[188:191], v[220:223], v[90:93]
	v_mfma_f32_16x16x32_bf16 v[82:85], v[196:199], v[220:223], v[82:85]
	v_mfma_f32_16x16x32_bf16 v[74:77], v[188:191], v[228:231], v[74:77]
	v_mfma_f32_16x16x32_bf16 v[66:69], v[196:199], v[228:231], v[66:69]
	s_barrier
	s_add_i32 s12, s39, s21
	v_lshl_add_u64 v[160:161], v[160:161], 0, s[84:85]
	s_mov_b32 m0, s12
	ds_read_b128 v[200:203], v163 offset:49152
	ds_read_b128 v[204:207], v163 offset:50176
	ds_read_b128 v[208:211], v163 offset:51200
	ds_read_b128 v[212:215], v163 offset:52224
	ds_read_b128 v[216:219], v163 offset:53248
	ds_read_b128 v[220:223], v163 offset:54272
	ds_read_b128 v[224:227], v163 offset:55296
	ds_read_b128 v[228:231], v163 offset:56320
	global_load_lds_dwordx4 v[160:161], off
	s_add_i32 m0, s12, 0x2000
	s_add_u32 s12, s16, 0x44080
	v_lshl_add_u64 v[160:161], v[180:181], 0, s[84:85]
	s_addc_u32 s13, s17, 0
	s_add_i32 s16, s40, s21
	global_load_lds_dwordx4 v[160:161], off
	s_mov_b32 m0, s16
	v_lshl_add_u64 v[160:161], s[12:13], 0, v[134:135]
	global_load_lds_dwordx4 v[160:161], off
	s_add_i32 m0, s16, 0x2000
	v_lshl_add_u64 v[160:161], s[12:13], 0, v[130:131]
	global_load_lds_dwordx4 v[160:161], off
	s_mov_b32 m0, s27
	v_lshl_add_u64 v[160:161], v[232:233], 0, s[84:85]
	global_load_lds_dwordx4 v[160:161], off
	s_mov_b32 m0, s28
	v_lshl_add_u64 v[160:161], v[234:235], 0, s[84:85]
	global_load_lds_dwordx4 v[160:161], off
	s_waitcnt vmcnt(8)
	s_waitcnt lgkmcnt(0)
	s_barrier
	v_mfma_f32_16x16x32_bf16 v[62:65], v[164:167], v[200:203], v[62:65]
	v_mfma_f32_16x16x32_bf16 v[54:57], v[172:175], v[200:203], v[54:57]
	v_mfma_f32_16x16x32_bf16 v[46:49], v[164:167], v[208:211], v[46:49]
	v_mfma_f32_16x16x32_bf16 v[38:41], v[172:175], v[208:211], v[38:41]
	v_mfma_f32_16x16x32_bf16 v[30:33], v[164:167], v[216:219], v[30:33]
	v_mfma_f32_16x16x32_bf16 v[22:25], v[172:175], v[216:219], v[22:25]
	v_mfma_f32_16x16x32_bf16 v[14:17], v[164:167], v[224:227], v[14:17]
	v_mfma_f32_16x16x32_bf16 v[6:9], v[172:175], v[224:227], v[6:9]
	v_mfma_f32_16x16x32_bf16 v[62:65], v[168:171], v[204:207], v[62:65]
	v_mfma_f32_16x16x32_bf16 v[54:57], v[176:179], v[204:207], v[54:57]
	v_mfma_f32_16x16x32_bf16 v[46:49], v[168:171], v[212:215], v[46:49]
	v_mfma_f32_16x16x32_bf16 v[38:41], v[176:179], v[212:215], v[38:41]
	v_mfma_f32_16x16x32_bf16 v[30:33], v[168:171], v[220:223], v[30:33]
	v_mfma_f32_16x16x32_bf16 v[22:25], v[176:179], v[220:223], v[22:25]
	v_mfma_f32_16x16x32_bf16 v[14:17], v[168:171], v[228:231], v[14:17]
	v_mfma_f32_16x16x32_bf16 v[6:9], v[176:179], v[228:231], v[6:9]
	v_mfma_f32_16x16x32_bf16 v[58:61], v[184:187], v[200:203], v[58:61]
	v_mfma_f32_16x16x32_bf16 v[50:53], v[192:195], v[200:203], v[50:53]
	v_mfma_f32_16x16x32_bf16 v[42:45], v[184:187], v[208:211], v[42:45]
	v_mfma_f32_16x16x32_bf16 v[34:37], v[192:195], v[208:211], v[34:37]
	v_mfma_f32_16x16x32_bf16 v[26:29], v[184:187], v[216:219], v[26:29]
	v_mfma_f32_16x16x32_bf16 v[18:21], v[192:195], v[216:219], v[18:21]
	v_mfma_f32_16x16x32_bf16 v[10:13], v[184:187], v[224:227], v[10:13]
	v_mfma_f32_16x16x32_bf16 v[2:5], v[192:195], v[224:227], v[2:5]
	v_mfma_f32_16x16x32_bf16 v[58:61], v[188:191], v[204:207], v[58:61]
	v_mfma_f32_16x16x32_bf16 v[50:53], v[196:199], v[204:207], v[50:53]
	v_mfma_f32_16x16x32_bf16 v[42:45], v[188:191], v[212:215], v[42:45]
	v_mfma_f32_16x16x32_bf16 v[34:37], v[196:199], v[212:215], v[34:37]
	v_mfma_f32_16x16x32_bf16 v[26:29], v[188:191], v[220:223], v[26:29]
	v_mfma_f32_16x16x32_bf16 v[18:21], v[196:199], v[220:223], v[18:21]
	v_mfma_f32_16x16x32_bf16 v[10:13], v[188:191], v[228:231], v[10:13]
	v_mfma_f32_16x16x32_bf16 v[2:5], v[196:199], v[228:231], v[2:5]
	s_barrier
	s_add_i32 s38, s38, 2
	s_add_u32 s36, s36, 0x100
	s_addc_u32 s37, s37, 0
	s_cmp_gt_u32 s38, 13
	s_mov_b64 s[12:13], s[14:15]
	s_cbranch_scc0 .LBB0_1050
	s_and_b64 vcc, exec, s[8:9]
	s_cbranch_vccz .LBB0_1053
	s_barrier

; #define PG8_STAGE(bufoff, gbase, voff) do { _Pragma("unroll") for (int _i = 0; _i < 2; ++_i) \
;         __builtin_amdgcn_global_load_lds((const unsigned*)((const char*)(gbase) + (voff)[_i]), (LAS unsigned*)(lds + (bufoff) + ldsw + _i * 8192), 16, 0, 0); } while (0)
; #define PG8_LDA(dst, b, h) do { _Pragma("unroll") for (int m = 0; m < 4; ++m) _Pragma("unroll") for (int k = 0; k < 2; ++k) dst[m][k] = *(const LAS bf16x8*)(lds + PG8_SA(b, h) + aoff + m * 2048 + k * 1024); } while (0)
; #define PG8_LDB(dst, b, h) do { _Pragma("unroll") for (int n = 0; n < 2; ++n) _Pragma("unroll") for (int k = 0; k < 2; ++k) dst[n][k] = *(const LAS bf16x8*)(lds + PG8_SB(b, h) + boff + n * 2048 + k * 1024); } while (0)
; #define PG8_MMA(ai, bj, At, Bt) do { __builtin_amdgcn_s_setprio(1); _Pragma("unroll") for (int m = 0; m < 4; ++m) _Pragma("unroll") for (int n = 0; n < 2; ++n) _Pragma("unroll") for (int k = 0; k < 2; ++k) \
;         acc[ai][bj][m][n] = __builtin_amdgcn_mfma_f32_16x16x32_bf16(Bt[n][k], At[m][k], acc[ai][bj][m][n], 0, 0, 0); __builtin_amdgcn_s_setprio(0); } while (0)
; #define PG8_WAIT_V(n) asm volatile("s_waitcnt vmcnt(" #n ")" ::: "memory")
; #define PG8_WAIT_L(n) asm volatile("s_waitcnt lgkmcnt(" #n ")" ::: "memory")
; #define PG8_BAR __builtin_amdgcn_s_barrier()
; #define PG8_SCHED __builtin_amdgcn_sched_barrier(0)
; template <class Epi, bool ALIGN_EPI = PG8_ALIGN, bool SP2 = PG8_SP2>
; __device__ __forceinline__ void gemm_phase(LAS uchar* lds, const Gemm g, const StaticOrder& S, const Epi& E) {
;     ...
;             PG8_LDB(B0, 0, 0); PG8_LDB(B1, 0, 1); PG8_SCHED; PG8_LDA(At, 0, 0); PG8_STAGE(PG8_SA(1, 1), a1 + hstepA, voffA);
;             PG8_WAIT_V(8); PG8_WAIT_L(0); PG8_BAR; PG8_MMA(0, 0, At, B0); PG8_MMA(0, 1, At, B1); PG8_BAR; PG8_SCHED;
;             PG8_LDA(At, 0, 1); PG8_STAGE(PG8_SB(0, 0), b2, voffB); PG8_STAGE(PG8_SB(0, 1), b2 + hstepB, voffB); PG8_STAGE(PG8_SA(0, 0), a2, voffA);
;             PG8_WAIT_V(8); PG8_WAIT_L(0); PG8_BAR; PG8_MMA(1, 0, At, B0); PG8_MMA(1, 1, At, B1); PG8_BAR; PG8_SCHED;
;     ...
; #pragma unroll
;         for (int a = 0; a < 2; ++a)
; #pragma unroll
;             for (int b = 0; b < 2; ++b)
; #pragma unroll
;                 for (int m = 0; m < 4; ++m)
; #pragma unroll
;                     for (int n = 0; n < 2; ++n) acc[a][b][m][n] = (f32x4){0.f, 0.f, 0.f, 0.f};
.LBB0_1142:
	s_add_u32 s38, s16, 0x100
	s_addc_u32 s39, s17, 0
	s_mov_b32 s40, -2
	s_add_u32 s16, s14, 0x100
	s_addc_u32 s17, s15, 0
	s_add_i32 s41, 0, 0x10000
	s_cmp_eq_u32 s40, 40
	s_cselect_b32 s21, s5, s17
	s_cselect_b32 s20, s4, s16
	v_add_u32_e32 v144, s41, v139
	s_cselect_b32 s19, s13, s39
	s_cselect_b32 s18, s12, s38
	s_add_i32 s42, 0, 0x14000
	ds_read_b128 v[160:163], v144
	ds_read_b128 v[166:169], v144 offset:1024
	ds_read_b128 v[170:173], v144 offset:2048
	ds_read_b128 v[174:177], v144 offset:3072
	v_add_u32_e32 v144, s42, v139
	ds_read_b128 v[178:181], v144
	ds_read_b128 v[184:187], v144 offset:1024
	ds_read_b128 v[188:191], v144 offset:2048
	ds_read_b128 v[192:195], v144 offset:3072
	v_lshl_add_u64 v[228:229], s[14:15], 0, v[156:157]
	s_add_i32 m0, s25, 0xc000
	ds_read_b128 v[196:199], v165
	ds_read_b128 v[200:203], v165 offset:1024
	ds_read_b128 v[204:207], v165 offset:2048
	ds_read_b128 v[208:211], v165 offset:3072
	ds_read_b128 v[212:215], v165 offset:4096
	ds_read_b128 v[216:219], v165 offset:5120
	ds_read_b128 v[220:223], v165 offset:6144
	ds_read_b128 v[224:227], v165 offset:7168
	global_load_lds_dwordx4 v[228:229], off
	s_add_i32 m0, s25, 0xe000
	v_lshl_add_u64 v[228:229], s[14:15], 0, v[158:159]
	global_load_lds_dwordx4 v[228:229], off
	s_waitcnt vmcnt(8)
	s_waitcnt lgkmcnt(0)
	s_barrier
	v_mfma_f32_16x16x32_bf16 v[126:129], v[160:163], v[196:199], 0
	v_mfma_f32_16x16x32_bf16 v[122:125], v[170:173], v[196:199], 0
	v_mfma_f32_16x16x32_bf16 v[118:121], v[160:163], v[204:207], 0
	v_mfma_f32_16x16x32_bf16 v[110:113], v[170:173], v[204:207], 0
	v_mfma_f32_16x16x32_bf16 v[102:105], v[160:163], v[212:215], 0
	v_mfma_f32_16x16x32_bf16 v[94:97], v[170:173], v[212:215], 0
	v_mfma_f32_16x16x32_bf16 v[86:89], v[160:163], v[220:223], 0
	v_mfma_f32_16x16x32_bf16 v[78:81], v[170:173], v[220:223], 0
	v_mfma_f32_16x16x32_bf16 v[126:129], v[166:169], v[200:203], v[126:129]
	v_mfma_f32_16x16x32_bf16 v[122:125], v[174:177], v[200:203], v[122:125]
	v_mfma_f32_16x16x32_bf16 v[118:121], v[166:169], v[208:211], v[118:121]
	v_mfma_f32_16x16x32_bf16 v[110:113], v[174:177], v[208:211], v[110:113]
	v_mfma_f32_16x16x32_bf16 v[102:105], v[166:169], v[216:219], v[102:105]
	v_mfma_f32_16x16x32_bf16 v[94:97], v[174:177], v[216:219], v[94:97]
	v_mfma_f32_16x16x32_bf16 v[86:89], v[166:169], v[224:227], v[86:89]
	v_mfma_f32_16x16x32_bf16 v[78:81], v[174:177], v[224:227], v[78:81]
	v_mfma_f32_16x16x32_bf16 v[114:117], v[178:181], v[196:199], 0
	v_mfma_f32_16x16x32_bf16 v[106:109], v[188:191], v[196:199], 0
	v_mfma_f32_16x16x32_bf16 v[98:101], v[178:181], v[204:207], 0
	v_mfma_f32_16x16x32_bf16 v[90:93], v[188:191], v[204:207], 0
	v_mfma_f32_16x16x32_bf16 v[82:85], v[178:181], v[212:215], 0
	v_mfma_f32_16x16x32_bf16 v[74:77], v[188:191], v[212:215], 0
	v_mfma_f32_16x16x32_bf16 v[70:73], v[178:181], v[220:223], 0
	v_mfma_f32_16x16x32_bf16 v[66:69], v[188:191], v[220:223], 0
	v_mfma_f32_16x16x32_bf16 v[114:117], v[184:187], v[200:203], v[114:117]
	v_mfma_f32_16x16x32_bf16 v[106:109], v[192:195], v[200:203], v[106:109]
	v_mfma_f32_16x16x32_bf16 v[98:101], v[184:187], v[208:211], v[98:101]
	v_mfma_f32_16x16x32_bf16 v[90:93], v[192:195], v[208:211], v[90:93]
	v_mfma_f32_16x16x32_bf16 v[82:85], v[184:187], v[216:219], v[82:85]
	v_mfma_f32_16x16x32_bf16 v[74:77], v[192:195], v[216:219], v[74:77]
	v_mfma_f32_16x16x32_bf16 v[70:73], v[184:187], v[224:227], v[70:73]
	v_mfma_f32_16x16x32_bf16 v[66:69], v[192:195], v[224:227], v[66:69]
	s_barrier
	s_add_i32 s14, s41, s24
	v_lshl_add_u64 v[228:229], s[18:19], 0, v[132:133]
	s_mov_b32 m0, s14
	ds_read_b128 v[196:199], v165 offset:16384
	ds_read_b128 v[200:203], v165 offset:17408
	ds_read_b128 v[204:207], v165 offset:18432
	ds_read_b128 v[208:211], v165 offset:19456
	ds_read_b128 v[212:215], v165 offset:20480
	ds_read_b128 v[216:219], v165 offset:21504
	ds_read_b128 v[220:223], v165 offset:22528
	ds_read_b128 v[224:227], v165 offset:23552
	global_load_lds_dwordx4 v[228:229], off
	s_add_i32 m0, s14, 0x2000
	s_add_u32 s14, s18, 0xb0000
	v_lshl_add_u64 v[230:231], s[18:19], 0, v[154:155]
	s_addc_u32 s15, s19, 0
	s_add_i32 s41, s42, s24
	global_load_lds_dwordx4 v[230:231], off
	v_lshl_add_u64 v[232:233], s[14:15], 0, v[132:133]
	s_mov_b32 m0, s41
	global_load_lds_dwordx4 v[232:233], off
	s_add_i32 m0, s41, 0x2000
	v_lshl_add_u64 v[232:233], s[14:15], 0, v[154:155]
	global_load_lds_dwordx4 v[232:233], off
	s_mov_b32 m0, s25
	v_lshl_add_u64 v[232:233], s[20:21], 0, v[130:131]
	global_load_lds_dwordx4 v[232:233], off
	s_mov_b32 m0, s26
	v_lshl_add_u64 v[234:235], s[20:21], 0, v[134:135]
	global_load_lds_dwordx4 v[234:235], off
	s_waitcnt vmcnt(8)
	s_waitcnt lgkmcnt(0)
	s_barrier
; #define PG8_STAGE(bufoff, gbase, voff) do { _Pragma("unroll") for (int _i = 0; _i < 2; ++_i) \
;         __builtin_amdgcn_global_load_lds((const unsigned*)((const char*)(gbase) + (voff)[_i]), (LAS unsigned*)(lds + (bufoff) + ldsw + _i * 8192), 16, 0, 0); } while (0)
; #define PG8_LDA(dst, b, h) do { _Pragma("unroll") for (int m = 0; m < 4; ++m) _Pragma("unroll") for (int k = 0; k < 2; ++k) dst[m][k] = *(const LAS bf16x8*)(lds + PG8_SA(b, h) + aoff + m * 2048 + k * 1024); } while (0)
; #define PG8_LDB(dst, b, h) do { _Pragma("unroll") for (int n = 0; n < 2; ++n) _Pragma("unroll") for (int k = 0; k < 2; ++k) dst[n][k] = *(const LAS bf16x8*)(lds + PG8_SB(b, h) + boff + n * 2048 + k * 1024); } while (0)
; #define PG8_MMA(ai, bj, At, Bt) do { __builtin_amdgcn_s_setprio(1); _Pragma("unroll") for (int m = 0; m < 4; ++m) _Pragma("unroll") for (int n = 0; n < 2; ++n) _Pragma("unroll") for (int k = 0; k < 2; ++k) \
;         acc[ai][bj][m][n] = __builtin_amdgcn_mfma_f32_16x16x32_bf16(Bt[n][k], At[m][k], acc[ai][bj][m][n], 0, 0, 0); __builtin_amdgcn_s_setprio(0); } while (0)
; #define PG8_WAIT_V(n) asm volatile("s_waitcnt vmcnt(" #n ")" ::: "memory")
; #define PG8_WAIT_L(n) asm volatile("s_waitcnt lgkmcnt(" #n ")" ::: "memory")
; #define PG8_BAR __builtin_amdgcn_s_barrier()
; #define PG8_SCHED __builtin_amdgcn_sched_barrier(0)
; template <class Epi, bool ALIGN_EPI = PG8_ALIGN, bool SP2 = PG8_SP2>
; __device__ __forceinline__ void gemm_phase(LAS uchar* lds, const Gemm g, const StaticOrder& S, const Epi& E) {
;     ...
;             PG8_WAIT_V(8); PG8_WAIT_L(0); PG8_BAR; PG8_MMA(1, 0, At, B0); PG8_MMA(1, 1, At, B1); PG8_BAR; PG8_SCHED;
;             PG8_LDB(B0, 1, 0); PG8_LDB(B1, 1, 1); PG8_SCHED; PG8_LDA(At, 1, 0); PG8_STAGE(PG8_SA(0, 1), a2 + hstepA, voffA);
;             PG8_WAIT_V(8); PG8_WAIT_L(0); PG8_BAR; PG8_MMA(0, 0, At, B0); PG8_MMA(0, 1, At, B1); PG8_BAR; PG8_SCHED;
	v_mfma_f32_16x16x32_bf16 v[62:65], v[160:163], v[196:199], 0
	v_mfma_f32_16x16x32_bf16 v[58:61], v[170:173], v[196:199], 0
	v_mfma_f32_16x16x32_bf16 v[54:57], v[160:163], v[204:207], 0
	v_mfma_f32_16x16x32_bf16 v[46:49], v[170:173], v[204:207], 0
	v_mfma_f32_16x16x32_bf16 v[38:41], v[160:163], v[212:215], 0
	v_mfma_f32_16x16x32_bf16 v[30:33], v[170:173], v[212:215], 0
	v_mfma_f32_16x16x32_bf16 v[22:25], v[160:163], v[220:223], 0
	v_mfma_f32_16x16x32_bf16 v[14:17], v[170:173], v[220:223], 0
	v_mfma_f32_16x16x32_bf16 v[62:65], v[166:169], v[200:203], v[62:65]
	v_mfma_f32_16x16x32_bf16 v[58:61], v[174:177], v[200:203], v[58:61]
	v_mfma_f32_16x16x32_bf16 v[54:57], v[166:169], v[208:211], v[54:57]
	v_mfma_f32_16x16x32_bf16 v[46:49], v[174:177], v[208:211], v[46:49]
	v_mfma_f32_16x16x32_bf16 v[38:41], v[166:169], v[216:219], v[38:41]
	v_mfma_f32_16x16x32_bf16 v[30:33], v[174:177], v[216:219], v[30:33]
	v_mfma_f32_16x16x32_bf16 v[22:25], v[166:169], v[224:227], v[22:25]
	v_mfma_f32_16x16x32_bf16 v[14:17], v[174:177], v[224:227], v[14:17]
	v_mfma_f32_16x16x32_bf16 v[50:53], v[178:181], v[196:199], 0
	v_mfma_f32_16x16x32_bf16 v[42:45], v[188:191], v[196:199], 0
	v_mfma_f32_16x16x32_bf16 v[34:37], v[178:181], v[204:207], 0
	v_mfma_f32_16x16x32_bf16 v[26:29], v[188:191], v[204:207], 0
	v_mfma_f32_16x16x32_bf16 v[18:21], v[178:181], v[212:215], 0
	v_mfma_f32_16x16x32_bf16 v[10:13], v[188:191], v[212:215], 0
	v_mfma_f32_16x16x32_bf16 v[6:9], v[178:181], v[220:223], 0
	v_mfma_f32_16x16x32_bf16 v[2:5], v[188:191], v[220:223], 0
	v_mfma_f32_16x16x32_bf16 v[50:53], v[184:187], v[200:203], v[50:53]
	v_mfma_f32_16x16x32_bf16 v[42:45], v[192:195], v[200:203], v[42:45]
	v_mfma_f32_16x16x32_bf16 v[34:37], v[184:187], v[208:211], v[34:37]
	v_mfma_f32_16x16x32_bf16 v[26:29], v[192:195], v[208:211], v[26:29]
	v_mfma_f32_16x16x32_bf16 v[18:21], v[184:187], v[216:219], v[18:21]
	v_mfma_f32_16x16x32_bf16 v[10:13], v[192:195], v[216:219], v[10:13]
	v_mfma_f32_16x16x32_bf16 v[6:9], v[184:187], v[224:227], v[6:9]
	v_mfma_f32_16x16x32_bf16 v[2:5], v[192:195], v[224:227], v[2:5]
	s_barrier
	s_add_i32 s41, 0, 0x18000
	v_add_u32_e32 v144, s41, v139
	s_add_i32 s42, 0, 0x1c000
	ds_read_b128 v[160:163], v144
	ds_read_b128 v[166:169], v144 offset:1024
	ds_read_b128 v[170:173], v144 offset:2048
	ds_read_b128 v[174:177], v144 offset:3072
	v_add_u32_e32 v144, s42, v139
	ds_read_b128 v[178:181], v144
	ds_read_b128 v[184:187], v144 offset:1024
	ds_read_b128 v[188:191], v144 offset:2048
	ds_read_b128 v[192:195], v144 offset:3072
	s_add_u32 s14, s20, 0xb0000
	s_addc_u32 s15, s21, 0
	s_mov_b32 m0, s27
	v_lshl_add_u64 v[236:237], s[14:15], 0, v[130:131]
	ds_read_b128 v[196:199], v165 offset:32768
	ds_read_b128 v[200:203], v165 offset:33792
	ds_read_b128 v[204:207], v165 offset:34816
	ds_read_b128 v[208:211], v165 offset:35840
	ds_read_b128 v[212:215], v165 offset:36864
	ds_read_b128 v[216:219], v165 offset:37888
	ds_read_b128 v[220:223], v165 offset:38912
	ds_read_b128 v[224:227], v165 offset:39936
	global_load_lds_dwordx4 v[236:237], off
	s_mov_b32 m0, s28
	v_lshl_add_u64 v[236:237], s[14:15], 0, v[134:135]
	global_load_lds_dwordx4 v[236:237], off
	s_waitcnt vmcnt(8)
	s_waitcnt lgkmcnt(0)
	s_barrier
	v_mfma_f32_16x16x32_bf16 v[126:129], v[160:163], v[196:199], v[126:129]
	v_mfma_f32_16x16x32_bf16 v[122:125], v[170:173], v[196:199], v[122:125]
	v_mfma_f32_16x16x32_bf16 v[118:121], v[160:163], v[204:207], v[118:121]
	v_mfma_f32_16x16x32_bf16 v[110:113], v[170:173], v[204:207], v[110:113]
	v_mfma_f32_16x16x32_bf16 v[102:105], v[160:163], v[212:215], v[102:105]
	v_mfma_f32_16x16x32_bf16 v[94:97], v[170:173], v[212:215], v[94:97]
	v_mfma_f32_16x16x32_bf16 v[86:89], v[160:163], v[220:223], v[86:89]
	v_mfma_f32_16x16x32_bf16 v[78:81], v[170:173], v[220:223], v[78:81]
	v_mfma_f32_16x16x32_bf16 v[126:129], v[166:169], v[200:203], v[126:129]
	v_mfma_f32_16x16x32_bf16 v[122:125], v[174:177], v[200:203], v[122:125]
	v_mfma_f32_16x16x32_bf16 v[118:121], v[166:169], v[208:211], v[118:121]
	v_mfma_f32_16x16x32_bf16 v[110:113], v[174:177], v[208:211], v[110:113]
	v_mfma_f32_16x16x32_bf16 v[102:105], v[166:169], v[216:219], v[102:105]
	v_mfma_f32_16x16x32_bf16 v[94:97], v[174:177], v[216:219], v[94:97]
	v_mfma_f32_16x16x32_bf16 v[86:89], v[166:169], v[224:227], v[86:89]
	v_mfma_f32_16x16x32_bf16 v[78:81], v[174:177], v[224:227], v[78:81]
	v_mfma_f32_16x16x32_bf16 v[114:117], v[178:181], v[196:199], v[114:117]
	v_mfma_f32_16x16x32_bf16 v[106:109], v[188:191], v[196:199], v[106:109]
	v_mfma_f32_16x16x32_bf16 v[98:101], v[178:181], v[204:207], v[98:101]
	v_mfma_f32_16x16x32_bf16 v[90:93], v[188:191], v[204:207], v[90:93]
	v_mfma_f32_16x16x32_bf16 v[82:85], v[178:181], v[212:215], v[82:85]
	v_mfma_f32_16x16x32_bf16 v[74:77], v[188:191], v[212:215], v[74:77]
	v_mfma_f32_16x16x32_bf16 v[70:73], v[178:181], v[220:223], v[70:73]
	v_mfma_f32_16x16x32_bf16 v[66:69], v[188:191], v[220:223], v[66:69]
	v_mfma_f32_16x16x32_bf16 v[114:117], v[184:187], v[200:203], v[114:117]
	v_mfma_f32_16x16x32_bf16 v[106:109], v[192:195], v[200:203], v[106:109]
	v_mfma_f32_16x16x32_bf16 v[98:101], v[184:187], v[208:211], v[98:101]
	v_mfma_f32_16x16x32_bf16 v[90:93], v[192:195], v[208:211], v[90:93]
	v_mfma_f32_16x16x32_bf16 v[82:85], v[184:187], v[216:219], v[82:85]
	v_mfma_f32_16x16x32_bf16 v[74:77], v[192:195], v[216:219], v[74:77]
	v_mfma_f32_16x16x32_bf16 v[70:73], v[184:187], v[224:227], v[70:73]
	v_mfma_f32_16x16x32_bf16 v[66:69], v[192:195], v[224:227], v[66:69]
	s_barrier
; #define PG8_STAGE(bufoff, gbase, voff) do { _Pragma("unroll") for (int _i = 0; _i < 2; ++_i) \
;         __builtin_amdgcn_global_load_lds((const unsigned*)((const char*)(gbase) + (voff)[_i]), (LAS unsigned*)(lds + (bufoff) + ldsw + _i * 8192), 16, 0, 0); } while (0)
; #define PG8_LDA(dst, b, h) do { _Pragma("unroll") for (int m = 0; m < 4; ++m) _Pragma("unroll") for (int k = 0; k < 2; ++k) dst[m][k] = *(const LAS bf16x8*)(lds + PG8_SA(b, h) + aoff + m * 2048 + k * 1024); } while (0)
; #define PG8_LDB(dst, b, h) do { _Pragma("unroll") for (int n = 0; n < 2; ++n) _Pragma("unroll") for (int k = 0; k < 2; ++k) dst[n][k] = *(const LAS bf16x8*)(lds + PG8_SB(b, h) + boff + n * 2048 + k * 1024); } while (0)
; #define PG8_MMA(ai, bj, At, Bt) do { __builtin_amdgcn_s_setprio(1); _Pragma("unroll") for (int m = 0; m < 4; ++m) _Pragma("unroll") for (int n = 0; n < 2; ++n) _Pragma("unroll") for (int k = 0; k < 2; ++k) \
;         acc[ai][bj][m][n] = __builtin_amdgcn_mfma_f32_16x16x32_bf16(Bt[n][k], At[m][k], acc[ai][bj][m][n], 0, 0, 0); __builtin_amdgcn_s_setprio(0); } while (0)
; #define PG8_WAIT_V(n) asm volatile("s_waitcnt vmcnt(" #n ")" ::: "memory")
; #define PG8_WAIT_L(n) asm volatile("s_waitcnt lgkmcnt(" #n ")" ::: "memory")
; #define PG8_BAR __builtin_amdgcn_s_barrier()
; #define PG8_SCHED __builtin_amdgcn_sched_barrier(0)
; template <class Epi, bool ALIGN_EPI = PG8_ALIGN, bool SP2 = PG8_SP2>
; __device__ __forceinline__ void gemm_phase(LAS uchar* lds, const Gemm g, const StaticOrder& S, const Epi& E) {
;     ...
;             PG8_LDB(B0, 0, 0); PG8_LDB(B1, 0, 1); PG8_SCHED; PG8_LDA(At, 0, 0); PG8_STAGE(PG8_SA(1, 1), a1 + hstepA, voffA);
;             PG8_WAIT_V(8); PG8_WAIT_L(0); PG8_BAR; PG8_MMA(0, 0, At, B0); PG8_MMA(0, 1, At, B1); PG8_BAR; PG8_SCHED;
;     ...
;             PG8_LDA(At, 1, 1); PG8_STAGE(PG8_SB(1, 0), b3, voffB); PG8_STAGE(PG8_SB(1, 1), b3 + hstepB, voffB); PG8_STAGE(PG8_SA(1, 0), a3, voffA);
;             PG8_WAIT_V(8); PG8_WAIT_L(0); PG8_BAR; PG8_MMA(1, 0, At, B0); PG8_MMA(1, 1, At, B1); PG8_BAR; PG8_SCHED;
	s_add_i32 s14, s41, s24
	v_lshl_add_u64 v[228:229], v[228:229], 0, s[84:85]
	s_mov_b32 m0, s14
	ds_read_b128 v[196:199], v165 offset:49152
	ds_read_b128 v[200:203], v165 offset:50176
	ds_read_b128 v[204:207], v165 offset:51200
	ds_read_b128 v[208:211], v165 offset:52224
	ds_read_b128 v[212:215], v165 offset:53248
	ds_read_b128 v[216:219], v165 offset:54272
	ds_read_b128 v[220:223], v165 offset:55296
	ds_read_b128 v[224:227], v165 offset:56320
	global_load_lds_dwordx4 v[228:229], off
	s_add_i32 m0, s14, 0x2000
	s_add_u32 s14, s18, 0xb0080
	v_lshl_add_u64 v[228:229], v[230:231], 0, s[84:85]
	s_addc_u32 s15, s19, 0
	s_add_i32 s18, s42, s24
	global_load_lds_dwordx4 v[228:229], off
	s_mov_b32 m0, s18
	v_lshl_add_u64 v[228:229], s[14:15], 0, v[132:133]
	global_load_lds_dwordx4 v[228:229], off
	s_add_i32 m0, s18, 0x2000
	v_lshl_add_u64 v[228:229], s[14:15], 0, v[154:155]
	global_load_lds_dwordx4 v[228:229], off
	s_mov_b32 m0, s29
	v_lshl_add_u64 v[228:229], v[232:233], 0, s[84:85]
	global_load_lds_dwordx4 v[228:229], off
	s_mov_b32 m0, s30
	v_lshl_add_u64 v[228:229], v[234:235], 0, s[84:85]
	global_load_lds_dwordx4 v[228:229], off
	s_waitcnt vmcnt(8)
	s_waitcnt lgkmcnt(0)
	s_barrier
	v_mfma_f32_16x16x32_bf16 v[62:65], v[160:163], v[196:199], v[62:65]
	v_mfma_f32_16x16x32_bf16 v[58:61], v[170:173], v[196:199], v[58:61]
	v_mfma_f32_16x16x32_bf16 v[54:57], v[160:163], v[204:207], v[54:57]
	v_mfma_f32_16x16x32_bf16 v[46:49], v[170:173], v[204:207], v[46:49]
	v_mfma_f32_16x16x32_bf16 v[38:41], v[160:163], v[212:215], v[38:41]
	v_mfma_f32_16x16x32_bf16 v[30:33], v[170:173], v[212:215], v[30:33]
	v_mfma_f32_16x16x32_bf16 v[22:25], v[160:163], v[220:223], v[22:25]
	v_mfma_f32_16x16x32_bf16 v[14:17], v[170:173], v[220:223], v[14:17]
	v_mfma_f32_16x16x32_bf16 v[62:65], v[166:169], v[200:203], v[62:65]
	v_mfma_f32_16x16x32_bf16 v[58:61], v[174:177], v[200:203], v[58:61]
	v_mfma_f32_16x16x32_bf16 v[54:57], v[166:169], v[208:211], v[54:57]
	v_mfma_f32_16x16x32_bf16 v[46:49], v[174:177], v[208:211], v[46:49]
	v_mfma_f32_16x16x32_bf16 v[38:41], v[166:169], v[216:219], v[38:41]
	v_mfma_f32_16x16x32_bf16 v[30:33], v[174:177], v[216:219], v[30:33]
	v_mfma_f32_16x16x32_bf16 v[22:25], v[166:169], v[224:227], v[22:25]
	v_mfma_f32_16x16x32_bf16 v[14:17], v[174:177], v[224:227], v[14:17]
	v_mfma_f32_16x16x32_bf16 v[50:53], v[178:181], v[196:199], v[50:53]
	v_mfma_f32_16x16x32_bf16 v[42:45], v[188:191], v[196:199], v[42:45]
	v_mfma_f32_16x16x32_bf16 v[34:37], v[178:181], v[204:207], v[34:37]
	v_mfma_f32_16x16x32_bf16 v[26:29], v[188:191], v[204:207], v[26:29]
	v_mfma_f32_16x16x32_bf16 v[18:21], v[178:181], v[212:215], v[18:21]
	v_mfma_f32_16x16x32_bf16 v[10:13], v[188:191], v[212:215], v[10:13]
	v_mfma_f32_16x16x32_bf16 v[6:9], v[178:181], v[220:223], v[6:9]
	v_mfma_f32_16x16x32_bf16 v[2:5], v[188:191], v[220:223], v[2:5]
	v_mfma_f32_16x16x32_bf16 v[50:53], v[184:187], v[200:203], v[50:53]
	v_mfma_f32_16x16x32_bf16 v[42:45], v[192:195], v[200:203], v[42:45]
	v_mfma_f32_16x16x32_bf16 v[34:37], v[184:187], v[208:211], v[34:37]
	v_mfma_f32_16x16x32_bf16 v[26:29], v[192:195], v[208:211], v[26:29]
	v_mfma_f32_16x16x32_bf16 v[18:21], v[184:187], v[216:219], v[18:21]
	v_mfma_f32_16x16x32_bf16 v[10:13], v[192:195], v[216:219], v[10:13]
	v_mfma_f32_16x16x32_bf16 v[6:9], v[184:187], v[224:227], v[6:9]
	v_mfma_f32_16x16x32_bf16 v[2:5], v[192:195], v[224:227], v[2:5]
	s_barrier
	s_add_i32 s40, s40, 2
	s_add_u32 s38, s38, 0x100
	s_addc_u32 s39, s39, 0
	s_cmp_gt_u32 s40, 41
	s_mov_b64 s[14:15], s[16:17]
.LBB0_1143:
	s_add_u32 s16, s14, 0x100
	s_addc_u32 s17, s15, 0
	s_add_i32 s41, 0, 0x10000
	s_cmp_eq_u32 s40, 40
	s_cselect_b32 s21, s5, s17
	s_cselect_b32 s20, s4, s16
	v_add_u32_e32 v144, s41, v139
	s_cselect_b32 s19, s13, s39
	s_cselect_b32 s18, s12, s38
	s_add_i32 s42, 0, 0x14000
	ds_read_b128 v[160:163], v144
	ds_read_b128 v[166:169], v144 offset:1024
	ds_read_b128 v[170:173], v144 offset:2048
	ds_read_b128 v[174:177], v144 offset:3072
	v_add_u32_e32 v144, s42, v139
	ds_read_b128 v[178:181], v144
	ds_read_b128 v[184:187], v144 offset:1024
	ds_read_b128 v[188:191], v144 offset:2048
	ds_read_b128 v[192:195], v144 offset:3072
	v_lshl_add_u64 v[228:229], s[14:15], 0, v[156:157]
	s_add_i32 m0, s25, 0xc000
	ds_read_b128 v[196:199], v165
	ds_read_b128 v[200:203], v165 offset:1024
	ds_read_b128 v[204:207], v165 offset:2048
	ds_read_b128 v[208:211], v165 offset:3072
	ds_read_b128 v[212:215], v165 offset:4096
	ds_read_b128 v[216:219], v165 offset:5120
	ds_read_b128 v[220:223], v165 offset:6144
	ds_read_b128 v[224:227], v165 offset:7168
	global_load_lds_dwordx4 v[228:229], off
	s_add_i32 m0, s25, 0xe000
	v_lshl_add_u64 v[228:229], s[14:15], 0, v[158:159]
	global_load_lds_dwordx4 v[228:229], off
	s_waitcnt vmcnt(8)
	s_waitcnt lgkmcnt(0)
	s_barrier
; #define PG8_STAGE(bufoff, gbase, voff) do { _Pragma("unroll") for (int _i = 0; _i < 2; ++_i) \
;         __builtin_amdgcn_global_load_lds((const unsigned*)((const char*)(gbase) + (voff)[_i]), (LAS unsigned*)(lds + (bufoff) + ldsw + _i * 8192), 16, 0, 0); } while (0)
; #define PG8_LDA(dst, b, h) do { _Pragma("unroll") for (int m = 0; m < 4; ++m) _Pragma("unroll") for (int k = 0; k < 2; ++k) dst[m][k] = *(const LAS bf16x8*)(lds + PG8_SA(b, h) + aoff + m * 2048 + k * 1024); } while (0)
; #define PG8_MMA(ai, bj, At, Bt) do { __builtin_amdgcn_s_setprio(1); _Pragma("unroll") for (int m = 0; m < 4; ++m) _Pragma("unroll") for (int n = 0; n < 2; ++n) _Pragma("unroll") for (int k = 0; k < 2; ++k) \
;         acc[ai][bj][m][n] = __builtin_amdgcn_mfma_f32_16x16x32_bf16(Bt[n][k], At[m][k], acc[ai][bj][m][n], 0, 0, 0); __builtin_amdgcn_s_setprio(0); } while (0)
; #define PG8_WAIT_V(n) asm volatile("s_waitcnt vmcnt(" #n ")" ::: "memory")
; #define PG8_WAIT_L(n) asm volatile("s_waitcnt lgkmcnt(" #n ")" ::: "memory")
; #define PG8_BAR __builtin_amdgcn_s_barrier()
; #define PG8_SCHED __builtin_amdgcn_sched_barrier(0)
; template <class Epi, bool ALIGN_EPI = PG8_ALIGN, bool SP2 = PG8_SP2>
; __device__ __forceinline__ void gemm_phase(LAS uchar* lds, const Gemm g, const StaticOrder& S, const Epi& E) {
;     ...
;             PG8_WAIT_V(8); PG8_WAIT_L(0); PG8_BAR; PG8_MMA(0, 0, At, B0); PG8_MMA(0, 1, At, B1); PG8_BAR; PG8_SCHED;
;             PG8_LDA(At, 0, 1); PG8_STAGE(PG8_SB(0, 0), b2, voffB); PG8_STAGE(PG8_SB(0, 1), b2 + hstepB, voffB); PG8_STAGE(PG8_SA(0, 0), a2, voffA);
;             PG8_WAIT_V(8); PG8_WAIT_L(0); PG8_BAR; PG8_MMA(1, 0, At, B0); PG8_MMA(1, 1, At, B1); PG8_BAR; PG8_SCHED;
	v_mfma_f32_16x16x32_bf16 v[126:129], v[160:163], v[196:199], v[126:129]
	v_mfma_f32_16x16x32_bf16 v[122:125], v[170:173], v[196:199], v[122:125]
	v_mfma_f32_16x16x32_bf16 v[118:121], v[160:163], v[204:207], v[118:121]
	v_mfma_f32_16x16x32_bf16 v[110:113], v[170:173], v[204:207], v[110:113]
	v_mfma_f32_16x16x32_bf16 v[102:105], v[160:163], v[212:215], v[102:105]
	v_mfma_f32_16x16x32_bf16 v[94:97], v[170:173], v[212:215], v[94:97]
	v_mfma_f32_16x16x32_bf16 v[86:89], v[160:163], v[220:223], v[86:89]
	v_mfma_f32_16x16x32_bf16 v[78:81], v[170:173], v[220:223], v[78:81]
	v_mfma_f32_16x16x32_bf16 v[126:129], v[166:169], v[200:203], v[126:129]
	v_mfma_f32_16x16x32_bf16 v[122:125], v[174:177], v[200:203], v[122:125]
	v_mfma_f32_16x16x32_bf16 v[118:121], v[166:169], v[208:211], v[118:121]
	v_mfma_f32_16x16x32_bf16 v[110:113], v[174:177], v[208:211], v[110:113]
	v_mfma_f32_16x16x32_bf16 v[102:105], v[166:169], v[216:219], v[102:105]
	v_mfma_f32_16x16x32_bf16 v[94:97], v[174:177], v[216:219], v[94:97]
	v_mfma_f32_16x16x32_bf16 v[86:89], v[166:169], v[224:227], v[86:89]
	v_mfma_f32_16x16x32_bf16 v[78:81], v[174:177], v[224:227], v[78:81]
	v_mfma_f32_16x16x32_bf16 v[114:117], v[178:181], v[196:199], v[114:117]
	v_mfma_f32_16x16x32_bf16 v[106:109], v[188:191], v[196:199], v[106:109]
	v_mfma_f32_16x16x32_bf16 v[98:101], v[178:181], v[204:207], v[98:101]
	v_mfma_f32_16x16x32_bf16 v[90:93], v[188:191], v[204:207], v[90:93]
	v_mfma_f32_16x16x32_bf16 v[82:85], v[178:181], v[212:215], v[82:85]
	v_mfma_f32_16x16x32_bf16 v[74:77], v[188:191], v[212:215], v[74:77]
	v_mfma_f32_16x16x32_bf16 v[70:73], v[178:181], v[220:223], v[70:73]
	v_mfma_f32_16x16x32_bf16 v[66:69], v[188:191], v[220:223], v[66:69]
	v_mfma_f32_16x16x32_bf16 v[114:117], v[184:187], v[200:203], v[114:117]
	v_mfma_f32_16x16x32_bf16 v[106:109], v[192:195], v[200:203], v[106:109]
	v_mfma_f32_16x16x32_bf16 v[98:101], v[184:187], v[208:211], v[98:101]
	v_mfma_f32_16x16x32_bf16 v[90:93], v[192:195], v[208:211], v[90:93]
	v_mfma_f32_16x16x32_bf16 v[82:85], v[184:187], v[216:219], v[82:85]
	v_mfma_f32_16x16x32_bf16 v[74:77], v[192:195], v[216:219], v[74:77]
	v_mfma_f32_16x16x32_bf16 v[70:73], v[184:187], v[224:227], v[70:73]
	v_mfma_f32_16x16x32_bf16 v[66:69], v[192:195], v[224:227], v[66:69]
	s_barrier
	s_add_i32 s14, s41, s24
	v_lshl_add_u64 v[228:229], s[18:19], 0, v[132:133]
	s_mov_b32 m0, s14
	ds_read_b128 v[196:199], v165 offset:16384
	ds_read_b128 v[200:203], v165 offset:17408
	ds_read_b128 v[204:207], v165 offset:18432
	ds_read_b128 v[208:211], v165 offset:19456
	ds_read_b128 v[212:215], v165 offset:20480
	ds_read_b128 v[216:219], v165 offset:21504
	ds_read_b128 v[220:223], v165 offset:22528
	ds_read_b128 v[224:227], v165 offset:23552
	global_load_lds_dwordx4 v[228:229], off
	s_add_i32 m0, s14, 0x2000
	s_add_u32 s14, s18, 0xb0000
	v_lshl_add_u64 v[230:231], s[18:19], 0, v[154:155]
	s_addc_u32 s15, s19, 0
	s_add_i32 s41, s42, s24
	global_load_lds_dwordx4 v[230:231], off
	v_lshl_add_u64 v[232:233], s[14:15], 0, v[132:133]
	s_mov_b32 m0, s41
	global_load_lds_dwordx4 v[232:233], off
	s_add_i32 m0, s41, 0x2000
	v_lshl_add_u64 v[232:233], s[14:15], 0, v[154:155]
	global_load_lds_dwordx4 v[232:233], off
	s_mov_b32 m0, s25
	v_lshl_add_u64 v[232:233], s[20:21], 0, v[130:131]
	global_load_lds_dwordx4 v[232:233], off
	s_mov_b32 m0, s26
	v_lshl_add_u64 v[234:235], s[20:21], 0, v[134:135]
	global_load_lds_dwordx4 v[234:235], off
	s_waitcnt vmcnt(8)
	s_waitcnt lgkmcnt(0)
	s_barrier
	v_mfma_f32_16x16x32_bf16 v[62:65], v[160:163], v[196:199], v[62:65]
	v_mfma_f32_16x16x32_bf16 v[58:61], v[170:173], v[196:199], v[58:61]
	v_mfma_f32_16x16x32_bf16 v[54:57], v[160:163], v[204:207], v[54:57]
	v_mfma_f32_16x16x32_bf16 v[46:49], v[170:173], v[204:207], v[46:49]
	v_mfma_f32_16x16x32_bf16 v[38:41], v[160:163], v[212:215], v[38:41]
	v_mfma_f32_16x16x32_bf16 v[30:33], v[170:173], v[212:215], v[30:33]
	v_mfma_f32_16x16x32_bf16 v[22:25], v[160:163], v[220:223], v[22:25]
	v_mfma_f32_16x16x32_bf16 v[14:17], v[170:173], v[220:223], v[14:17]
	v_mfma_f32_16x16x32_bf16 v[62:65], v[166:169], v[200:203], v[62:65]
	v_mfma_f32_16x16x32_bf16 v[58:61], v[174:177], v[200:203], v[58:61]
	v_mfma_f32_16x16x32_bf16 v[54:57], v[166:169], v[208:211], v[54:57]
	v_mfma_f32_16x16x32_bf16 v[46:49], v[174:177], v[208:211], v[46:49]
	v_mfma_f32_16x16x32_bf16 v[38:41], v[166:169], v[216:219], v[38:41]
	v_mfma_f32_16x16x32_bf16 v[30:33], v[174:177], v[216:219], v[30:33]
	v_mfma_f32_16x16x32_bf16 v[22:25], v[166:169], v[224:227], v[22:25]
	v_mfma_f32_16x16x32_bf16 v[14:17], v[174:177], v[224:227], v[14:17]
	v_mfma_f32_16x16x32_bf16 v[50:53], v[178:181], v[196:199], v[50:53]
	v_mfma_f32_16x16x32_bf16 v[42:45], v[188:191], v[196:199], v[42:45]
	v_mfma_f32_16x16x32_bf16 v[34:37], v[178:181], v[204:207], v[34:37]
	v_mfma_f32_16x16x32_bf16 v[26:29], v[188:191], v[204:207], v[26:29]
	v_mfma_f32_16x16x32_bf16 v[18:21], v[178:181], v[212:215], v[18:21]
	v_mfma_f32_16x16x32_bf16 v[10:13], v[188:191], v[212:215], v[10:13]
	v_mfma_f32_16x16x32_bf16 v[6:9], v[178:181], v[220:223], v[6:9]
	v_mfma_f32_16x16x32_bf16 v[2:5], v[188:191], v[220:223], v[2:5]
	v_mfma_f32_16x16x32_bf16 v[50:53], v[184:187], v[200:203], v[50:53]
	v_mfma_f32_16x16x32_bf16 v[42:45], v[192:195], v[200:203], v[42:45]
	v_mfma_f32_16x16x32_bf16 v[34:37], v[184:187], v[208:211], v[34:37]
	v_mfma_f32_16x16x32_bf16 v[26:29], v[192:195], v[208:211], v[26:29]
	v_mfma_f32_16x16x32_bf16 v[18:21], v[184:187], v[216:219], v[18:21]
	v_mfma_f32_16x16x32_bf16 v[10:13], v[192:195], v[216:219], v[10:13]
	v_mfma_f32_16x16x32_bf16 v[6:9], v[184:187], v[224:227], v[6:9]
	v_mfma_f32_16x16x32_bf16 v[2:5], v[192:195], v[224:227], v[2:5]
	s_barrier
; #define PG8_STAGE(bufoff, gbase, voff) do { _Pragma("unroll") for (int _i = 0; _i < 2; ++_i) \
;         __builtin_amdgcn_global_load_lds((const unsigned*)((const char*)(gbase) + (voff)[_i]), (LAS unsigned*)(lds + (bufoff) + ldsw + _i * 8192), 16, 0, 0); } while (0)
; #define PG8_LDA(dst, b, h) do { _Pragma("unroll") for (int m = 0; m < 4; ++m) _Pragma("unroll") for (int k = 0; k < 2; ++k) dst[m][k] = *(const LAS bf16x8*)(lds + PG8_SA(b, h) + aoff + m * 2048 + k * 1024); } while (0)
; #define PG8_LDB(dst, b, h) do { _Pragma("unroll") for (int n = 0; n < 2; ++n) _Pragma("unroll") for (int k = 0; k < 2; ++k) dst[n][k] = *(const LAS bf16x8*)(lds + PG8_SB(b, h) + boff + n * 2048 + k * 1024); } while (0)
; #define PG8_MMA(ai, bj, At, Bt) do { __builtin_amdgcn_s_setprio(1); _Pragma("unroll") for (int m = 0; m < 4; ++m) _Pragma("unroll") for (int n = 0; n < 2; ++n) _Pragma("unroll") for (int k = 0; k < 2; ++k) \
;         acc[ai][bj][m][n] = __builtin_amdgcn_mfma_f32_16x16x32_bf16(Bt[n][k], At[m][k], acc[ai][bj][m][n], 0, 0, 0); __builtin_amdgcn_s_setprio(0); } while (0)
; #define PG8_WAIT_V(n) asm volatile("s_waitcnt vmcnt(" #n ")" ::: "memory")
; #define PG8_WAIT_L(n) asm volatile("s_waitcnt lgkmcnt(" #n ")" ::: "memory")
; #define PG8_BAR __builtin_amdgcn_s_barrier()
; #define PG8_SCHED __builtin_amdgcn_sched_barrier(0)
; template <class Epi, bool ALIGN_EPI = PG8_ALIGN, bool SP2 = PG8_SP2>
; __device__ __forceinline__ void gemm_phase(LAS uchar* lds, const Gemm g, const StaticOrder& S, const Epi& E) {
;     ...
;         for (int t = tb; t < tb + tblk; t += 2) {
;             const bool last = (t == nt - 2);
;             const char* a1 = cA + (size_t)(t + 1) * kstep;
;             const char* a2 = last ? nA : cA + (size_t)(t + 2) * kstep; const char* b2 = last ? nB : cB + (size_t)(t + 2) * kstep;
;     ...
;             PG8_LDB(B0, 1, 0); PG8_LDB(B1, 1, 1); PG8_SCHED; PG8_LDA(At, 1, 0); PG8_STAGE(PG8_SA(0, 1), a2 + hstepA, voffA);
;             PG8_WAIT_V(8); PG8_WAIT_L(0); PG8_BAR; PG8_MMA(0, 0, At, B0); PG8_MMA(0, 1, At, B1); PG8_BAR; PG8_SCHED;
;             PG8_LDA(At, 1, 1); PG8_STAGE(PG8_SB(1, 0), b3, voffB); PG8_STAGE(PG8_SB(1, 1), b3 + hstepB, voffB); PG8_STAGE(PG8_SA(1, 0), a3, voffA);
;             PG8_WAIT_V(8); PG8_WAIT_L(0); PG8_BAR; PG8_MMA(1, 0, At, B0); PG8_MMA(1, 1, At, B1); PG8_BAR; PG8_SCHED;
	s_add_i32 s41, 0, 0x18000
	v_add_u32_e32 v144, s41, v139
	s_add_i32 s42, 0, 0x1c000
	ds_read_b128 v[160:163], v144
	ds_read_b128 v[166:169], v144 offset:1024
	ds_read_b128 v[170:173], v144 offset:2048
	ds_read_b128 v[174:177], v144 offset:3072
	v_add_u32_e32 v144, s42, v139
	ds_read_b128 v[178:181], v144
	ds_read_b128 v[184:187], v144 offset:1024
	ds_read_b128 v[188:191], v144 offset:2048
	ds_read_b128 v[192:195], v144 offset:3072
	s_add_u32 s14, s20, 0xb0000
	s_addc_u32 s15, s21, 0
	s_mov_b32 m0, s27
	v_lshl_add_u64 v[236:237], s[14:15], 0, v[130:131]
	ds_read_b128 v[196:199], v165 offset:32768
	ds_read_b128 v[200:203], v165 offset:33792
	ds_read_b128 v[204:207], v165 offset:34816
	ds_read_b128 v[208:211], v165 offset:35840
	ds_read_b128 v[212:215], v165 offset:36864
	ds_read_b128 v[216:219], v165 offset:37888
	ds_read_b128 v[220:223], v165 offset:38912
	ds_read_b128 v[224:227], v165 offset:39936
	global_load_lds_dwordx4 v[236:237], off
	s_mov_b32 m0, s28
	v_lshl_add_u64 v[236:237], s[14:15], 0, v[134:135]
	global_load_lds_dwordx4 v[236:237], off
	s_waitcnt vmcnt(8)
	s_waitcnt lgkmcnt(0)
	s_barrier
	v_mfma_f32_16x16x32_bf16 v[126:129], v[160:163], v[196:199], v[126:129]
	v_mfma_f32_16x16x32_bf16 v[122:125], v[170:173], v[196:199], v[122:125]
	v_mfma_f32_16x16x32_bf16 v[118:121], v[160:163], v[204:207], v[118:121]
	v_mfma_f32_16x16x32_bf16 v[110:113], v[170:173], v[204:207], v[110:113]
	v_mfma_f32_16x16x32_bf16 v[102:105], v[160:163], v[212:215], v[102:105]
	v_mfma_f32_16x16x32_bf16 v[94:97], v[170:173], v[212:215], v[94:97]
	v_mfma_f32_16x16x32_bf16 v[86:89], v[160:163], v[220:223], v[86:89]
	v_mfma_f32_16x16x32_bf16 v[78:81], v[170:173], v[220:223], v[78:81]
	v_mfma_f32_16x16x32_bf16 v[126:129], v[166:169], v[200:203], v[126:129]
	v_mfma_f32_16x16x32_bf16 v[122:125], v[174:177], v[200:203], v[122:125]
	v_mfma_f32_16x16x32_bf16 v[118:121], v[166:169], v[208:211], v[118:121]
	v_mfma_f32_16x16x32_bf16 v[110:113], v[174:177], v[208:211], v[110:113]
	v_mfma_f32_16x16x32_bf16 v[102:105], v[166:169], v[216:219], v[102:105]
	v_mfma_f32_16x16x32_bf16 v[94:97], v[174:177], v[216:219], v[94:97]
	v_mfma_f32_16x16x32_bf16 v[86:89], v[166:169], v[224:227], v[86:89]
	v_mfma_f32_16x16x32_bf16 v[78:81], v[174:177], v[224:227], v[78:81]
	v_mfma_f32_16x16x32_bf16 v[114:117], v[178:181], v[196:199], v[114:117]
	v_mfma_f32_16x16x32_bf16 v[106:109], v[188:191], v[196:199], v[106:109]
	v_mfma_f32_16x16x32_bf16 v[98:101], v[178:181], v[204:207], v[98:101]
	v_mfma_f32_16x16x32_bf16 v[90:93], v[188:191], v[204:207], v[90:93]
	v_mfma_f32_16x16x32_bf16 v[82:85], v[178:181], v[212:215], v[82:85]
	v_mfma_f32_16x16x32_bf16 v[74:77], v[188:191], v[212:215], v[74:77]
	v_mfma_f32_16x16x32_bf16 v[70:73], v[178:181], v[220:223], v[70:73]
	v_mfma_f32_16x16x32_bf16 v[66:69], v[188:191], v[220:223], v[66:69]
	v_mfma_f32_16x16x32_bf16 v[114:117], v[184:187], v[200:203], v[114:117]
	v_mfma_f32_16x16x32_bf16 v[106:109], v[192:195], v[200:203], v[106:109]
	v_mfma_f32_16x16x32_bf16 v[98:101], v[184:187], v[208:211], v[98:101]
	v_mfma_f32_16x16x32_bf16 v[90:93], v[192:195], v[208:211], v[90:93]
	v_mfma_f32_16x16x32_bf16 v[82:85], v[184:187], v[216:219], v[82:85]
	v_mfma_f32_16x16x32_bf16 v[74:77], v[192:195], v[216:219], v[74:77]
	v_mfma_f32_16x16x32_bf16 v[70:73], v[184:187], v[224:227], v[70:73]
	v_mfma_f32_16x16x32_bf16 v[66:69], v[192:195], v[224:227], v[66:69]
	s_barrier
	s_add_i32 s14, s41, s24
	v_lshl_add_u64 v[228:229], v[228:229], 0, s[84:85]
	s_mov_b32 m0, s14
	ds_read_b128 v[196:199], v165 offset:49152
	ds_read_b128 v[200:203], v165 offset:50176
	ds_read_b128 v[204:207], v165 offset:51200
	ds_read_b128 v[208:211], v165 offset:52224
	ds_read_b128 v[212:215], v165 offset:53248
	ds_read_b128 v[216:219], v165 offset:54272
	ds_read_b128 v[220:223], v165 offset:55296
	ds_read_b128 v[224:227], v165 offset:56320
	global_load_lds_dwordx4 v[228:229], off
	s_add_i32 m0, s14, 0x2000
	s_add_u32 s14, s18, 0xb0080
	v_lshl_add_u64 v[228:229], v[230:231], 0, s[84:85]
	s_addc_u32 s15, s19, 0
	s_add_i32 s18, s42, s24
	global_load_lds_dwordx4 v[228:229], off
	s_mov_b32 m0, s18
	v_lshl_add_u64 v[228:229], s[14:15], 0, v[132:133]
	global_load_lds_dwordx4 v[228:229], off
	s_add_i32 m0, s18, 0x2000
	v_lshl_add_u64 v[228:229], s[14:15], 0, v[154:155]
	global_load_lds_dwordx4 v[228:229], off
	s_mov_b32 m0, s29
	v_lshl_add_u64 v[228:229], v[232:233], 0, s[84:85]
	global_load_lds_dwordx4 v[228:229], off
	s_mov_b32 m0, s30
	v_lshl_add_u64 v[228:229], v[234:235], 0, s[84:85]
	global_load_lds_dwordx4 v[228:229], off
	s_waitcnt vmcnt(8)
	s_waitcnt lgkmcnt(0)
	s_barrier
	v_mfma_f32_16x16x32_bf16 v[62:65], v[160:163], v[196:199], v[62:65]
	v_mfma_f32_16x16x32_bf16 v[58:61], v[170:173], v[196:199], v[58:61]
	v_mfma_f32_16x16x32_bf16 v[54:57], v[160:163], v[204:207], v[54:57]
	v_mfma_f32_16x16x32_bf16 v[46:49], v[170:173], v[204:207], v[46:49]
	v_mfma_f32_16x16x32_bf16 v[38:41], v[160:163], v[212:215], v[38:41]
	v_mfma_f32_16x16x32_bf16 v[30:33], v[170:173], v[212:215], v[30:33]
	v_mfma_f32_16x16x32_bf16 v[22:25], v[160:163], v[220:223], v[22:25]
	v_mfma_f32_16x16x32_bf16 v[14:17], v[170:173], v[220:223], v[14:17]
	v_mfma_f32_16x16x32_bf16 v[62:65], v[166:169], v[200:203], v[62:65]
	v_mfma_f32_16x16x32_bf16 v[58:61], v[174:177], v[200:203], v[58:61]
	v_mfma_f32_16x16x32_bf16 v[54:57], v[166:169], v[208:211], v[54:57]
	v_mfma_f32_16x16x32_bf16 v[46:49], v[174:177], v[208:211], v[46:49]
	v_mfma_f32_16x16x32_bf16 v[38:41], v[166:169], v[216:219], v[38:41]
	v_mfma_f32_16x16x32_bf16 v[30:33], v[174:177], v[216:219], v[30:33]
	v_mfma_f32_16x16x32_bf16 v[22:25], v[166:169], v[224:227], v[22:25]
	v_mfma_f32_16x16x32_bf16 v[14:17], v[174:177], v[224:227], v[14:17]
	v_mfma_f32_16x16x32_bf16 v[50:53], v[178:181], v[196:199], v[50:53]
	v_mfma_f32_16x16x32_bf16 v[42:45], v[188:191], v[196:199], v[42:45]
	v_mfma_f32_16x16x32_bf16 v[34:37], v[178:181], v[204:207], v[34:37]
	v_mfma_f32_16x16x32_bf16 v[26:29], v[188:191], v[204:207], v[26:29]
	v_mfma_f32_16x16x32_bf16 v[18:21], v[178:181], v[212:215], v[18:21]
	v_mfma_f32_16x16x32_bf16 v[10:13], v[188:191], v[212:215], v[10:13]
	v_mfma_f32_16x16x32_bf16 v[6:9], v[178:181], v[220:223], v[6:9]
	v_mfma_f32_16x16x32_bf16 v[2:5], v[188:191], v[220:223], v[2:5]
	v_mfma_f32_16x16x32_bf16 v[50:53], v[184:187], v[200:203], v[50:53]
	v_mfma_f32_16x16x32_bf16 v[42:45], v[192:195], v[200:203], v[42:45]
	v_mfma_f32_16x16x32_bf16 v[34:37], v[184:187], v[208:211], v[34:37]
	v_mfma_f32_16x16x32_bf16 v[26:29], v[192:195], v[208:211], v[26:29]
	v_mfma_f32_16x16x32_bf16 v[18:21], v[184:187], v[216:219], v[18:21]
	v_mfma_f32_16x16x32_bf16 v[10:13], v[192:195], v[216:219], v[10:13]
	v_mfma_f32_16x16x32_bf16 v[6:9], v[184:187], v[224:227], v[6:9]
	v_mfma_f32_16x16x32_bf16 v[2:5], v[192:195], v[224:227], v[2:5]
	s_barrier
	s_add_i32 s40, s40, 2
	s_add_u32 s38, s38, 0x100
	s_addc_u32 s39, s39, 0
	s_cmp_gt_u32 s40, 41
	s_mov_b64 s[14:15], s[16:17]
	s_cbranch_scc0 .LBB0_1143
	s_and_b64 vcc, exec, s[10:11]
	s_cbranch_vccz .LBB0_1146
	s_barrier
